# Cross-attention sample units: seven of the next eight key rows prefetched into spare registers one batch ahead (copies at the old load sites, staged waits adjusted); hazard pads in the RWKV prefetch b
# baseline (speedup 1.0000x reference)
.LBB0_317:
	v_writelane_b32 v249, s0, 38
	s_and_b64 vcc, exec, s[2:3]
	s_nop 0
	v_writelane_b32 v249, s1, 39
	s_cbranch_vccz .LBB0_905
	s_cmp_eq_u32 s80, 4
	s_cselect_b64 s[0:1], -1, 0
	s_cmp_lg_u32 s80, 4
	s_cselect_b64 s[2:3], -1, 0
	v_writelane_b32 v249, s2, 40
	s_cmp_lt_u32 s8, 9
	s_cselect_b64 s[72:73], -1, 0
	v_writelane_b32 v249, s3, 41
	v_writelane_b32 v249, s0, 42
	s_mov_b64 s[46:47], 0x1000
	s_nop 0
	v_writelane_b32 v249, s1, 43
	s_and_b64 s[0:1], s[0:1], s[72:73]
	s_andn2_b64 vcc, exec, s[0:1]
	s_cbranch_vccnz .LBB0_486
	s_cmpk_gt_i32 s64, 0x8ff
	s_cbranch_scc1 .LBB0_342
	v_readlane_b32 s0, v249, 36
	s_lshl_b32 s8, s64, 2
	s_lshl_b32 s9, s0, 2
	s_mov_b32 s22, s64
	v_readlane_b32 s1, v249, 37
	s_mov_b32 s100, s8
	v_mbcnt_lo_u32_b32 v166, -1, 0
	v_mbcnt_hi_u32_b32 v166, -1, v166
	v_add_u32_e32 v167, s61, v166
	v_lshrrev_b32_e32 v168, 7, v167
	v_add_u32_e32 v168, s100, v168
	s_load_dwordx2 s[100:101], s[58:59], 0x158
	v_lshlrev_b32_e32 v169, 4, v168
	v_and_b32_e32 v169, 0x7f0, v169
	v_ashrrev_i32_e32 v170, 10, v168
	v_lshl_or_b32 v170, v170, 11, v169
	v_lshrrev_b32_e32 v171, 7, v168
	v_add_u32_e32 v172, 0xffffe000, v168
	v_and_b32_e32 v172, -8, v172
	v_add_u32_e32 v172, 0x4000, v172
	v_cmp_lt_i32_e32 vcc, 0x1fff, v168
	s_nop 1
	v_cndmask_b32_e32 v170, v170, v172, vcc
	v_cndmask_b32_e64 v169, v169, 0, vcc
	v_cndmask_b32_e32 v171, v171, v168, vcc
	v_mov_b32_e32 v173, 16
	v_cndmask_b32_e64 v173, v173, 8, vcc
	v_bfe_u32 v174, v167, 6, 1
	v_bfe_u32 v175, v166, 3, 3
	v_lshl_or_b32 v174, v174, 3, v175
	v_cmp_gt_u32_e32 vcc, v173, v174
	s_nop 1
	v_cndmask_b32_e32 v174, 0, v174, vcc
	v_lshlrev_b32_e32 v171, 6, v171
	v_and_b32_e32 v171, 0x1c0, v171
	v_lshlrev_b32_e32 v175, 3, v167
	v_and_b32_e32 v175, 56, v175
	v_or_b32_e32 v171, v171, v175
	v_add_u32_e32 v170, v170, v174
	v_or_b32_e32 v169, v169, v174
	v_lshlrev_b32_e32 v176, 1, v171
	v_mov_b32_e32 v177, 0
	v_mov_b32_e32 v178, 0xc00
	s_waitcnt lgkmcnt(0)
	v_mov_b64_e32 v[180:181], s[100:101]
	v_mov_b64_e32 v[182:183], s[100:101]
	v_mad_i64_i32 v[180:181], vcc, v170, s83, v[180:181]
	v_mad_i64_i32 v[182:183], vcc, v170, v178, v[182:183]
	v_lshl_add_u64 v[180:181], v[180:181], 0, v[176:177]
	v_lshl_add_u64 v[182:183], v[182:183], 0, v[176:177]
	v_add_co_u32_e32 v180, vcc, 0x12f01000, v180
	s_nop 1
	v_addc_co_u32_e32 v181, vcc, 0, v181, vcc
	v_add_co_u32_e32 v182, vcc, 0x25600000, v182
	s_nop 1
	v_addc_co_u32_e32 v183, vcc, 0, v183, vcc
	v_cmp_eq_u32_e32 vcc, 0, v169
	s_nop 1
	v_cndmask_b32_e64 v185, -1, 0, vcc
	v_cndmask_b32_e64 v184, v205, 0, vcc
	v_lshl_add_u64 v[184:185], v[180:181], 0, v[184:185]
	global_load_dwordx4 v[128:131], v[182:183], off
	global_load_dwordx4 v[132:135], v[184:185], off
	global_load_dwordx4 v[136:139], v[184:185], off offset:1024
	global_load_dwordx4 v[140:143], v[180:181], off offset:1024
	global_load_dwordx4 v[144:147], v[180:181], off offset:2048
	global_load_dwordx4 v[148:151], v[180:181], off
	global_load_dwordx4 v[152:155], v[184:185], off offset:2048
	global_load_dwordx4 v[158:161], v[182:183], off offset:1024
	global_load_dwordx4 v[162:165], v[182:183], off offset:2048
	s_branch .LBB0_322

.LBB0_332:
	s_or_b64 exec, exec, s[12:13]
	s_add_i32 s100, s8, s9
	s_cmpk_ge_i32 s100, 0x2400
	s_cbranch_scc1 .Lr1pf_skip
	v_mbcnt_lo_u32_b32 v166, -1, 0
	v_mbcnt_hi_u32_b32 v166, -1, v166
	v_add_u32_e32 v167, s61, v166
	v_lshrrev_b32_e32 v168, 7, v167
	v_add_u32_e32 v168, s100, v168
	s_load_dwordx2 s[100:101], s[58:59], 0x158
	v_lshlrev_b32_e32 v169, 4, v168
	v_and_b32_e32 v169, 0x7f0, v169
	v_ashrrev_i32_e32 v170, 10, v168
	v_lshl_or_b32 v170, v170, 11, v169
	v_lshrrev_b32_e32 v171, 7, v168
	v_add_u32_e32 v172, 0xffffe000, v168
	v_and_b32_e32 v172, -8, v172
	v_add_u32_e32 v172, 0x4000, v172
	v_cmp_lt_i32_e32 vcc, 0x1fff, v168
	s_nop 1
	v_cndmask_b32_e32 v170, v170, v172, vcc
	v_cndmask_b32_e64 v169, v169, 0, vcc
	v_cndmask_b32_e32 v171, v171, v168, vcc
	v_mov_b32_e32 v173, 16
	v_cndmask_b32_e64 v173, v173, 8, vcc
	v_bfe_u32 v174, v167, 6, 1
	v_bfe_u32 v175, v166, 3, 3
	v_lshl_or_b32 v174, v174, 3, v175
	v_cmp_gt_u32_e32 vcc, v173, v174
	s_nop 1
	v_cndmask_b32_e32 v174, 0, v174, vcc
	v_lshlrev_b32_e32 v171, 6, v171
	v_and_b32_e32 v171, 0x1c0, v171
	v_lshlrev_b32_e32 v175, 3, v167
	v_and_b32_e32 v175, 56, v175
	v_or_b32_e32 v171, v171, v175
	v_add_u32_e32 v170, v170, v174
	v_or_b32_e32 v169, v169, v174
	v_lshlrev_b32_e32 v176, 1, v171
	v_mov_b32_e32 v177, 0
	v_mov_b32_e32 v178, 0xc00
	s_waitcnt lgkmcnt(0)
	v_mov_b64_e32 v[180:181], s[100:101]
	v_mov_b64_e32 v[182:183], s[100:101]
	v_mad_i64_i32 v[180:181], vcc, v170, s83, v[180:181]
	v_mad_i64_i32 v[182:183], vcc, v170, v178, v[182:183]
	v_lshl_add_u64 v[180:181], v[180:181], 0, v[176:177]
	v_lshl_add_u64 v[182:183], v[182:183], 0, v[176:177]
	v_add_co_u32_e32 v180, vcc, 0x12f01000, v180
	s_nop 1
	v_addc_co_u32_e32 v181, vcc, 0, v181, vcc
	v_add_co_u32_e32 v182, vcc, 0x25600000, v182
	s_nop 1
	v_addc_co_u32_e32 v183, vcc, 0, v183, vcc
	v_cmp_eq_u32_e32 vcc, 0, v169
	s_nop 1
	v_cndmask_b32_e64 v185, -1, 0, vcc
	v_cndmask_b32_e64 v184, v205, 0, vcc
	v_lshl_add_u64 v[184:185], v[180:181], 0, v[184:185]
	global_load_dwordx4 v[128:131], v[182:183], off
	global_load_dwordx4 v[132:135], v[184:185], off
	global_load_dwordx4 v[136:139], v[184:185], off offset:1024
	global_load_dwordx4 v[140:143], v[180:181], off offset:1024
	global_load_dwordx4 v[144:147], v[180:181], off offset:2048
	global_load_dwordx4 v[148:151], v[180:181], off
	global_load_dwordx4 v[152:155], v[184:185], off offset:2048
	global_load_dwordx4 v[158:161], v[182:183], off offset:1024
	global_load_dwordx4 v[162:165], v[182:183], off offset:2048

.LBB0_501:
	s_mov_b64 s[0:1], s[58:59]
	s_load_dwordx2 s[0:1], s[0:1], 0x158
	s_mov_b64 s[2:3], s[58:59]
	s_ashr_i32 s6, s9, 2
	s_load_dwordx2 s[4:5], s[2:3], 0x38
	s_mov_b64 s[2:3], s[58:59]
	s_mov_b64 s[10:11], s[58:59]
	s_lshl_b32 s36, s6, 3
	s_and_b32 s29, s8, 0x300
	s_load_dwordx2 s[2:3], s[2:3], 0x40
	s_add_i32 s20, s36, 0x4000
	s_lshl_b32 s30, s29, 1
	s_load_dwordx2 s[10:11], s[10:11], 0x158
	v_mbcnt_lo_u32_b32 v130, -1, 0
	v_mbcnt_hi_u32_b32 v130, -1, v130
	s_waitcnt lgkmcnt(0)
	s_add_u32 s0, s0, s30
	v_and_b32_e32 v131, 63, v130
	s_addc_u32 s1, s1, 0
	v_lshlrev_b32_e32 v156, 3, v131
	v_lshl_add_u64 v[0:1], s[0:1], 0, v[156:157]
	s_ashr_i32 s21, s20, 31
	v_lshl_add_u64 v[0:1], v[0:1], 0, s[62:63]
	s_lshl_b64 s[0:1], s[20:21], 11
	s_ashr_i32 s37, s36, 31
	v_lshl_add_u64 v[2:3], v[0:1], 0, s[0:1]
	s_lshl_b64 s[0:1], s[36:37], 11
	v_lshl_add_u64 v[0:1], v[0:1], 0, s[0:1]
	s_brev_b32 s0, 64
	v_add_co_u32_e32 v4, vcc, s0, v0
	s_mov_b32 s0, 0x2002000
	s_nop 0
	v_addc_co_u32_e32 v5, vcc, 0, v1, vcc
	v_add_co_u32_e32 v6, vcc, s0, v0
	s_mov_b32 s0, 0x2001000
	s_nop 0
	v_addc_co_u32_e32 v7, vcc, 0, v1, vcc
	v_add_co_u32_e32 v10, vcc, s0, v0
	s_mov_b32 s0, 0x2003000
	s_nop 0
	v_addc_co_u32_e32 v11, vcc, 0, v1, vcc
	v_add_co_u32_e32 v0, vcc, s0, v0
	global_load_dwordx2 v[2:3], v[2:3], off
	s_nop 0
	v_addc_co_u32_e32 v1, vcc, 0, v1, vcc
	global_load_dwordx2 v[4:5], v[4:5], off offset:2048
	v_add_u32_e32 v132, s61, v130
	global_load_dwordx2 v[8:9], v[6:7], off offset:-4096
	s_nop 0
	global_load_dwordx2 v[10:11], v[10:11], off offset:2048
	s_nop 0
	global_load_dwordx2 v[12:13], v[6:7], off
	s_nop 0
	global_load_dwordx2 v[6:7], v[6:7], off offset:2048
	s_nop 0
	global_load_dwordx2 v[14:15], v[0:1], off
	s_nop 0
	global_load_dwordx2 v[0:1], v[0:1], off offset:2048
	s_ashr_i32 s7, s6, 31
	v_ashrrev_i32_e32 v129, 6, v132
	s_lshl_b64 s[0:1], s[6:7], 8
	v_lshlrev_b32_e32 v16, 5, v129
	s_add_u32 s0, s0, s15
	v_ashrrev_i32_e32 v17, 31, v16
	s_addc_u32 s1, s1, 0
	v_lshl_add_u64 v[16:17], s[0:1], 0, v[16:17]
	v_lshlrev_b32_e32 v128, 2, v131
	v_lshlrev_b64 v[16:17], 10, v[16:17]
	v_or3_b32 v16, v16, s29, v128
	v_lshlrev_b64 v[16:17], 2, v[16:17]
	v_lshl_add_u64 v[116:117], s[4:5], 0, v[16:17]
	global_load_dwordx4 v[60:63], v[116:117], off nt
	v_lshl_add_u64 v[124:125], s[2:3], 0, v[16:17]
	v_and_b32_e32 v82, 16, v130
	v_cmp_eq_u32_e64 s[2:3], 0, v82
	v_and_b32_e32 v83, 8, v130
	v_cmp_eq_u32_e64 s[4:5], 0, v83
	s_mov_b32 s0, 0x15000
	s_waitcnt vmcnt(0)
	v_lshlrev_b32_e32 v92, 16, v3
	v_and_b32_e32 v93, 0xffff0000, v3
	v_lshlrev_b32_e32 v84, 16, v2
	v_lshlrev_b32_e32 v96, 16, v5
	v_and_b32_e32 v97, 0xffff0000, v5
	v_lshlrev_b32_e32 v94, 16, v12
	v_and_b32_e32 v95, 0xffff0000, v12
	v_lshlrev_b32_e32 v106, 16, v0
	v_and_b32_e32 v107, 0xffff0000, v0
	v_add_co_u32_e32 v0, vcc, s93, v116
	v_lshlrev_b32_e32 v114, 16, v1
	v_and_b32_e32 v115, 0xffff0000, v1
	v_addc_co_u32_e32 v1, vcc, 0, v117, vcc
	global_load_dwordx4 v[64:67], v[0:1], off offset:-4096 nt
	global_load_dwordx4 v[52:55], v[0:1], off nt
	v_add_co_u32_e32 v0, vcc, s88, v116
	v_lshlrev_b32_e32 v108, 16, v13
	s_nop 0
	v_addc_co_u32_e32 v1, vcc, 0, v117, vcc
	global_load_dwordx4 v[48:51], v[0:1], off offset:-4096 nt
	global_load_dwordx4 v[44:47], v[0:1], off nt
	v_add_co_u32_e32 v0, vcc, s45, v116
	v_and_b32_e32 v109, 0xffff0000, v13
	s_nop 0
	v_addc_co_u32_e32 v1, vcc, 0, v117, vcc
	v_add_co_u32_e32 v58, vcc, s35, v116
	global_load_dwordx4 v[40:43], v[0:1], off offset:-4096 nt
	global_load_dwordx4 v[36:39], v[0:1], off nt
	v_addc_co_u32_e32 v59, vcc, 0, v117, vcc
	v_add_co_u32_e32 v0, vcc, s93, v124
	global_load_dwordx4 v[32:35], v[58:59], off offset:-4096 nt
	global_load_dwordx4 v[28:31], v[124:125], off nt
	v_addc_co_u32_e32 v1, vcc, 0, v125, vcc
	global_load_dwordx4 v[24:27], v[0:1], off offset:-4096 nt
	global_load_dwordx4 v[20:23], v[0:1], off nt
	v_add_co_u32_e32 v0, vcc, s88, v124
	v_lshlrev_b32_e32 v102, 16, v14
	s_nop 0
	v_addc_co_u32_e32 v1, vcc, 0, v125, vcc
	v_and_b32_e32 v103, 0xffff0000, v14
	v_lshlrev_b32_e32 v112, 16, v15
	v_and_b32_e32 v113, 0xffff0000, v15
	global_load_dwordx4 v[16:19], v[0:1], off offset:-4096 nt
	global_load_dwordx4 v[12:15], v[0:1], off nt
	v_add_co_u32_e32 v0, vcc, s45, v124
	v_lshlrev_b32_e32 v100, 16, v9
	v_and_b32_e32 v101, 0xffff0000, v9
	v_lshlrev_b32_e32 v104, 16, v11
	v_and_b32_e32 v105, 0xffff0000, v11
	v_lshlrev_b32_e32 v110, 16, v7
	v_and_b32_e32 v111, 0xffff0000, v7
	v_addc_co_u32_e32 v1, vcc, 0, v125, vcc
	v_and_b32_e32 v85, 0xffff0000, v2
	v_lshlrev_b32_e32 v86, 16, v4
	v_and_b32_e32 v87, 0xffff0000, v4
	v_lshlrev_b32_e32 v88, 16, v8
	v_and_b32_e32 v89, 0xffff0000, v8
	v_lshlrev_b32_e32 v90, 16, v10
	v_and_b32_e32 v91, 0xffff0000, v10
	v_lshlrev_b32_e32 v98, 16, v6
	v_and_b32_e32 v99, 0xffff0000, v6
	v_add_co_u32_e32 v56, vcc, s35, v124
	v_pk_mul_f32 v[68:69], v[62:63], v[92:93]
	v_pk_mul_f32 v[70:71], v[62:63], v[96:97]
	v_pk_mul_f32 v[72:73], v[62:63], v[100:101]
	v_pk_mul_f32 v[74:75], v[62:63], v[104:105]
	v_pk_mul_f32 v[76:77], v[62:63], v[108:109]
	v_pk_mul_f32 v[78:79], v[62:63], v[110:111]
	v_pk_mul_f32 v[80:81], v[62:63], v[112:113]
	v_pk_mul_f32 v[62:63], v[62:63], v[114:115]
	v_addc_co_u32_e32 v57, vcc, 0, v125, vcc
	v_pk_fma_f32 v[68:69], v[60:61], v[84:85], v[68:69]
	v_pk_fma_f32 v[70:71], v[60:61], v[86:87], v[70:71]
	v_pk_fma_f32 v[72:73], v[60:61], v[88:89], v[72:73]
	v_pk_fma_f32 v[74:75], v[60:61], v[90:91], v[74:75]
	v_pk_fma_f32 v[76:77], v[60:61], v[94:95], v[76:77]
	v_pk_fma_f32 v[78:79], v[60:61], v[98:99], v[78:79]
	v_pk_fma_f32 v[80:81], v[60:61], v[102:103], v[80:81]
	v_pk_fma_f32 v[60:61], v[60:61], v[106:107], v[62:63]
	v_pk_add_f32 v[68:69], v[68:69], v[68:69] op_sel:[0,1] op_sel_hi:[1,0]
	v_pk_add_f32 v[76:77], v[76:77], v[76:77] op_sel:[0,1] op_sel_hi:[1,0]
	v_pk_add_f32 v[60:61], v[60:61], v[60:61] op_sel:[0,1] op_sel_hi:[1,0]
	v_cmp_lt_u32_e32 vcc, 31, v131
	global_load_dwordx4 v[8:11], v[0:1], off offset:-4096 nt
	global_load_dwordx4 v[4:7], v[0:1], off nt
	v_cndmask_b32_e32 v61, v76, v68, vcc
	v_mov_b32_e32 v63, v61
	global_load_dwordx4 v[0:3], v[56:57], off offset:-4096 nt
	global_load_dwordx4 v[222:225], v[58:59], off nt
	v_add_co_u32_e64 v254, s[100:101], s43, v116
	s_nop 1
	v_addc_co_u32_e64 v255, s[100:101], 0, v117, s[100:101]
	global_load_dwordx4 v[226:229], v[254:255], off offset:-4096 nt
	global_load_dwordx4 v[230:233], v[254:255], off nt
	v_add_co_u32_e64 v254, s[100:101], s38, v116
	s_nop 1
	v_addc_co_u32_e64 v255, s[100:101], 0, v117, s[100:101]
	global_load_dwordx4 v[234:237], v[254:255], off offset:-4096 nt
	global_load_dwordx4 v[238:241], v[254:255], off nt
	v_add_co_u32_e64 v254, s[100:101], s44, v116
	s_nop 1
	v_addc_co_u32_e64 v255, s[100:101], 0, v117, s[100:101]
	global_load_dwordx4 v[242:245], v[254:255], off offset:-4096 nt
	global_load_dwordx4 v[250:253], v[254:255], off nt
	v_pk_add_f32 v[70:71], v[70:71], v[70:71] op_sel:[0,1] op_sel_hi:[1,0]
	v_permlane32_swap_b32_e32 v61, v63
	v_pk_add_f32 v[78:79], v[78:79], v[78:79] op_sel:[0,1] op_sel_hi:[1,0]
	v_cndmask_b32_e32 v62, v68, v76, vcc
	v_cndmask_b32_e32 v61, v63, v61, vcc
	v_add_f32_e32 v61, v62, v61
	v_cndmask_b32_e32 v62, v78, v70, vcc
	v_mov_b32_e32 v68, v62
	v_pk_add_f32 v[72:73], v[72:73], v[72:73] op_sel:[0,1] op_sel_hi:[1,0]
	s_nop 0
	v_permlane32_swap_b32_e32 v62, v68
	v_pk_add_f32 v[80:81], v[80:81], v[80:81] op_sel:[0,1] op_sel_hi:[1,0]
	v_cndmask_b32_e32 v63, v70, v78, vcc
	v_cndmask_b32_e32 v62, v68, v62, vcc
	v_add_f32_e32 v62, v63, v62
	v_cndmask_b32_e32 v63, v80, v72, vcc
	v_mov_b32_e32 v69, v63
	v_pk_add_f32 v[74:75], v[74:75], v[74:75] op_sel:[0,1] op_sel_hi:[1,0]
	s_nop 0
	v_permlane32_swap_b32_e32 v63, v69
	v_cndmask_b32_e32 v68, v72, v80, vcc
	v_cndmask_b32_e32 v63, v69, v63, vcc
	v_add_f32_e32 v63, v68, v63
	v_cndmask_b32_e32 v68, v60, v74, vcc
	v_mov_b32_e32 v69, v68
	v_cndmask_b32_e32 v60, v74, v60, vcc
	s_nop 0
	v_permlane32_swap_b32_e32 v68, v69
	v_cndmask_b32_e32 v68, v69, v68, vcc
	v_add_f32_e32 v60, v60, v68
	v_cndmask_b32_e64 v68, v61, v63, s[2:3]
	v_cndmask_b32_e64 v61, v63, v61, s[2:3]
	v_mov_b32_e32 v63, v68
	s_waitcnt vmcnt(21)
	v_pk_mul_f32 v[72:73], v[66:67], v[108:109]
	v_permlane16_swap_b32_e32 v68, v63
	v_cndmask_b32_e64 v63, v68, v63, s[2:3]
	v_add_f32_e32 v61, v61, v63
	v_cndmask_b32_e64 v63, v62, v60, s[2:3]
	v_cndmask_b32_e64 v60, v60, v62, s[2:3]
	v_mov_b32_e32 v62, v63
	v_pk_fma_f32 v[72:73], v[64:65], v[94:95], v[72:73]
	s_nop 0
	v_permlane16_swap_b32_e32 v63, v62
	v_cndmask_b32_e64 v62, v63, v62, s[2:3]
	v_add_f32_e32 v60, v60, v62
	v_cndmask_b32_e64 v62, v61, v60, s[4:5]
	v_cndmask_b32_e64 v60, v60, v61, s[4:5]
	v_pk_add_f32 v[72:73], v[72:73], v[72:73] op_sel:[0,1] op_sel_hi:[1,0]
	v_pk_mul_f32 v[74:75], v[66:67], v[110:111]
	v_add_f32_dpp v60, v62, v60 row_ror:8 row_mask:0xf bank_mask:0xf bound_ctrl:1
	v_pk_mul_f32 v[62:63], v[66:67], v[96:97]
	v_pk_fma_f32 v[74:75], v[64:65], v[98:99], v[74:75]
	v_add_f32_dpp v60, v60, v60 quad_perm:[1,0,3,2] row_mask:0xf bank_mask:0xf bound_ctrl:1
	v_pk_fma_f32 v[62:63], v[64:65], v[86:87], v[62:63]
	v_pk_add_f32 v[74:75], v[74:75], v[74:75] op_sel:[0,1] op_sel_hi:[1,0]
	v_add_f32_dpp v60, v60, v60 quad_perm:[2,3,0,1] row_mask:0xf bank_mask:0xf bound_ctrl:1
	v_pk_add_f32 v[62:63], v[62:63], v[62:63] op_sel:[0,1] op_sel_hi:[1,0]
	v_pk_mul_f32 v[68:69], v[66:67], v[100:101]
	v_add_f32_dpp v133, v60, v60 row_half_mirror row_mask:0xf bank_mask:0xf bound_ctrl:1
	v_pk_mul_f32 v[60:61], v[66:67], v[92:93]
	v_pk_mul_f32 v[76:77], v[66:67], v[112:113]
	v_pk_fma_f32 v[60:61], v[64:65], v[84:85], v[60:61]
	v_pk_fma_f32 v[68:69], v[64:65], v[88:89], v[68:69]
	v_pk_add_f32 v[60:61], v[60:61], v[60:61] op_sel:[0,1] op_sel_hi:[1,0]
	v_pk_mul_f32 v[70:71], v[66:67], v[104:105]
	v_cndmask_b32_e32 v61, v72, v60, vcc
	v_mov_b32_e32 v63, v61
	v_cndmask_b32_e32 v60, v60, v72, vcc
	s_nop 0
	v_permlane32_swap_b32_e32 v61, v63
	v_cndmask_b32_e32 v61, v63, v61, vcc
	v_add_f32_e32 v60, v60, v61
	v_cndmask_b32_e32 v61, v74, v62, vcc
	v_mov_b32_e32 v63, v61
	v_pk_fma_f32 v[76:77], v[64:65], v[102:103], v[76:77]
	v_pk_mul_f32 v[66:67], v[66:67], v[114:115]
	v_permlane32_swap_b32_e32 v61, v63
	v_pk_add_f32 v[68:69], v[68:69], v[68:69] op_sel:[0,1] op_sel_hi:[1,0]
	v_pk_fma_f32 v[70:71], v[64:65], v[90:91], v[70:71]
	v_pk_add_f32 v[76:77], v[76:77], v[76:77] op_sel:[0,1] op_sel_hi:[1,0]
	v_pk_fma_f32 v[64:65], v[64:65], v[106:107], v[66:67]
	v_cndmask_b32_e32 v62, v62, v74, vcc
	v_cndmask_b32_e32 v61, v63, v61, vcc
	v_pk_add_f32 v[64:65], v[64:65], v[64:65] op_sel:[0,1] op_sel_hi:[1,0]
	v_add_f32_e32 v61, v62, v61
	v_cndmask_b32_e32 v62, v76, v68, vcc
	v_mov_b32_e32 v65, v62
	v_pk_add_f32 v[70:71], v[70:71], v[70:71] op_sel:[0,1] op_sel_hi:[1,0]
	s_nop 0
	v_permlane32_swap_b32_e32 v62, v65
	v_cndmask_b32_e32 v63, v68, v76, vcc
	v_cndmask_b32_e32 v62, v65, v62, vcc
	v_add_f32_e32 v62, v63, v62
	v_cndmask_b32_e32 v63, v64, v70, vcc
	v_mov_b32_e32 v65, v63
	v_cndmask_b32_e32 v64, v70, v64, vcc
	s_nop 0
	v_permlane32_swap_b32_e32 v63, v65
	v_cndmask_b32_e32 v63, v65, v63, vcc
	v_add_f32_e32 v63, v64, v63
	v_cndmask_b32_e64 v64, v60, v62, s[2:3]
	v_cndmask_b32_e64 v60, v62, v60, s[2:3]
	v_mov_b32_e32 v62, v64
	s_waitcnt vmcnt(20)
	v_pk_mul_f32 v[66:67], v[54:55], v[104:105]
	v_permlane16_swap_b32_e32 v64, v62
	v_cndmask_b32_e64 v62, v64, v62, s[2:3]
	v_add_f32_e32 v60, v60, v62
	v_cndmask_b32_e64 v62, v61, v63, s[2:3]
	v_cndmask_b32_e64 v61, v63, v61, s[2:3]
	v_mov_b32_e32 v63, v62
	v_pk_mul_f32 v[64:65], v[54:55], v[100:101]
	s_nop 0
	v_permlane16_swap_b32_e32 v62, v63
	v_cndmask_b32_e64 v62, v62, v63, s[2:3]
	v_add_f32_e32 v61, v61, v62
	v_cndmask_b32_e64 v62, v60, v61, s[4:5]
	v_cndmask_b32_e64 v60, v61, v60, s[4:5]
	v_pk_mul_f32 v[68:69], v[54:55], v[108:109]
	v_pk_mul_f32 v[70:71], v[54:55], v[110:111]
	v_add_f32_dpp v60, v62, v60 row_ror:8 row_mask:0xf bank_mask:0xf bound_ctrl:1
	v_pk_mul_f32 v[62:63], v[54:55], v[96:97]
	v_pk_mul_f32 v[72:73], v[54:55], v[112:113]
	v_add_f32_dpp v60, v60, v60 quad_perm:[1,0,3,2] row_mask:0xf bank_mask:0xf bound_ctrl:1
	v_pk_fma_f32 v[62:63], v[52:53], v[86:87], v[62:63]
	v_pk_fma_f32 v[64:65], v[52:53], v[88:89], v[64:65]
	v_add_f32_dpp v60, v60, v60 quad_perm:[2,3,0,1] row_mask:0xf bank_mask:0xf bound_ctrl:1
	v_pk_fma_f32 v[66:67], v[52:53], v[90:91], v[66:67]
	v_pk_fma_f32 v[68:69], v[52:53], v[94:95], v[68:69]
	v_add_f32_dpp v135, v60, v60 row_half_mirror row_mask:0xf bank_mask:0xf bound_ctrl:1
	v_pk_mul_f32 v[60:61], v[54:55], v[92:93]
	v_pk_mul_f32 v[54:55], v[54:55], v[114:115]
	v_pk_fma_f32 v[60:61], v[52:53], v[84:85], v[60:61]
	v_pk_fma_f32 v[70:71], v[52:53], v[98:99], v[70:71]
	v_pk_fma_f32 v[72:73], v[52:53], v[102:103], v[72:73]
	v_pk_fma_f32 v[52:53], v[52:53], v[106:107], v[54:55]
	v_pk_add_f32 v[60:61], v[60:61], v[60:61] op_sel:[0,1] op_sel_hi:[1,0]
	v_pk_add_f32 v[68:69], v[68:69], v[68:69] op_sel:[0,1] op_sel_hi:[1,0]
	v_pk_add_f32 v[52:53], v[52:53], v[52:53] op_sel:[0,1] op_sel_hi:[1,0]
	v_pk_add_f32 v[62:63], v[62:63], v[62:63] op_sel:[0,1] op_sel_hi:[1,0]
	v_cndmask_b32_e32 v53, v68, v60, vcc
	v_mov_b32_e32 v55, v53
	v_pk_add_f32 v[70:71], v[70:71], v[70:71] op_sel:[0,1] op_sel_hi:[1,0]
	s_nop 0
	v_permlane32_swap_b32_e32 v53, v55
	v_cndmask_b32_e32 v54, v60, v68, vcc
	v_cndmask_b32_e32 v53, v55, v53, vcc
	v_add_f32_e32 v53, v54, v53
	v_cndmask_b32_e32 v54, v70, v62, vcc
	v_mov_b32_e32 v60, v54
	v_pk_add_f32 v[64:65], v[64:65], v[64:65] op_sel:[0,1] op_sel_hi:[1,0]
	s_nop 0
	v_permlane32_swap_b32_e32 v54, v60
	v_pk_add_f32 v[72:73], v[72:73], v[72:73] op_sel:[0,1] op_sel_hi:[1,0]
	v_cndmask_b32_e32 v55, v62, v70, vcc
	v_cndmask_b32_e32 v54, v60, v54, vcc
	v_add_f32_e32 v54, v55, v54
	v_cndmask_b32_e32 v55, v72, v64, vcc
	v_mov_b32_e32 v61, v55
	v_pk_add_f32 v[66:67], v[66:67], v[66:67] op_sel:[0,1] op_sel_hi:[1,0]
	s_nop 0
	v_permlane32_swap_b32_e32 v55, v61
	v_cndmask_b32_e32 v60, v64, v72, vcc
	v_cndmask_b32_e32 v55, v61, v55, vcc
	v_add_f32_e32 v55, v60, v55
	v_cndmask_b32_e32 v60, v52, v66, vcc
	v_mov_b32_e32 v61, v60
	v_cndmask_b32_e32 v52, v66, v52, vcc
	s_nop 0
	v_permlane32_swap_b32_e32 v60, v61
	v_cndmask_b32_e32 v60, v61, v60, vcc
	v_add_f32_e32 v52, v52, v60
	v_cndmask_b32_e64 v60, v53, v55, s[2:3]
	v_cndmask_b32_e64 v53, v55, v53, s[2:3]
	v_mov_b32_e32 v55, v60
	s_waitcnt vmcnt(19)
	v_pk_mul_f32 v[62:63], v[50:51], v[104:105]
	v_permlane16_swap_b32_e32 v60, v55
	v_cndmask_b32_e64 v55, v60, v55, s[2:3]
	v_add_f32_e32 v53, v53, v55
	v_cndmask_b32_e64 v55, v54, v52, s[2:3]
	v_cndmask_b32_e64 v52, v52, v54, s[2:3]
	v_mov_b32_e32 v54, v55
	v_pk_mul_f32 v[60:61], v[50:51], v[100:101]
	s_nop 0
	v_permlane16_swap_b32_e32 v55, v54
	v_cndmask_b32_e64 v54, v55, v54, s[2:3]
	v_add_f32_e32 v52, v52, v54
	v_cndmask_b32_e64 v54, v53, v52, s[4:5]
	v_cndmask_b32_e64 v52, v52, v53, s[4:5]
	v_pk_mul_f32 v[64:65], v[50:51], v[108:109]
	v_pk_mul_f32 v[66:67], v[50:51], v[110:111]
	v_add_f32_dpp v52, v54, v52 row_ror:8 row_mask:0xf bank_mask:0xf bound_ctrl:1
	v_pk_mul_f32 v[54:55], v[50:51], v[96:97]
	v_pk_mul_f32 v[68:69], v[50:51], v[112:113]
	v_add_f32_dpp v52, v52, v52 quad_perm:[1,0,3,2] row_mask:0xf bank_mask:0xf bound_ctrl:1
	v_pk_fma_f32 v[54:55], v[48:49], v[86:87], v[54:55]
	v_pk_fma_f32 v[60:61], v[48:49], v[88:89], v[60:61]
	v_add_f32_dpp v52, v52, v52 quad_perm:[2,3,0,1] row_mask:0xf bank_mask:0xf bound_ctrl:1
	v_pk_fma_f32 v[62:63], v[48:49], v[90:91], v[62:63]
	v_pk_fma_f32 v[64:65], v[48:49], v[94:95], v[64:65]
	v_add_f32_dpp v137, v52, v52 row_half_mirror row_mask:0xf bank_mask:0xf bound_ctrl:1
	v_pk_mul_f32 v[52:53], v[50:51], v[92:93]
	v_pk_mul_f32 v[50:51], v[50:51], v[114:115]
	v_pk_fma_f32 v[52:53], v[48:49], v[84:85], v[52:53]
	v_pk_fma_f32 v[66:67], v[48:49], v[98:99], v[66:67]
	v_pk_fma_f32 v[68:69], v[48:49], v[102:103], v[68:69]
	v_pk_fma_f32 v[48:49], v[48:49], v[106:107], v[50:51]
	v_pk_add_f32 v[52:53], v[52:53], v[52:53] op_sel:[0,1] op_sel_hi:[1,0]
	v_pk_add_f32 v[64:65], v[64:65], v[64:65] op_sel:[0,1] op_sel_hi:[1,0]
	v_pk_add_f32 v[48:49], v[48:49], v[48:49] op_sel:[0,1] op_sel_hi:[1,0]
	v_pk_add_f32 v[54:55], v[54:55], v[54:55] op_sel:[0,1] op_sel_hi:[1,0]
	v_cndmask_b32_e32 v49, v64, v52, vcc
	v_mov_b32_e32 v51, v49
	v_pk_add_f32 v[66:67], v[66:67], v[66:67] op_sel:[0,1] op_sel_hi:[1,0]
	s_nop 0
	v_permlane32_swap_b32_e32 v49, v51
	v_cndmask_b32_e32 v50, v52, v64, vcc
	v_cndmask_b32_e32 v49, v51, v49, vcc
	v_add_f32_e32 v49, v50, v49
	v_cndmask_b32_e32 v50, v66, v54, vcc
	v_mov_b32_e32 v52, v50
	v_pk_add_f32 v[60:61], v[60:61], v[60:61] op_sel:[0,1] op_sel_hi:[1,0]
	s_nop 0
	v_permlane32_swap_b32_e32 v50, v52
	v_pk_add_f32 v[68:69], v[68:69], v[68:69] op_sel:[0,1] op_sel_hi:[1,0]
	v_cndmask_b32_e32 v51, v54, v66, vcc
	v_cndmask_b32_e32 v50, v52, v50, vcc
	v_add_f32_e32 v50, v51, v50
	v_cndmask_b32_e32 v51, v68, v60, vcc
	v_mov_b32_e32 v53, v51
	v_pk_add_f32 v[62:63], v[62:63], v[62:63] op_sel:[0,1] op_sel_hi:[1,0]
	s_nop 0
	v_permlane32_swap_b32_e32 v51, v53
	v_cndmask_b32_e32 v52, v60, v68, vcc
	v_cndmask_b32_e32 v51, v53, v51, vcc
	v_add_f32_e32 v51, v52, v51
	v_cndmask_b32_e32 v52, v48, v62, vcc
	v_mov_b32_e32 v53, v52
	v_cndmask_b32_e32 v48, v62, v48, vcc
	s_nop 0
	v_permlane32_swap_b32_e32 v52, v53
	v_cndmask_b32_e32 v52, v53, v52, vcc
	v_add_f32_e32 v48, v48, v52
	v_cndmask_b32_e64 v52, v49, v51, s[2:3]
	v_cndmask_b32_e64 v49, v51, v49, s[2:3]
	v_mov_b32_e32 v51, v52
	s_waitcnt vmcnt(18)
	v_pk_mul_f32 v[54:55], v[46:47], v[104:105]
	v_permlane16_swap_b32_e32 v52, v51
	v_cndmask_b32_e64 v51, v52, v51, s[2:3]
	v_add_f32_e32 v49, v49, v51
	v_cndmask_b32_e64 v51, v50, v48, s[2:3]
	v_cndmask_b32_e64 v48, v48, v50, s[2:3]
	v_mov_b32_e32 v50, v51
	v_pk_mul_f32 v[52:53], v[46:47], v[100:101]
	s_nop 0
	v_permlane16_swap_b32_e32 v51, v50
	v_cndmask_b32_e64 v50, v51, v50, s[2:3]
	v_add_f32_e32 v48, v48, v50
	v_cndmask_b32_e64 v50, v49, v48, s[4:5]
	v_cndmask_b32_e64 v48, v48, v49, s[4:5]
	v_pk_mul_f32 v[60:61], v[46:47], v[108:109]
	v_pk_mul_f32 v[62:63], v[46:47], v[110:111]
	v_add_f32_dpp v48, v50, v48 row_ror:8 row_mask:0xf bank_mask:0xf bound_ctrl:1
	v_pk_mul_f32 v[50:51], v[46:47], v[96:97]
	v_pk_mul_f32 v[64:65], v[46:47], v[112:113]
	v_add_f32_dpp v48, v48, v48 quad_perm:[1,0,3,2] row_mask:0xf bank_mask:0xf bound_ctrl:1
	v_pk_fma_f32 v[50:51], v[44:45], v[86:87], v[50:51]
	v_pk_fma_f32 v[52:53], v[44:45], v[88:89], v[52:53]
	v_add_f32_dpp v48, v48, v48 quad_perm:[2,3,0,1] row_mask:0xf bank_mask:0xf bound_ctrl:1
	v_pk_fma_f32 v[54:55], v[44:45], v[90:91], v[54:55]
	v_pk_fma_f32 v[60:61], v[44:45], v[94:95], v[60:61]
	v_add_f32_dpp v139, v48, v48 row_half_mirror row_mask:0xf bank_mask:0xf bound_ctrl:1
	v_pk_mul_f32 v[48:49], v[46:47], v[92:93]
	v_pk_mul_f32 v[46:47], v[46:47], v[114:115]
	v_pk_fma_f32 v[48:49], v[44:45], v[84:85], v[48:49]
	v_pk_fma_f32 v[62:63], v[44:45], v[98:99], v[62:63]
	v_pk_fma_f32 v[64:65], v[44:45], v[102:103], v[64:65]
	v_pk_fma_f32 v[44:45], v[44:45], v[106:107], v[46:47]
	v_pk_add_f32 v[48:49], v[48:49], v[48:49] op_sel:[0,1] op_sel_hi:[1,0]
	v_pk_add_f32 v[60:61], v[60:61], v[60:61] op_sel:[0,1] op_sel_hi:[1,0]
	v_pk_add_f32 v[44:45], v[44:45], v[44:45] op_sel:[0,1] op_sel_hi:[1,0]
	v_pk_add_f32 v[50:51], v[50:51], v[50:51] op_sel:[0,1] op_sel_hi:[1,0]
	v_cndmask_b32_e32 v45, v60, v48, vcc
	v_mov_b32_e32 v47, v45
	v_pk_add_f32 v[62:63], v[62:63], v[62:63] op_sel:[0,1] op_sel_hi:[1,0]
	s_nop 0
	v_permlane32_swap_b32_e32 v45, v47
	v_cndmask_b32_e32 v46, v48, v60, vcc
	v_cndmask_b32_e32 v45, v47, v45, vcc
	v_add_f32_e32 v45, v46, v45
	v_cndmask_b32_e32 v46, v62, v50, vcc
	v_mov_b32_e32 v48, v46
	v_pk_add_f32 v[52:53], v[52:53], v[52:53] op_sel:[0,1] op_sel_hi:[1,0]
	s_nop 0
	v_permlane32_swap_b32_e32 v46, v48
	v_pk_add_f32 v[64:65], v[64:65], v[64:65] op_sel:[0,1] op_sel_hi:[1,0]
	v_cndmask_b32_e32 v47, v50, v62, vcc
	v_cndmask_b32_e32 v46, v48, v46, vcc
	v_add_f32_e32 v46, v47, v46
	v_cndmask_b32_e32 v47, v64, v52, vcc
	v_mov_b32_e32 v49, v47
	v_pk_add_f32 v[54:55], v[54:55], v[54:55] op_sel:[0,1] op_sel_hi:[1,0]
	s_nop 0
	v_permlane32_swap_b32_e32 v47, v49
	v_cndmask_b32_e32 v48, v52, v64, vcc
	v_cndmask_b32_e32 v47, v49, v47, vcc
	v_add_f32_e32 v47, v48, v47
	v_cndmask_b32_e32 v48, v44, v54, vcc
	v_mov_b32_e32 v49, v48
	v_cndmask_b32_e32 v44, v54, v44, vcc
	s_nop 0
	v_permlane32_swap_b32_e32 v48, v49
	v_cndmask_b32_e32 v48, v49, v48, vcc
	v_add_f32_e32 v44, v44, v48
	v_cndmask_b32_e64 v48, v45, v47, s[2:3]
	v_cndmask_b32_e64 v45, v47, v45, s[2:3]
	v_mov_b32_e32 v47, v48
	s_waitcnt vmcnt(17)
	v_pk_mul_f32 v[50:51], v[42:43], v[104:105]
	v_permlane16_swap_b32_e32 v48, v47
	v_cndmask_b32_e64 v47, v48, v47, s[2:3]
	v_add_f32_e32 v45, v45, v47
	v_cndmask_b32_e64 v47, v46, v44, s[2:3]
	v_cndmask_b32_e64 v44, v44, v46, s[2:3]
	v_mov_b32_e32 v46, v47
	v_pk_mul_f32 v[48:49], v[42:43], v[100:101]
	s_nop 0
	v_permlane16_swap_b32_e32 v47, v46
	v_cndmask_b32_e64 v46, v47, v46, s[2:3]
	v_add_f32_e32 v44, v44, v46
	v_cndmask_b32_e64 v46, v45, v44, s[4:5]
	v_cndmask_b32_e64 v44, v44, v45, s[4:5]
	v_pk_mul_f32 v[52:53], v[42:43], v[108:109]
	v_pk_mul_f32 v[54:55], v[42:43], v[110:111]
	v_add_f32_dpp v44, v46, v44 row_ror:8 row_mask:0xf bank_mask:0xf bound_ctrl:1
	v_pk_mul_f32 v[46:47], v[42:43], v[96:97]
	v_pk_mul_f32 v[60:61], v[42:43], v[112:113]
	v_add_f32_dpp v44, v44, v44 quad_perm:[1,0,3,2] row_mask:0xf bank_mask:0xf bound_ctrl:1
	v_pk_fma_f32 v[46:47], v[40:41], v[86:87], v[46:47]
	v_pk_fma_f32 v[48:49], v[40:41], v[88:89], v[48:49]
	v_add_f32_dpp v44, v44, v44 quad_perm:[2,3,0,1] row_mask:0xf bank_mask:0xf bound_ctrl:1
	v_pk_fma_f32 v[50:51], v[40:41], v[90:91], v[50:51]
	v_pk_fma_f32 v[52:53], v[40:41], v[94:95], v[52:53]
	v_add_f32_dpp v141, v44, v44 row_half_mirror row_mask:0xf bank_mask:0xf bound_ctrl:1
	v_pk_mul_f32 v[44:45], v[42:43], v[92:93]
	v_pk_mul_f32 v[42:43], v[42:43], v[114:115]
	v_pk_fma_f32 v[44:45], v[40:41], v[84:85], v[44:45]
	v_pk_fma_f32 v[54:55], v[40:41], v[98:99], v[54:55]
	v_pk_fma_f32 v[60:61], v[40:41], v[102:103], v[60:61]
	v_pk_fma_f32 v[40:41], v[40:41], v[106:107], v[42:43]
	v_pk_add_f32 v[44:45], v[44:45], v[44:45] op_sel:[0,1] op_sel_hi:[1,0]
	v_pk_add_f32 v[52:53], v[52:53], v[52:53] op_sel:[0,1] op_sel_hi:[1,0]
	v_pk_add_f32 v[40:41], v[40:41], v[40:41] op_sel:[0,1] op_sel_hi:[1,0]
	v_pk_add_f32 v[46:47], v[46:47], v[46:47] op_sel:[0,1] op_sel_hi:[1,0]
	v_cndmask_b32_e32 v41, v52, v44, vcc
	v_mov_b32_e32 v43, v41
	v_pk_add_f32 v[54:55], v[54:55], v[54:55] op_sel:[0,1] op_sel_hi:[1,0]
	s_nop 0
	v_permlane32_swap_b32_e32 v41, v43
	v_cndmask_b32_e32 v42, v44, v52, vcc
	v_cndmask_b32_e32 v41, v43, v41, vcc
	v_add_f32_e32 v41, v42, v41
	v_cndmask_b32_e32 v42, v54, v46, vcc
	v_mov_b32_e32 v44, v42
	v_pk_add_f32 v[48:49], v[48:49], v[48:49] op_sel:[0,1] op_sel_hi:[1,0]
	s_nop 0
	v_permlane32_swap_b32_e32 v42, v44
	v_pk_add_f32 v[60:61], v[60:61], v[60:61] op_sel:[0,1] op_sel_hi:[1,0]
	v_cndmask_b32_e32 v43, v46, v54, vcc
	v_cndmask_b32_e32 v42, v44, v42, vcc
	v_add_f32_e32 v42, v43, v42
	v_cndmask_b32_e32 v43, v60, v48, vcc
	v_mov_b32_e32 v45, v43
	v_pk_add_f32 v[50:51], v[50:51], v[50:51] op_sel:[0,1] op_sel_hi:[1,0]
	s_nop 0
	v_permlane32_swap_b32_e32 v43, v45
	v_cndmask_b32_e32 v44, v48, v60, vcc
	v_cndmask_b32_e32 v43, v45, v43, vcc
	v_add_f32_e32 v43, v44, v43
	v_cndmask_b32_e32 v44, v40, v50, vcc
	v_mov_b32_e32 v45, v44
	v_cndmask_b32_e32 v40, v50, v40, vcc
	s_nop 0
	v_permlane32_swap_b32_e32 v44, v45
	v_cndmask_b32_e32 v44, v45, v44, vcc
	v_add_f32_e32 v40, v40, v44
	v_cndmask_b32_e64 v44, v41, v43, s[2:3]
	v_cndmask_b32_e64 v41, v43, v41, s[2:3]
	v_mov_b32_e32 v43, v44
	s_waitcnt vmcnt(16)
	v_pk_mul_f32 v[46:47], v[38:39], v[104:105]
	v_permlane16_swap_b32_e32 v44, v43
	v_cndmask_b32_e64 v43, v44, v43, s[2:3]
	v_add_f32_e32 v41, v41, v43
	v_cndmask_b32_e64 v43, v42, v40, s[2:3]
	v_cndmask_b32_e64 v40, v40, v42, s[2:3]
	v_mov_b32_e32 v42, v43
	v_pk_mul_f32 v[44:45], v[38:39], v[100:101]
	s_nop 0
	v_permlane16_swap_b32_e32 v43, v42
	v_cndmask_b32_e64 v42, v43, v42, s[2:3]
	v_add_f32_e32 v40, v40, v42
	v_cndmask_b32_e64 v42, v41, v40, s[4:5]
	v_cndmask_b32_e64 v40, v40, v41, s[4:5]
	v_pk_mul_f32 v[48:49], v[38:39], v[108:109]
	v_pk_mul_f32 v[50:51], v[38:39], v[110:111]
	v_add_f32_dpp v40, v42, v40 row_ror:8 row_mask:0xf bank_mask:0xf bound_ctrl:1
	v_pk_mul_f32 v[42:43], v[38:39], v[96:97]
	v_pk_mul_f32 v[52:53], v[38:39], v[112:113]
	v_add_f32_dpp v40, v40, v40 quad_perm:[1,0,3,2] row_mask:0xf bank_mask:0xf bound_ctrl:1
	v_pk_fma_f32 v[42:43], v[36:37], v[86:87], v[42:43]
	v_pk_fma_f32 v[44:45], v[36:37], v[88:89], v[44:45]
	v_add_f32_dpp v40, v40, v40 quad_perm:[2,3,0,1] row_mask:0xf bank_mask:0xf bound_ctrl:1
	v_pk_fma_f32 v[46:47], v[36:37], v[90:91], v[46:47]
	v_pk_fma_f32 v[48:49], v[36:37], v[94:95], v[48:49]
	v_add_f32_dpp v143, v40, v40 row_half_mirror row_mask:0xf bank_mask:0xf bound_ctrl:1
	v_pk_mul_f32 v[40:41], v[38:39], v[92:93]
	v_pk_mul_f32 v[38:39], v[38:39], v[114:115]
	v_pk_fma_f32 v[40:41], v[36:37], v[84:85], v[40:41]
	v_pk_fma_f32 v[50:51], v[36:37], v[98:99], v[50:51]
	v_pk_fma_f32 v[52:53], v[36:37], v[102:103], v[52:53]
	v_pk_fma_f32 v[36:37], v[36:37], v[106:107], v[38:39]
	v_pk_add_f32 v[40:41], v[40:41], v[40:41] op_sel:[0,1] op_sel_hi:[1,0]
	v_pk_add_f32 v[48:49], v[48:49], v[48:49] op_sel:[0,1] op_sel_hi:[1,0]
	v_pk_add_f32 v[36:37], v[36:37], v[36:37] op_sel:[0,1] op_sel_hi:[1,0]
	v_pk_add_f32 v[42:43], v[42:43], v[42:43] op_sel:[0,1] op_sel_hi:[1,0]
	v_cndmask_b32_e32 v37, v48, v40, vcc
	v_mov_b32_e32 v39, v37
	v_pk_add_f32 v[50:51], v[50:51], v[50:51] op_sel:[0,1] op_sel_hi:[1,0]
	s_nop 0
	v_permlane32_swap_b32_e32 v37, v39
	v_cndmask_b32_e32 v38, v40, v48, vcc
	v_cndmask_b32_e32 v37, v39, v37, vcc
	v_add_f32_e32 v37, v38, v37
	v_cndmask_b32_e32 v38, v50, v42, vcc
	v_mov_b32_e32 v40, v38
	v_pk_add_f32 v[44:45], v[44:45], v[44:45] op_sel:[0,1] op_sel_hi:[1,0]
	s_nop 0
	v_permlane32_swap_b32_e32 v38, v40
	v_pk_add_f32 v[52:53], v[52:53], v[52:53] op_sel:[0,1] op_sel_hi:[1,0]
	v_cndmask_b32_e32 v39, v42, v50, vcc
	v_cndmask_b32_e32 v38, v40, v38, vcc
	v_add_f32_e32 v50, v39, v38
	v_cndmask_b32_e32 v38, v52, v44, vcc
	v_mov_b32_e32 v40, v38
	v_pk_add_f32 v[46:47], v[46:47], v[46:47] op_sel:[0,1] op_sel_hi:[1,0]
	s_nop 0
	v_permlane32_swap_b32_e32 v38, v40
	v_cndmask_b32_e32 v39, v44, v52, vcc
	v_cndmask_b32_e32 v38, v40, v38, vcc
	v_add_f32_e32 v38, v39, v38
	v_cndmask_b32_e32 v39, v36, v46, vcc
	v_mov_b32_e32 v40, v39
	v_cndmask_b32_e32 v36, v46, v36, vcc
	s_nop 0
	v_permlane32_swap_b32_e32 v39, v40
	v_cndmask_b32_e32 v39, v40, v39, vcc
	v_add_f32_e32 v51, v36, v39
	v_cndmask_b32_e64 v52, v37, v38, s[2:3]
	v_cndmask_b32_e64 v53, v38, v37, s[2:3]
	s_waitcnt vmcnt(15)
	v_pk_mul_f32 v[36:37], v[34:35], v[92:93]
	v_pk_mul_f32 v[38:39], v[34:35], v[96:97]
	v_pk_mul_f32 v[40:41], v[34:35], v[100:101]
	v_pk_mul_f32 v[42:43], v[34:35], v[104:105]
	v_pk_mul_f32 v[44:45], v[34:35], v[108:109]
	v_pk_mul_f32 v[46:47], v[34:35], v[110:111]
	v_pk_mul_f32 v[48:49], v[34:35], v[112:113]
	v_pk_mul_f32 v[34:35], v[34:35], v[114:115]
	v_pk_fma_f32 v[36:37], v[32:33], v[84:85], v[36:37]
	v_pk_fma_f32 v[38:39], v[32:33], v[86:87], v[38:39]
	v_pk_fma_f32 v[40:41], v[32:33], v[88:89], v[40:41]
	v_pk_fma_f32 v[42:43], v[32:33], v[90:91], v[42:43]
	v_pk_fma_f32 v[44:45], v[32:33], v[94:95], v[44:45]
	v_pk_fma_f32 v[46:47], v[32:33], v[98:99], v[46:47]
	v_pk_fma_f32 v[48:49], v[32:33], v[102:103], v[48:49]
	v_pk_fma_f32 v[32:33], v[32:33], v[106:107], v[34:35]
	v_pk_add_f32 v[36:37], v[36:37], v[36:37] op_sel:[0,1] op_sel_hi:[1,0]
	v_pk_add_f32 v[44:45], v[44:45], v[44:45] op_sel:[0,1] op_sel_hi:[1,0]
	v_pk_add_f32 v[32:33], v[32:33], v[32:33] op_sel:[0,1] op_sel_hi:[1,0]
	v_cndmask_b32_e64 v55, v50, v51, s[2:3]
	v_cndmask_b32_e32 v33, v44, v36, vcc
	v_mov_b32_e32 v54, v52
	v_mov_b32_e32 v60, v55
	v_mov_b32_e32 v35, v33
	v_pk_add_f32 v[38:39], v[38:39], v[38:39] op_sel:[0,1] op_sel_hi:[1,0]
	s_nop 0
	v_permlane32_swap_b32_e32 v33, v35
	v_pk_add_f32 v[46:47], v[46:47], v[46:47] op_sel:[0,1] op_sel_hi:[1,0]
	v_cndmask_b32_e32 v34, v36, v44, vcc
	v_cndmask_b32_e32 v33, v35, v33, vcc
	v_add_f32_e32 v33, v34, v33
	v_cndmask_b32_e32 v34, v46, v38, vcc
	v_mov_b32_e32 v36, v34
	v_pk_add_f32 v[40:41], v[40:41], v[40:41] op_sel:[0,1] op_sel_hi:[1,0]
	s_nop 0
	v_permlane32_swap_b32_e32 v34, v36
	v_pk_add_f32 v[48:49], v[48:49], v[48:49] op_sel:[0,1] op_sel_hi:[1,0]
	v_cndmask_b32_e32 v35, v38, v46, vcc
	v_cndmask_b32_e32 v34, v36, v34, vcc
	v_add_f32_e32 v34, v35, v34
	v_cndmask_b32_e32 v35, v48, v40, vcc
	v_mov_b32_e32 v37, v35
	v_pk_add_f32 v[42:43], v[42:43], v[42:43] op_sel:[0,1] op_sel_hi:[1,0]
	s_nop 0
	v_permlane32_swap_b32_e32 v35, v37
	v_cndmask_b32_e32 v36, v40, v48, vcc
	v_cndmask_b32_e32 v35, v37, v35, vcc
	v_add_f32_e32 v35, v36, v35
	v_cndmask_b32_e32 v36, v32, v42, vcc
	v_mov_b32_e32 v37, v36
	v_cndmask_b32_e32 v32, v42, v32, vcc
	s_nop 0
	v_permlane32_swap_b32_e32 v36, v37
	v_cndmask_b32_e32 v36, v37, v36, vcc
	v_add_f32_e32 v32, v32, v36
	v_cndmask_b32_e64 v36, v33, v35, s[2:3]
	v_cndmask_b32_e64 v38, v34, v32, s[2:3]
	v_mov_b32_e32 v37, v36
	v_mov_b32_e32 v39, v38
	s_waitcnt vmcnt(0)
	v_mov_b32_e32 v150, v222
	v_mov_b32_e32 v151, v223
	v_mov_b32_e32 v152, v224
	v_mov_b32_e32 v153, v225
	v_permlane16_swap_b32_e32 v36, v37
	v_permlane16_swap_b32_e32 v38, v39
	v_cndmask_b32_e64 v33, v35, v33, s[2:3]
	v_cndmask_b32_e64 v35, v36, v37, s[2:3]
	v_cndmask_b32_e64 v32, v32, v34, s[2:3]
	v_cndmask_b32_e64 v34, v38, v39, s[2:3]
	v_add_f32_e32 v33, v33, v35
	v_add_f32_e32 v32, v32, v34
	v_cndmask_b32_e64 v34, v33, v32, s[4:5]
	v_cndmask_b32_e64 v32, v32, v33, s[4:5]
	v_permlane16_swap_b32_e32 v52, v54
	s_nop 0
	v_add_f32_dpp v32, v34, v32 row_ror:8 row_mask:0xf bank_mask:0xf bound_ctrl:1
	v_cndmask_b32_e64 v40, v52, v54, s[2:3]
	v_permlane16_swap_b32_e32 v55, v60
	v_add_f32_dpp v32, v32, v32 quad_perm:[1,0,3,2] row_mask:0xf bank_mask:0xf bound_ctrl:1
	v_add_f32_e32 v40, v53, v40
	v_cndmask_b32_e64 v41, v51, v50, s[2:3]
	v_add_f32_dpp v32, v32, v32 quad_perm:[2,3,0,1] row_mask:0xf bank_mask:0xf bound_ctrl:1
	v_cndmask_b32_e64 v42, v55, v60, s[2:3]
	v_add_f32_e32 v41, v41, v42
	v_add_f32_dpp v146, v32, v32 row_half_mirror row_mask:0xf bank_mask:0xf bound_ctrl:1
	v_add_co_u32_e64 v32, s[6:7], s43, v116
	v_cndmask_b32_e64 v42, v40, v41, s[4:5]
	s_nop 0
	v_addc_co_u32_e64 v33, s[6:7], 0, v117, s[6:7]
	v_mov_b32_e32 v158, v226
	v_mov_b32_e32 v159, v227
	v_mov_b32_e32 v160, v228
	v_mov_b32_e32 v161, v229
	v_mov_b32_e32 v162, v230
	v_mov_b32_e32 v163, v231
	v_mov_b32_e32 v164, v232
	v_mov_b32_e32 v165, v233
	v_add_co_u32_e64 v32, s[6:7], s38, v116
	v_cndmask_b32_e64 v40, v41, v40, s[4:5]
	s_nop 0
	v_addc_co_u32_e64 v33, s[6:7], 0, v117, s[6:7]
	v_mov_b32_e32 v80, v234
	v_mov_b32_e32 v81, v235
	v_mov_b32_e32 v82, v236
	v_mov_b32_e32 v83, v237
	v_mov_b32_e32 v76, v238
	v_mov_b32_e32 v77, v239
	v_mov_b32_e32 v78, v240
	v_mov_b32_e32 v79, v241
	v_add_co_u32_e64 v32, s[6:7], s44, v116
	v_add_f32_dpp v40, v42, v40 row_ror:8 row_mask:0xf bank_mask:0xf bound_ctrl:1
	s_nop 0
	v_addc_co_u32_e64 v33, s[6:7], 0, v117, s[6:7]
	v_add_co_u32_e64 v120, s[6:7], s39, v116
	v_mov_b32_e32 v72, v242
	v_mov_b32_e32 v73, v243
	v_mov_b32_e32 v74, v244
	v_mov_b32_e32 v75, v245
	v_mov_b32_e32 v68, v250
	v_mov_b32_e32 v69, v251
	v_mov_b32_e32 v70, v252
	v_mov_b32_e32 v71, v253
	v_addc_co_u32_e64 v121, s[6:7], 0, v117, s[6:7]
	v_add_co_u32_e64 v32, s[6:7], s43, v124
	global_load_dwordx4 v[64:67], v[120:121], off offset:-4096 nt
	global_load_dwordx4 v[60:63], v[56:57], off nt
	v_addc_co_u32_e64 v33, s[6:7], 0, v125, s[6:7]
	global_load_dwordx4 v[56:59], v[32:33], off offset:-4096 nt
	global_load_dwordx4 v[52:55], v[32:33], off nt
	v_add_co_u32_e64 v32, s[6:7], s38, v124
	v_add_f32_dpp v40, v40, v40 quad_perm:[1,0,3,2] row_mask:0xf bank_mask:0xf bound_ctrl:1
	s_nop 0
	v_addc_co_u32_e64 v33, s[6:7], 0, v125, s[6:7]
	global_load_dwordx4 v[48:51], v[32:33], off offset:-4096 nt
	global_load_dwordx4 v[44:47], v[32:33], off nt
	v_add_co_u32_e64 v32, s[6:7], s44, v124
	v_add_f32_dpp v40, v40, v40 quad_perm:[2,3,0,1] row_mask:0xf bank_mask:0xf bound_ctrl:1
	s_nop 0
	v_addc_co_u32_e64 v33, s[6:7], 0, v125, s[6:7]
	v_add_co_u32_e64 v126, s[6:7], s39, v124
	v_add_f32_dpp v145, v40, v40 row_half_mirror row_mask:0xf bank_mask:0xf bound_ctrl:1
	s_nop 0
	v_addc_co_u32_e64 v127, s[6:7], 0, v125, s[6:7]
	global_load_dwordx4 v[40:43], v[32:33], off offset:-4096 nt
	global_load_dwordx4 v[36:39], v[32:33], off nt
	v_mul_f32_e32 v134, 0x3d800000, v133
	global_load_dwordx4 v[32:35], v[126:127], off offset:-4096 nt
	v_add_co_u32_e64 v254, s[100:101], s41, v116
	s_nop 1
	v_addc_co_u32_e64 v255, s[100:101], 0, v117, s[100:101]
	global_load_dwordx4 v[222:225], v[254:255], off offset:-4096 nt
	v_add_co_u32_e64 v254, s[100:101], s39, v116
	s_nop 1
	v_addc_co_u32_e64 v255, s[100:101], 0, v117, s[100:101]
	global_load_dwordx4 v[226:229], v[254:255], off nt
	v_add_co_u32_e64 v254, s[100:101], s46, v116
	s_nop 1
	v_addc_co_u32_e64 v255, s[100:101], 0, v117, s[100:101]
	global_load_dwordx4 v[230:233], v[254:255], off nt
	global_load_dwordx4 v[234:237], v[254:255], off offset:-4096 nt
	v_add_co_u32_e64 v254, s[100:101], s47, v116
	s_nop 1
	v_addc_co_u32_e64 v255, s[100:101], 0, v117, s[100:101]
	global_load_dwordx4 v[238:241], v[254:255], off nt
	global_load_dwordx4 v[242:245], v[254:255], off offset:-4096 nt
	v_add_co_u32_e64 v254, s[100:101], s40, v116
	s_nop 1
	v_addc_co_u32_e64 v255, s[100:101], 0, v117, s[100:101]
	global_load_dwordx4 v[250:253], v[254:255], off nt
	v_mul_f32_e32 v136, 0x3d800000, v135
	v_mul_f32_e32 v138, 0x3d800000, v137
	v_mul_f32_e32 v140, 0x3d800000, v139
	v_max_f32_e32 v134, v134, v136
	v_mul_f32_e32 v142, 0x3d800000, v141
	v_mul_f32_e32 v144, 0x3d800000, v143
	v_max3_f32 v134, v134, v138, v140
	v_pk_mul_f32 v[118:119], v[152:153], v[92:93]
	v_pk_mul_f32 v[168:169], v[152:153], v[108:109]
	v_pk_fma_f32 v[118:119], v[150:151], v[84:85], v[118:119]
	v_pk_mul_f32 v[122:123], v[152:153], v[96:97]
	v_pk_fma_f32 v[168:169], v[150:151], v[94:95], v[168:169]
	v_pk_add_f32 v[118:119], v[118:119], v[118:119] op_sel:[0,1] op_sel_hi:[1,0]
	v_pk_fma_f32 v[122:123], v[150:151], v[86:87], v[122:123]
	v_pk_add_f32 v[168:169], v[168:169], v[168:169] op_sel:[0,1] op_sel_hi:[1,0]
	v_pk_add_f32 v[122:123], v[122:123], v[122:123] op_sel:[0,1] op_sel_hi:[1,0]
	v_cndmask_b32_e32 v119, v168, v118, vcc
	v_mov_b32_e32 v123, v119
	v_pk_mul_f32 v[170:171], v[152:153], v[110:111]
	v_cndmask_b32_e32 v118, v118, v168, vcc
	v_pk_fma_f32 v[170:171], v[150:151], v[98:99], v[170:171]
	v_permlane32_swap_b32_e32 v119, v123
	v_pk_add_f32 v[170:171], v[170:171], v[170:171] op_sel:[0,1] op_sel_hi:[1,0]
	v_cndmask_b32_e32 v119, v123, v119, vcc
	v_add_f32_e32 v118, v118, v119
	v_cndmask_b32_e32 v119, v170, v122, vcc
	v_mov_b32_e32 v123, v119
	v_pk_mul_f32 v[154:155], v[152:153], v[100:101]
	v_pk_mul_f32 v[172:173], v[152:153], v[112:113]
	v_pk_fma_f32 v[154:155], v[150:151], v[88:89], v[154:155]
	v_pk_fma_f32 v[172:173], v[150:151], v[102:103], v[172:173]
	v_permlane32_swap_b32_e32 v119, v123
	v_pk_add_f32 v[154:155], v[154:155], v[154:155] op_sel:[0,1] op_sel_hi:[1,0]
	v_pk_add_f32 v[172:173], v[172:173], v[172:173] op_sel:[0,1] op_sel_hi:[1,0]
	v_cndmask_b32_e32 v122, v122, v170, vcc
	v_cndmask_b32_e32 v119, v123, v119, vcc
	v_add_f32_e32 v119, v122, v119
	v_cndmask_b32_e32 v122, v172, v154, vcc
	v_mov_b32_e32 v149, v122
	v_pk_mul_f32 v[166:167], v[152:153], v[104:105]
	v_pk_mul_f32 v[152:153], v[152:153], v[114:115]
	v_pk_fma_f32 v[166:167], v[150:151], v[90:91], v[166:167]
	v_pk_fma_f32 v[150:151], v[150:151], v[106:107], v[152:153]
	v_permlane32_swap_b32_e32 v122, v149
	v_pk_add_f32 v[166:167], v[166:167], v[166:167] op_sel:[0,1] op_sel_hi:[1,0]
	v_pk_add_f32 v[150:151], v[150:151], v[150:151] op_sel:[0,1] op_sel_hi:[1,0]
	v_cndmask_b32_e32 v123, v154, v172, vcc
	v_cndmask_b32_e32 v122, v149, v122, vcc
	v_add_f32_e32 v122, v123, v122
	v_cndmask_b32_e32 v123, v150, v166, vcc
	v_cndmask_b32_e32 v149, v166, v150, vcc
	v_mov_b32_e32 v150, v123
	v_pk_mul_f32 v[166:167], v[160:161], v[108:109]
	v_permlane32_swap_b32_e32 v123, v150
	v_cndmask_b32_e32 v123, v150, v123, vcc
	v_add_f32_e32 v123, v149, v123
	v_cndmask_b32_e64 v149, v118, v122, s[2:3]
	v_cndmask_b32_e64 v118, v122, v118, s[2:3]
	v_mov_b32_e32 v122, v149
	v_pk_fma_f32 v[166:167], v[158:159], v[94:95], v[166:167]
	s_nop 0
	v_permlane16_swap_b32_e32 v149, v122
	v_cndmask_b32_e64 v122, v149, v122, s[2:3]
	v_add_f32_e32 v118, v118, v122
	v_cndmask_b32_e64 v122, v119, v123, s[2:3]
	v_cndmask_b32_e64 v119, v123, v119, s[2:3]
	v_mov_b32_e32 v123, v122
	v_pk_add_f32 v[166:167], v[166:167], v[166:167] op_sel:[0,1] op_sel_hi:[1,0]
	s_nop 0
	v_permlane16_swap_b32_e32 v122, v123
	v_cndmask_b32_e64 v122, v122, v123, s[2:3]
	v_add_f32_e32 v119, v119, v122
	v_cndmask_b32_e64 v122, v118, v119, s[4:5]
	v_cndmask_b32_e64 v118, v119, v118, s[4:5]
	v_pk_mul_f32 v[168:169], v[160:161], v[110:111]
	v_pk_mul_f32 v[152:153], v[160:161], v[100:101]
	v_add_f32_dpp v118, v122, v118 row_ror:8 row_mask:0xf bank_mask:0xf bound_ctrl:1
	v_pk_mul_f32 v[122:123], v[160:161], v[96:97]
	v_pk_fma_f32 v[168:169], v[158:159], v[98:99], v[168:169]
	v_add_f32_dpp v118, v118, v118 quad_perm:[1,0,3,2] row_mask:0xf bank_mask:0xf bound_ctrl:1
	v_pk_fma_f32 v[122:123], v[158:159], v[86:87], v[122:123]
	v_pk_add_f32 v[168:169], v[168:169], v[168:169] op_sel:[0,1] op_sel_hi:[1,0]
	v_add_f32_dpp v118, v118, v118 quad_perm:[2,3,0,1] row_mask:0xf bank_mask:0xf bound_ctrl:1
	v_pk_add_f32 v[122:123], v[122:123], v[122:123] op_sel:[0,1] op_sel_hi:[1,0]
	v_pk_mul_f32 v[170:171], v[160:161], v[112:113]
	v_add_f32_dpp v149, v118, v118 row_half_mirror row_mask:0xf bank_mask:0xf bound_ctrl:1
	v_pk_mul_f32 v[118:119], v[160:161], v[92:93]
	v_pk_fma_f32 v[152:153], v[158:159], v[88:89], v[152:153]
	v_pk_fma_f32 v[118:119], v[158:159], v[84:85], v[118:119]
	v_pk_fma_f32 v[170:171], v[158:159], v[102:103], v[170:171]
	v_pk_add_f32 v[118:119], v[118:119], v[118:119] op_sel:[0,1] op_sel_hi:[1,0]
	v_pk_add_f32 v[152:153], v[152:153], v[152:153] op_sel:[0,1] op_sel_hi:[1,0]
	v_cndmask_b32_e32 v119, v166, v118, vcc
	v_mov_b32_e32 v123, v119
	v_cndmask_b32_e32 v118, v118, v166, vcc
	s_nop 0
	v_permlane32_swap_b32_e32 v119, v123
	v_cndmask_b32_e32 v119, v123, v119, vcc
	v_add_f32_e32 v118, v118, v119
	v_cndmask_b32_e32 v119, v168, v122, vcc
	v_mov_b32_e32 v123, v119
	v_pk_add_f32 v[170:171], v[170:171], v[170:171] op_sel:[0,1] op_sel_hi:[1,0]
	s_nop 0
	v_permlane32_swap_b32_e32 v119, v123
	v_cndmask_b32_e32 v122, v122, v168, vcc
	v_cndmask_b32_e32 v119, v123, v119, vcc
	v_add_f32_e32 v119, v122, v119
	v_cndmask_b32_e32 v122, v170, v152, vcc
	v_mov_b32_e32 v151, v122
	v_pk_mul_f32 v[154:155], v[160:161], v[104:105]
	v_pk_mul_f32 v[160:161], v[160:161], v[114:115]
	v_pk_fma_f32 v[154:155], v[158:159], v[90:91], v[154:155]
	v_pk_fma_f32 v[158:159], v[158:159], v[106:107], v[160:161]
	v_permlane32_swap_b32_e32 v122, v151
	v_pk_add_f32 v[154:155], v[154:155], v[154:155] op_sel:[0,1] op_sel_hi:[1,0]
	v_pk_add_f32 v[158:159], v[158:159], v[158:159] op_sel:[0,1] op_sel_hi:[1,0]
	v_cndmask_b32_e32 v123, v152, v170, vcc
	v_cndmask_b32_e32 v122, v151, v122, vcc
	v_add_f32_e32 v122, v123, v122
	v_cndmask_b32_e32 v123, v158, v154, vcc
	v_mov_b32_e32 v152, v123
	v_cndmask_b32_e32 v151, v154, v158, vcc
	s_nop 0
	v_permlane32_swap_b32_e32 v123, v152
	v_cndmask_b32_e32 v123, v152, v123, vcc
	v_add_f32_e32 v123, v151, v123
	v_cndmask_b32_e64 v151, v118, v122, s[2:3]
	v_cndmask_b32_e64 v118, v122, v118, s[2:3]
	v_mov_b32_e32 v122, v151
	v_pk_mul_f32 v[160:161], v[164:165], v[108:109]
	v_permlane16_swap_b32_e32 v151, v122
	v_cndmask_b32_e64 v122, v151, v122, s[2:3]
	v_add_f32_e32 v118, v118, v122
	v_cndmask_b32_e64 v122, v119, v123, s[2:3]
	v_cndmask_b32_e64 v119, v123, v119, s[2:3]
	v_mov_b32_e32 v123, v122
	v_pk_fma_f32 v[160:161], v[162:163], v[94:95], v[160:161]
	s_nop 0
	v_permlane16_swap_b32_e32 v122, v123
	v_cndmask_b32_e64 v122, v122, v123, s[2:3]
	v_add_f32_e32 v119, v119, v122
	v_cndmask_b32_e64 v122, v118, v119, s[4:5]
	v_cndmask_b32_e64 v118, v119, v118, s[4:5]
	v_pk_add_f32 v[160:161], v[160:161], v[160:161] op_sel:[0,1] op_sel_hi:[1,0]
	v_pk_mul_f32 v[166:167], v[164:165], v[110:111]
	v_add_f32_dpp v118, v122, v118 row_ror:8 row_mask:0xf bank_mask:0xf bound_ctrl:1
	v_pk_mul_f32 v[122:123], v[164:165], v[96:97]
	v_pk_fma_f32 v[166:167], v[162:163], v[98:99], v[166:167]
	v_add_f32_dpp v118, v118, v118 quad_perm:[1,0,3,2] row_mask:0xf bank_mask:0xf bound_ctrl:1
	v_pk_fma_f32 v[122:123], v[162:163], v[86:87], v[122:123]
	v_pk_add_f32 v[166:167], v[166:167], v[166:167] op_sel:[0,1] op_sel_hi:[1,0]
	v_add_f32_dpp v118, v118, v118 quad_perm:[2,3,0,1] row_mask:0xf bank_mask:0xf bound_ctrl:1
	v_pk_add_f32 v[122:123], v[122:123], v[122:123] op_sel:[0,1] op_sel_hi:[1,0]
	v_pk_mul_f32 v[154:155], v[164:165], v[100:101]
	v_add_f32_dpp v151, v118, v118 row_half_mirror row_mask:0xf bank_mask:0xf bound_ctrl:1
	v_pk_mul_f32 v[118:119], v[164:165], v[92:93]
	v_pk_mul_f32 v[168:169], v[164:165], v[112:113]
	v_pk_fma_f32 v[118:119], v[162:163], v[84:85], v[118:119]
	v_pk_fma_f32 v[154:155], v[162:163], v[88:89], v[154:155]
	v_pk_add_f32 v[118:119], v[118:119], v[118:119] op_sel:[0,1] op_sel_hi:[1,0]
	v_pk_fma_f32 v[168:169], v[162:163], v[102:103], v[168:169]
	v_cndmask_b32_e32 v119, v160, v118, vcc
	v_mov_b32_e32 v123, v119
	v_cndmask_b32_e32 v118, v118, v160, vcc
	s_nop 0
	v_permlane32_swap_b32_e32 v119, v123
	v_cndmask_b32_e32 v119, v123, v119, vcc
	v_add_f32_e32 v118, v118, v119
	v_cndmask_b32_e32 v119, v166, v122, vcc
	v_mov_b32_e32 v123, v119
	v_pk_add_f32 v[154:155], v[154:155], v[154:155] op_sel:[0,1] op_sel_hi:[1,0]
	s_nop 0
	v_permlane32_swap_b32_e32 v119, v123
	v_pk_add_f32 v[168:169], v[168:169], v[168:169] op_sel:[0,1] op_sel_hi:[1,0]
	v_cndmask_b32_e32 v122, v122, v166, vcc
	v_cndmask_b32_e32 v119, v123, v119, vcc
	v_add_f32_e32 v119, v122, v119
	v_cndmask_b32_e32 v122, v168, v154, vcc
	v_mov_b32_e32 v153, v122
	v_pk_mul_f32 v[158:159], v[164:165], v[104:105]
	v_pk_mul_f32 v[164:165], v[164:165], v[114:115]
	v_pk_fma_f32 v[158:159], v[162:163], v[90:91], v[158:159]
	v_pk_fma_f32 v[162:163], v[162:163], v[106:107], v[164:165]
	v_permlane32_swap_b32_e32 v122, v153
	v_pk_add_f32 v[158:159], v[158:159], v[158:159] op_sel:[0,1] op_sel_hi:[1,0]
	v_pk_add_f32 v[162:163], v[162:163], v[162:163] op_sel:[0,1] op_sel_hi:[1,0]
	v_cndmask_b32_e32 v123, v154, v168, vcc
	v_cndmask_b32_e32 v122, v153, v122, vcc
	v_add_f32_e32 v122, v123, v122
	v_cndmask_b32_e32 v123, v162, v158, vcc
	v_mov_b32_e32 v154, v123
	v_cndmask_b32_e32 v153, v158, v162, vcc
	s_nop 0
	v_permlane32_swap_b32_e32 v123, v154
	v_cndmask_b32_e32 v123, v154, v123, vcc
	v_add_f32_e32 v123, v153, v123
	v_cndmask_b32_e64 v153, v118, v122, s[2:3]
	v_cndmask_b32_e64 v118, v122, v118, s[2:3]
	v_mov_b32_e32 v122, v153
	v_pk_mul_f32 v[158:159], v[82:83], v[100:101]
	v_permlane16_swap_b32_e32 v153, v122
	v_cndmask_b32_e64 v122, v153, v122, s[2:3]
	v_add_f32_e32 v118, v118, v122
	v_cndmask_b32_e64 v122, v119, v123, s[2:3]
	v_cndmask_b32_e64 v119, v123, v119, s[2:3]
	v_mov_b32_e32 v123, v122
	v_pk_mul_f32 v[160:161], v[82:83], v[104:105]
	s_nop 0
	v_permlane16_swap_b32_e32 v122, v123
	v_cndmask_b32_e64 v122, v122, v123, s[2:3]
	v_add_f32_e32 v119, v119, v122
	v_cndmask_b32_e64 v122, v118, v119, s[4:5]
	v_cndmask_b32_e64 v118, v119, v118, s[4:5]
	v_pk_mul_f32 v[162:163], v[82:83], v[108:109]
	v_pk_mul_f32 v[164:165], v[82:83], v[110:111]
	v_add_f32_dpp v118, v122, v118 row_ror:8 row_mask:0xf bank_mask:0xf bound_ctrl:1
	v_pk_mul_f32 v[122:123], v[82:83], v[96:97]
	v_pk_mul_f32 v[166:167], v[82:83], v[112:113]
	v_add_f32_dpp v118, v118, v118 quad_perm:[1,0,3,2] row_mask:0xf bank_mask:0xf bound_ctrl:1
	v_pk_fma_f32 v[122:123], v[80:81], v[86:87], v[122:123]
	v_pk_fma_f32 v[158:159], v[80:81], v[88:89], v[158:159]
	v_add_f32_dpp v118, v118, v118 quad_perm:[2,3,0,1] row_mask:0xf bank_mask:0xf bound_ctrl:1
	v_pk_fma_f32 v[160:161], v[80:81], v[90:91], v[160:161]
	v_pk_fma_f32 v[162:163], v[80:81], v[94:95], v[162:163]
	v_add_f32_dpp v153, v118, v118 row_half_mirror row_mask:0xf bank_mask:0xf bound_ctrl:1
	v_pk_mul_f32 v[118:119], v[82:83], v[92:93]
	v_pk_mul_f32 v[82:83], v[82:83], v[114:115]
	v_pk_fma_f32 v[118:119], v[80:81], v[84:85], v[118:119]
	v_pk_fma_f32 v[164:165], v[80:81], v[98:99], v[164:165]
	v_pk_fma_f32 v[166:167], v[80:81], v[102:103], v[166:167]
	v_pk_fma_f32 v[80:81], v[80:81], v[106:107], v[82:83]
	v_pk_add_f32 v[118:119], v[118:119], v[118:119] op_sel:[0,1] op_sel_hi:[1,0]
	v_pk_add_f32 v[162:163], v[162:163], v[162:163] op_sel:[0,1] op_sel_hi:[1,0]
	v_pk_add_f32 v[80:81], v[80:81], v[80:81] op_sel:[0,1] op_sel_hi:[1,0]
	v_pk_add_f32 v[122:123], v[122:123], v[122:123] op_sel:[0,1] op_sel_hi:[1,0]
	v_cndmask_b32_e32 v81, v162, v118, vcc
	v_mov_b32_e32 v83, v81
	v_pk_add_f32 v[164:165], v[164:165], v[164:165] op_sel:[0,1] op_sel_hi:[1,0]
	s_nop 0
	v_permlane32_swap_b32_e32 v81, v83
	v_cndmask_b32_e32 v82, v118, v162, vcc
	v_cndmask_b32_e32 v81, v83, v81, vcc
	v_add_f32_e32 v81, v82, v81
	v_cndmask_b32_e32 v82, v164, v122, vcc
	v_mov_b32_e32 v118, v82
	v_pk_add_f32 v[158:159], v[158:159], v[158:159] op_sel:[0,1] op_sel_hi:[1,0]
	s_nop 0
	v_permlane32_swap_b32_e32 v82, v118
	v_pk_add_f32 v[166:167], v[166:167], v[166:167] op_sel:[0,1] op_sel_hi:[1,0]
	v_cndmask_b32_e32 v83, v122, v164, vcc
	v_cndmask_b32_e32 v82, v118, v82, vcc
	v_add_f32_e32 v82, v83, v82
	v_cndmask_b32_e32 v83, v166, v158, vcc
	v_mov_b32_e32 v119, v83
	v_pk_add_f32 v[160:161], v[160:161], v[160:161] op_sel:[0,1] op_sel_hi:[1,0]
	s_nop 0
	v_permlane32_swap_b32_e32 v83, v119
	v_cndmask_b32_e32 v118, v158, v166, vcc
	v_cndmask_b32_e32 v83, v119, v83, vcc
	v_add_f32_e32 v83, v118, v83
	v_cndmask_b32_e32 v118, v80, v160, vcc
	v_mov_b32_e32 v119, v118
	v_cndmask_b32_e32 v80, v160, v80, vcc
	s_nop 0
	v_permlane32_swap_b32_e32 v118, v119
	v_cndmask_b32_e32 v118, v119, v118, vcc
	v_add_f32_e32 v80, v80, v118
	v_cndmask_b32_e64 v118, v81, v83, s[2:3]
	v_cndmask_b32_e64 v81, v83, v81, s[2:3]
	v_mov_b32_e32 v83, v118
	v_pk_mul_f32 v[122:123], v[78:79], v[104:105]
	v_permlane16_swap_b32_e32 v118, v83
	v_cndmask_b32_e64 v83, v118, v83, s[2:3]
	v_add_f32_e32 v81, v81, v83
	v_cndmask_b32_e64 v83, v82, v80, s[2:3]
	v_cndmask_b32_e64 v80, v80, v82, s[2:3]
	v_mov_b32_e32 v82, v83
	v_pk_mul_f32 v[118:119], v[78:79], v[100:101]
	s_nop 0
	v_permlane16_swap_b32_e32 v83, v82
	v_cndmask_b32_e64 v82, v83, v82, s[2:3]
	v_add_f32_e32 v80, v80, v82
	v_cndmask_b32_e64 v82, v81, v80, s[4:5]
	v_cndmask_b32_e64 v80, v80, v81, s[4:5]
	v_pk_mul_f32 v[158:159], v[78:79], v[108:109]
	v_pk_mul_f32 v[160:161], v[78:79], v[110:111]
	v_add_f32_dpp v80, v82, v80 row_ror:8 row_mask:0xf bank_mask:0xf bound_ctrl:1
	v_pk_mul_f32 v[82:83], v[78:79], v[96:97]
	v_pk_mul_f32 v[162:163], v[78:79], v[112:113]
	v_add_f32_dpp v80, v80, v80 quad_perm:[1,0,3,2] row_mask:0xf bank_mask:0xf bound_ctrl:1
	v_pk_fma_f32 v[82:83], v[76:77], v[86:87], v[82:83]
	v_pk_fma_f32 v[118:119], v[76:77], v[88:89], v[118:119]
	v_add_f32_dpp v80, v80, v80 quad_perm:[2,3,0,1] row_mask:0xf bank_mask:0xf bound_ctrl:1
	v_pk_fma_f32 v[122:123], v[76:77], v[90:91], v[122:123]
	v_pk_fma_f32 v[158:159], v[76:77], v[94:95], v[158:159]
	v_add_f32_dpp v155, v80, v80 row_half_mirror row_mask:0xf bank_mask:0xf bound_ctrl:1
	v_pk_mul_f32 v[80:81], v[78:79], v[92:93]
	v_pk_mul_f32 v[78:79], v[78:79], v[114:115]
	v_pk_fma_f32 v[80:81], v[76:77], v[84:85], v[80:81]
	v_pk_fma_f32 v[160:161], v[76:77], v[98:99], v[160:161]
	v_pk_fma_f32 v[162:163], v[76:77], v[102:103], v[162:163]
	v_pk_fma_f32 v[76:77], v[76:77], v[106:107], v[78:79]
	v_pk_add_f32 v[80:81], v[80:81], v[80:81] op_sel:[0,1] op_sel_hi:[1,0]
	v_pk_add_f32 v[158:159], v[158:159], v[158:159] op_sel:[0,1] op_sel_hi:[1,0]
	v_pk_add_f32 v[76:77], v[76:77], v[76:77] op_sel:[0,1] op_sel_hi:[1,0]
	v_pk_add_f32 v[82:83], v[82:83], v[82:83] op_sel:[0,1] op_sel_hi:[1,0]
	v_cndmask_b32_e32 v77, v158, v80, vcc
	v_mov_b32_e32 v79, v77
	v_pk_add_f32 v[160:161], v[160:161], v[160:161] op_sel:[0,1] op_sel_hi:[1,0]
	s_nop 0
	v_permlane32_swap_b32_e32 v77, v79
	v_cndmask_b32_e32 v78, v80, v158, vcc
	v_cndmask_b32_e32 v77, v79, v77, vcc
	v_add_f32_e32 v77, v78, v77
	v_cndmask_b32_e32 v78, v160, v82, vcc
	v_mov_b32_e32 v80, v78
	v_pk_add_f32 v[118:119], v[118:119], v[118:119] op_sel:[0,1] op_sel_hi:[1,0]
	s_nop 0
	v_permlane32_swap_b32_e32 v78, v80
	v_pk_add_f32 v[162:163], v[162:163], v[162:163] op_sel:[0,1] op_sel_hi:[1,0]
	v_cndmask_b32_e32 v79, v82, v160, vcc
	v_cndmask_b32_e32 v78, v80, v78, vcc
	v_add_f32_e32 v78, v79, v78
	v_cndmask_b32_e32 v79, v162, v118, vcc
	v_mov_b32_e32 v81, v79
	v_pk_add_f32 v[122:123], v[122:123], v[122:123] op_sel:[0,1] op_sel_hi:[1,0]
	s_nop 0
	v_permlane32_swap_b32_e32 v79, v81
	v_cndmask_b32_e32 v80, v118, v162, vcc
	v_cndmask_b32_e32 v79, v81, v79, vcc
	v_add_f32_e32 v79, v80, v79
	v_cndmask_b32_e32 v80, v76, v122, vcc
	v_mov_b32_e32 v81, v80
	v_cndmask_b32_e32 v76, v122, v76, vcc
	s_nop 0
	v_permlane32_swap_b32_e32 v80, v81
	v_cndmask_b32_e32 v80, v81, v80, vcc
	v_add_f32_e32 v76, v76, v80
	v_cndmask_b32_e64 v80, v77, v79, s[2:3]
	v_cndmask_b32_e64 v77, v79, v77, s[2:3]
	v_mov_b32_e32 v79, v80
	v_pk_mul_f32 v[82:83], v[74:75], v[104:105]
	v_permlane16_swap_b32_e32 v80, v79
	v_cndmask_b32_e64 v79, v80, v79, s[2:3]
	v_add_f32_e32 v77, v77, v79
	v_cndmask_b32_e64 v79, v78, v76, s[2:3]
	v_cndmask_b32_e64 v76, v76, v78, s[2:3]
	v_mov_b32_e32 v78, v79
	v_pk_mul_f32 v[80:81], v[74:75], v[100:101]
	s_nop 0
	v_permlane16_swap_b32_e32 v79, v78
	v_cndmask_b32_e64 v78, v79, v78, s[2:3]
	v_add_f32_e32 v76, v76, v78
	v_cndmask_b32_e64 v78, v77, v76, s[4:5]
	v_cndmask_b32_e64 v76, v76, v77, s[4:5]
	v_pk_mul_f32 v[118:119], v[74:75], v[108:109]
	v_pk_mul_f32 v[122:123], v[74:75], v[110:111]
	v_add_f32_dpp v76, v78, v76 row_ror:8 row_mask:0xf bank_mask:0xf bound_ctrl:1
	v_pk_mul_f32 v[78:79], v[74:75], v[96:97]
	v_pk_mul_f32 v[160:161], v[74:75], v[112:113]
	v_add_f32_dpp v76, v76, v76 quad_perm:[1,0,3,2] row_mask:0xf bank_mask:0xf bound_ctrl:1
	v_pk_fma_f32 v[78:79], v[72:73], v[86:87], v[78:79]
	v_pk_fma_f32 v[80:81], v[72:73], v[88:89], v[80:81]
	v_add_f32_dpp v76, v76, v76 quad_perm:[2,3,0,1] row_mask:0xf bank_mask:0xf bound_ctrl:1
	v_pk_fma_f32 v[82:83], v[72:73], v[90:91], v[82:83]
	v_pk_fma_f32 v[118:119], v[72:73], v[94:95], v[118:119]
	v_add_f32_dpp v158, v76, v76 row_half_mirror row_mask:0xf bank_mask:0xf bound_ctrl:1
	v_pk_mul_f32 v[76:77], v[74:75], v[92:93]
	v_pk_mul_f32 v[74:75], v[74:75], v[114:115]
	v_pk_fma_f32 v[76:77], v[72:73], v[84:85], v[76:77]
	v_pk_fma_f32 v[122:123], v[72:73], v[98:99], v[122:123]
	v_pk_fma_f32 v[160:161], v[72:73], v[102:103], v[160:161]
	v_pk_fma_f32 v[72:73], v[72:73], v[106:107], v[74:75]
	v_pk_add_f32 v[76:77], v[76:77], v[76:77] op_sel:[0,1] op_sel_hi:[1,0]
	v_pk_add_f32 v[118:119], v[118:119], v[118:119] op_sel:[0,1] op_sel_hi:[1,0]
	v_pk_add_f32 v[72:73], v[72:73], v[72:73] op_sel:[0,1] op_sel_hi:[1,0]
	v_pk_add_f32 v[78:79], v[78:79], v[78:79] op_sel:[0,1] op_sel_hi:[1,0]
	v_cndmask_b32_e32 v73, v118, v76, vcc
	v_mov_b32_e32 v75, v73
	v_pk_add_f32 v[122:123], v[122:123], v[122:123] op_sel:[0,1] op_sel_hi:[1,0]
	s_nop 0
	v_permlane32_swap_b32_e32 v73, v75
	v_cndmask_b32_e32 v74, v76, v118, vcc
	v_cndmask_b32_e32 v73, v75, v73, vcc
	v_add_f32_e32 v73, v74, v73
	v_cndmask_b32_e32 v74, v122, v78, vcc
	v_mov_b32_e32 v76, v74
	v_pk_add_f32 v[80:81], v[80:81], v[80:81] op_sel:[0,1] op_sel_hi:[1,0]
	s_nop 0
	v_permlane32_swap_b32_e32 v74, v76
	v_pk_add_f32 v[160:161], v[160:161], v[160:161] op_sel:[0,1] op_sel_hi:[1,0]
	v_cndmask_b32_e32 v75, v78, v122, vcc
	v_cndmask_b32_e32 v74, v76, v74, vcc
	v_add_f32_e32 v161, v75, v74
	v_cndmask_b32_e32 v74, v160, v80, vcc
	v_mov_b32_e32 v76, v74
	v_pk_add_f32 v[82:83], v[82:83], v[82:83] op_sel:[0,1] op_sel_hi:[1,0]
	s_nop 0
	v_permlane32_swap_b32_e32 v74, v76
	v_cndmask_b32_e32 v75, v80, v160, vcc
	v_cndmask_b32_e32 v74, v76, v74, vcc
	v_add_f32_e32 v74, v75, v74
	v_cndmask_b32_e32 v75, v72, v82, vcc
	v_mov_b32_e32 v76, v75
	v_cndmask_b32_e32 v72, v82, v72, vcc
	s_nop 0
	v_permlane32_swap_b32_e32 v75, v76
	v_cndmask_b32_e32 v75, v76, v75, vcc
	v_add_f32_e32 v160, v72, v75
	v_cndmask_b32_e64 v162, v73, v74, s[2:3]
	v_cndmask_b32_e64 v163, v74, v73, s[2:3]
	v_pk_mul_f32 v[72:73], v[70:71], v[92:93]
	v_pk_mul_f32 v[74:75], v[70:71], v[96:97]
	v_pk_mul_f32 v[76:77], v[70:71], v[100:101]
	v_pk_mul_f32 v[78:79], v[70:71], v[104:105]
	v_pk_mul_f32 v[80:81], v[70:71], v[108:109]
	v_pk_mul_f32 v[82:83], v[70:71], v[110:111]
	v_pk_mul_f32 v[118:119], v[70:71], v[112:113]
	v_pk_mul_f32 v[70:71], v[70:71], v[114:115]
	v_pk_fma_f32 v[72:73], v[68:69], v[84:85], v[72:73]
	v_pk_fma_f32 v[74:75], v[68:69], v[86:87], v[74:75]
	v_pk_fma_f32 v[76:77], v[68:69], v[88:89], v[76:77]
	v_pk_fma_f32 v[78:79], v[68:69], v[90:91], v[78:79]
	v_pk_fma_f32 v[80:81], v[68:69], v[94:95], v[80:81]
	v_pk_fma_f32 v[82:83], v[68:69], v[98:99], v[82:83]
	v_pk_fma_f32 v[118:119], v[68:69], v[102:103], v[118:119]
	v_pk_fma_f32 v[68:69], v[68:69], v[106:107], v[70:71]
	v_pk_add_f32 v[72:73], v[72:73], v[72:73] op_sel:[0,1] op_sel_hi:[1,0]
	v_pk_add_f32 v[80:81], v[80:81], v[80:81] op_sel:[0,1] op_sel_hi:[1,0]
	v_pk_add_f32 v[68:69], v[68:69], v[68:69] op_sel:[0,1] op_sel_hi:[1,0]
	v_cndmask_b32_e64 v165, v161, v160, s[2:3]
	v_cndmask_b32_e32 v69, v80, v72, vcc
	v_mov_b32_e32 v164, v162
	v_mov_b32_e32 v166, v165
	v_mov_b32_e32 v71, v69
	v_pk_add_f32 v[74:75], v[74:75], v[74:75] op_sel:[0,1] op_sel_hi:[1,0]
	s_nop 0
	v_permlane32_swap_b32_e32 v69, v71
	v_pk_add_f32 v[82:83], v[82:83], v[82:83] op_sel:[0,1] op_sel_hi:[1,0]
	v_cndmask_b32_e32 v70, v72, v80, vcc
	v_cndmask_b32_e32 v69, v71, v69, vcc
	v_add_f32_e32 v83, v70, v69
	v_cndmask_b32_e32 v69, v82, v74, vcc
	v_mov_b32_e32 v71, v69
	v_pk_add_f32 v[76:77], v[76:77], v[76:77] op_sel:[0,1] op_sel_hi:[1,0]
	s_nop 0
	v_permlane32_swap_b32_e32 v69, v71
	v_pk_add_f32 v[118:119], v[118:119], v[118:119] op_sel:[0,1] op_sel_hi:[1,0]
	v_cndmask_b32_e32 v70, v74, v82, vcc
	v_cndmask_b32_e32 v69, v71, v69, vcc
	v_add_f32_e32 v82, v70, v69
	v_cndmask_b32_e32 v69, v118, v76, vcc
	v_mov_b32_e32 v71, v69
	v_pk_add_f32 v[78:79], v[78:79], v[78:79] op_sel:[0,1] op_sel_hi:[1,0]
	s_nop 0
	v_permlane32_swap_b32_e32 v69, v71
	v_cndmask_b32_e32 v70, v76, v118, vcc
	v_cndmask_b32_e32 v69, v71, v69, vcc
	v_add_f32_e32 v167, v70, v69
	v_cndmask_b32_e32 v69, v68, v78, vcc
	v_mov_b32_e32 v70, v69
	v_cndmask_b32_e32 v68, v78, v68, vcc
	s_nop 0
	v_permlane32_swap_b32_e32 v69, v70
	v_cndmask_b32_e32 v69, v70, v69, vcc
	v_add_f32_e32 v168, v68, v69
	s_waitcnt vmcnt(15)
	v_pk_mul_f32 v[68:69], v[66:67], v[92:93]
	v_pk_mul_f32 v[70:71], v[66:67], v[96:97]
	v_pk_mul_f32 v[72:73], v[66:67], v[100:101]
	v_pk_mul_f32 v[74:75], v[66:67], v[104:105]
	v_pk_mul_f32 v[76:77], v[66:67], v[108:109]
	v_pk_mul_f32 v[78:79], v[66:67], v[110:111]
	v_pk_mul_f32 v[80:81], v[66:67], v[112:113]
	v_pk_mul_f32 v[66:67], v[66:67], v[114:115]
	v_pk_fma_f32 v[68:69], v[64:65], v[84:85], v[68:69]
	v_pk_fma_f32 v[70:71], v[64:65], v[86:87], v[70:71]
	v_pk_fma_f32 v[72:73], v[64:65], v[88:89], v[72:73]
	v_pk_fma_f32 v[74:75], v[64:65], v[90:91], v[74:75]
	v_pk_fma_f32 v[76:77], v[64:65], v[94:95], v[76:77]
	v_pk_fma_f32 v[78:79], v[64:65], v[98:99], v[78:79]
	v_pk_fma_f32 v[80:81], v[64:65], v[102:103], v[80:81]
	v_pk_fma_f32 v[64:65], v[64:65], v[106:107], v[66:67]
	v_pk_add_f32 v[68:69], v[68:69], v[68:69] op_sel:[0,1] op_sel_hi:[1,0]
	v_pk_add_f32 v[76:77], v[76:77], v[76:77] op_sel:[0,1] op_sel_hi:[1,0]
	v_pk_add_f32 v[64:65], v[64:65], v[64:65] op_sel:[0,1] op_sel_hi:[1,0]
	v_cndmask_b32_e64 v169, v83, v167, s[2:3]
	v_cndmask_b32_e64 v171, v82, v168, s[2:3]
	v_cndmask_b32_e32 v65, v76, v68, vcc
	v_mov_b32_e32 v170, v169
	v_mov_b32_e32 v172, v171
	v_mov_b32_e32 v67, v65
	v_pk_add_f32 v[70:71], v[70:71], v[70:71] op_sel:[0,1] op_sel_hi:[1,0]
	s_nop 0
	v_permlane32_swap_b32_e32 v65, v67
	v_pk_add_f32 v[78:79], v[78:79], v[78:79] op_sel:[0,1] op_sel_hi:[1,0]
	v_cndmask_b32_e32 v66, v68, v76, vcc
	v_cndmask_b32_e32 v65, v67, v65, vcc
	v_add_f32_e32 v68, v66, v65
	v_cndmask_b32_e32 v65, v78, v70, vcc
	v_mov_b32_e32 v67, v65
	v_pk_add_f32 v[72:73], v[72:73], v[72:73] op_sel:[0,1] op_sel_hi:[1,0]
	s_nop 0
	v_permlane32_swap_b32_e32 v65, v67
	v_pk_add_f32 v[80:81], v[80:81], v[80:81] op_sel:[0,1] op_sel_hi:[1,0]
	v_cndmask_b32_e32 v66, v70, v78, vcc
	v_cndmask_b32_e32 v65, v67, v65, vcc
	v_add_f32_e32 v69, v66, v65
	v_cndmask_b32_e32 v65, v80, v72, vcc
	v_mov_b32_e32 v67, v65
	v_pk_add_f32 v[74:75], v[74:75], v[74:75] op_sel:[0,1] op_sel_hi:[1,0]
	s_nop 0
	v_permlane32_swap_b32_e32 v65, v67
	v_cndmask_b32_e32 v66, v72, v80, vcc
	v_cndmask_b32_e32 v65, v67, v65, vcc
	v_add_f32_e32 v70, v66, v65
	v_cndmask_b32_e32 v65, v64, v74, vcc
	v_mov_b32_e32 v66, v65
	v_cndmask_b32_e32 v64, v74, v64, vcc
	s_nop 0
	v_permlane32_swap_b32_e32 v65, v66
	v_cndmask_b32_e32 v65, v66, v65, vcc
	v_add_f32_e32 v71, v64, v65
	v_cndmask_b32_e64 v72, v68, v70, s[2:3]
	v_cndmask_b32_e64 v74, v69, v71, s[2:3]
	v_add_co_u32_e64 v118, s[6:7], s41, v116
	v_mov_b32_e32 v73, v72
	v_mov_b32_e32 v75, v74
	v_addc_co_u32_e64 v119, s[6:7], 0, v117, s[6:7]
	s_waitcnt vmcnt(0)
	v_mov_b32_e32 v64, v222
	v_mov_b32_e32 v65, v223
	v_mov_b32_e32 v66, v224
	v_mov_b32_e32 v67, v225
	s_nop 0
	v_mov_b32_e32 v120, v226
	v_mov_b32_e32 v121, v227
	v_mov_b32_e32 v122, v228
	v_mov_b32_e32 v123, v229
	v_permlane16_swap_b32_e32 v162, v164
	v_permlane16_swap_b32_e32 v165, v166
	v_cndmask_b32_e64 v76, v162, v164, s[2:3]
	v_cndmask_b32_e64 v77, v160, v161, s[2:3]
	v_cndmask_b32_e64 v78, v165, v166, s[2:3]
	v_add_f32_e32 v76, v163, v76
	v_add_f32_e32 v77, v77, v78
	v_permlane16_swap_b32_e32 v72, v73
	v_cndmask_b32_e64 v78, v76, v77, s[4:5]
	v_cndmask_b32_e64 v76, v77, v76, s[4:5]
	v_cndmask_b32_e64 v68, v70, v68, s[2:3]
	v_cndmask_b32_e64 v70, v72, v73, s[2:3]
	v_permlane16_swap_b32_e32 v74, v75
	v_add_f32_dpp v76, v78, v76 row_ror:8 row_mask:0xf bank_mask:0xf bound_ctrl:1
	v_add_f32_e32 v68, v68, v70
	v_cndmask_b32_e64 v69, v71, v69, s[2:3]
	v_cndmask_b32_e64 v70, v74, v75, s[2:3]
	v_add_f32_dpp v76, v76, v76 quad_perm:[1,0,3,2] row_mask:0xf bank_mask:0xf bound_ctrl:1
	v_add_f32_e32 v69, v69, v70
	v_permlane16_swap_b32_e32 v169, v170
	v_add_f32_dpp v76, v76, v76 quad_perm:[2,3,0,1] row_mask:0xf bank_mask:0xf bound_ctrl:1
	v_cndmask_b32_e64 v70, v68, v69, s[4:5]
	v_cndmask_b32_e64 v68, v69, v68, s[4:5]
	v_add_f32_dpp v160, v76, v76 row_half_mirror row_mask:0xf bank_mask:0xf bound_ctrl:1
	v_cndmask_b32_e64 v76, v167, v83, s[2:3]
	v_cndmask_b32_e64 v77, v169, v170, s[2:3]
	v_permlane16_swap_b32_e32 v171, v172
	v_add_f32_dpp v68, v70, v68 row_ror:8 row_mask:0xf bank_mask:0xf bound_ctrl:1
	v_add_f32_e32 v76, v76, v77
	v_cndmask_b32_e64 v77, v168, v82, s[2:3]
	v_cndmask_b32_e64 v78, v171, v172, s[2:3]
	v_add_f32_dpp v68, v68, v68 quad_perm:[1,0,3,2] row_mask:0xf bank_mask:0xf bound_ctrl:1
	v_add_f32_e32 v77, v77, v78
	v_cndmask_b32_e64 v78, v76, v77, s[4:5]
	v_add_f32_dpp v68, v68, v68 quad_perm:[2,3,0,1] row_mask:0xf bank_mask:0xf bound_ctrl:1
	v_cndmask_b32_e64 v76, v77, v76, s[4:5]
	v_mul_f32_e32 v147, 0x3d800000, v145
	v_add_f32_dpp v162, v68, v68 row_half_mirror row_mask:0xf bank_mask:0xf bound_ctrl:1
	v_add_co_u32_e64 v68, s[6:7], s46, v116
	v_add_f32_dpp v76, v78, v76 row_ror:8 row_mask:0xf bank_mask:0xf bound_ctrl:1
	s_nop 0
	v_addc_co_u32_e64 v69, s[6:7], 0, v117, s[6:7]
	v_add_f32_dpp v76, v76, v76 quad_perm:[1,0,3,2] row_mask:0xf bank_mask:0xf bound_ctrl:1
	v_add_co_u32_e64 v72, s[6:7], s0, v116
	s_nop 0
	v_add_f32_dpp v76, v76, v76 quad_perm:[2,3,0,1] row_mask:0xf bank_mask:0xf bound_ctrl:1
	v_addc_co_u32_e64 v73, s[6:7], 0, v117, s[6:7]
	s_nop 0
	v_add_f32_dpp v161, v76, v76 row_half_mirror row_mask:0xf bank_mask:0xf bound_ctrl:1
	v_add_co_u32_e64 v76, s[6:7], s40, v116
	s_mov_b32 s0, 0x13000
	s_nop 0
	v_addc_co_u32_e64 v77, s[6:7], 0, v117, s[6:7]
	v_add_co_u32_e64 v80, s[6:7], s0, v116
	s_mov_b32 s0, 0x11000
	s_nop 0
	v_addc_co_u32_e64 v81, s[6:7], 0, v117, s[6:7]
	v_add_co_u32_e64 v78, s[6:7], s47, v116
	v_mov_b32_e32 v68, v230
	v_mov_b32_e32 v69, v231
	v_mov_b32_e32 v70, v232
	v_mov_b32_e32 v71, v233
	s_nop 0
	v_mov_b32_e32 v72, v234
	v_mov_b32_e32 v73, v235
	v_mov_b32_e32 v74, v236
	v_mov_b32_e32 v75, v237
	v_addc_co_u32_e64 v79, s[6:7], 0, v117, s[6:7]
	v_add_co_u32_e64 v82, s[6:7], s0, v116
	s_mov_b32 s0, 0x19000
	s_nop 0
	v_addc_co_u32_e64 v83, s[6:7], 0, v117, s[6:7]
	v_mov_b32_e32 v166, v238
	v_mov_b32_e32 v167, v239
	v_mov_b32_e32 v168, v240
	v_mov_b32_e32 v169, v241
	v_mov_b32_e32 v170, v242
	v_mov_b32_e32 v171, v243
	v_mov_b32_e32 v172, v244
	v_mov_b32_e32 v173, v245
	s_nop 0
	v_mov_b32_e32 v76, v250
	v_mov_b32_e32 v77, v251
	v_mov_b32_e32 v78, v252
	v_mov_b32_e32 v79, v253
	s_nop 0
	global_load_dwordx4 v[80:83], v[80:81], off nt
	v_add_co_u32_e64 v254, s[100:101], s50, v116
	s_nop 1
	v_addc_co_u32_e64 v255, s[100:101], 0, v117, s[100:101]
	global_load_dwordx4 v[222:225], v[254:255], off offset:-4096 nt
	v_add_co_u32_e64 v254, s[100:101], s41, v116
	s_nop 1
	v_addc_co_u32_e64 v255, s[100:101], 0, v117, s[100:101]
	global_load_dwordx4 v[226:229], v[254:255], off nt
	v_add_co_u32_e64 v254, s[100:101], s48, v116
	s_nop 1
	v_addc_co_u32_e64 v255, s[100:101], 0, v117, s[100:101]
	global_load_dwordx4 v[230:233], v[254:255], off nt
	v_add_co_u32_e64 v254, s[100:101], s49, v116
	s_nop 1
	v_addc_co_u32_e64 v255, s[100:101], 0, v117, s[100:101]
	global_load_dwordx4 v[234:237], v[254:255], off nt
	global_load_dwordx4 v[238:241], v[254:255], off offset:-4096 nt
	v_add_co_u32_e64 v254, s[100:101], s42, v116
	s_nop 1
	v_addc_co_u32_e64 v255, s[100:101], 0, v117, s[100:101]
	global_load_dwordx4 v[242:245], v[254:255], off nt
	global_load_dwordx4 v[250:253], v[254:255], off offset:-4096 nt
	v_mul_f32_e32 v148, 0x3d800000, v146
	v_max3_f32 v134, v134, v142, v144
	v_pk_mul_f32 v[174:175], v[122:123], v[92:93]
	v_pk_mul_f32 v[176:177], v[122:123], v[96:97]
	v_pk_mul_f32 v[178:179], v[122:123], v[100:101]
	v_pk_mul_f32 v[180:181], v[122:123], v[104:105]
	v_pk_mul_f32 v[182:183], v[122:123], v[108:109]
	v_pk_mul_f32 v[184:185], v[122:123], v[110:111]
	v_pk_mul_f32 v[186:187], v[122:123], v[112:113]
	v_pk_mul_f32 v[122:123], v[122:123], v[114:115]
	v_pk_fma_f32 v[174:175], v[120:121], v[84:85], v[174:175]
	v_pk_fma_f32 v[176:177], v[120:121], v[86:87], v[176:177]
	v_pk_fma_f32 v[178:179], v[120:121], v[88:89], v[178:179]
	v_pk_fma_f32 v[180:181], v[120:121], v[90:91], v[180:181]
	v_pk_fma_f32 v[182:183], v[120:121], v[94:95], v[182:183]
	v_pk_fma_f32 v[184:185], v[120:121], v[98:99], v[184:185]
	v_pk_fma_f32 v[186:187], v[120:121], v[102:103], v[186:187]
	v_pk_fma_f32 v[120:121], v[120:121], v[106:107], v[122:123]
	v_pk_add_f32 v[174:175], v[174:175], v[174:175] op_sel:[0,1] op_sel_hi:[1,0]
	v_pk_add_f32 v[182:183], v[182:183], v[182:183] op_sel:[0,1] op_sel_hi:[1,0]
	v_pk_add_f32 v[120:121], v[120:121], v[120:121] op_sel:[0,1] op_sel_hi:[1,0]
	v_pk_add_f32 v[176:177], v[176:177], v[176:177] op_sel:[0,1] op_sel_hi:[1,0]
	v_cndmask_b32_e32 v121, v182, v174, vcc
	v_mov_b32_e32 v123, v121
	v_pk_add_f32 v[184:185], v[184:185], v[184:185] op_sel:[0,1] op_sel_hi:[1,0]
	s_nop 0
	v_permlane32_swap_b32_e32 v121, v123
	v_cndmask_b32_e32 v122, v174, v182, vcc
	v_cndmask_b32_e32 v121, v123, v121, vcc
	v_add_f32_e32 v121, v121, v122
	v_cndmask_b32_e32 v122, v184, v176, vcc
	v_mov_b32_e32 v174, v122
	v_pk_add_f32 v[178:179], v[178:179], v[178:179] op_sel:[0,1] op_sel_hi:[1,0]
	s_nop 0
	v_permlane32_swap_b32_e32 v122, v174
	v_pk_add_f32 v[186:187], v[186:187], v[186:187] op_sel:[0,1] op_sel_hi:[1,0]
	v_cndmask_b32_e32 v123, v176, v184, vcc
	v_cndmask_b32_e32 v122, v174, v122, vcc
	v_add_f32_e32 v122, v122, v123
	v_cndmask_b32_e32 v123, v186, v178, vcc
	v_mov_b32_e32 v175, v123
	v_pk_add_f32 v[180:181], v[180:181], v[180:181] op_sel:[0,1] op_sel_hi:[1,0]
	s_nop 0
	v_permlane32_swap_b32_e32 v123, v175
	v_cndmask_b32_e32 v174, v178, v186, vcc
	v_cndmask_b32_e32 v123, v175, v123, vcc
	v_add_f32_e32 v123, v174, v123
	v_cndmask_b32_e32 v174, v120, v180, vcc
	v_mov_b32_e32 v175, v174
	v_cndmask_b32_e32 v120, v180, v120, vcc
	s_nop 0
	v_permlane32_swap_b32_e32 v174, v175
	v_cndmask_b32_e32 v174, v175, v174, vcc
	v_add_f32_e32 v120, v120, v174
	v_cndmask_b32_e64 v174, v121, v123, s[2:3]
	v_cndmask_b32_e64 v121, v123, v121, s[2:3]
	v_mov_b32_e32 v123, v174
	v_mul_f32_e32 v150, 0x3d800000, v149
	s_nop 0
	v_permlane16_swap_b32_e32 v174, v123
	v_cndmask_b32_e64 v123, v174, v123, s[2:3]
	v_add_f32_e32 v121, v121, v123
	v_cndmask_b32_e64 v123, v122, v120, s[2:3]
	v_cndmask_b32_e64 v120, v120, v122, s[2:3]
	v_mov_b32_e32 v122, v123
	v_mul_f32_e32 v152, 0x3d800000, v151
	s_nop 0
	v_permlane16_swap_b32_e32 v123, v122
	v_cndmask_b32_e64 v122, v123, v122, s[2:3]
	v_add_f32_e32 v120, v120, v122
	v_cndmask_b32_e64 v122, v121, v120, s[4:5]
	v_cndmask_b32_e64 v120, v120, v121, s[4:5]
	v_pk_mul_f32 v[180:181], v[172:173], v[108:109]
	v_pk_mul_f32 v[174:175], v[172:173], v[96:97]
	v_add_f32_dpp v120, v122, v120 row_ror:8 row_mask:0xf bank_mask:0xf bound_ctrl:1
	v_pk_mul_f32 v[122:123], v[172:173], v[92:93]
	v_pk_mul_f32 v[176:177], v[172:173], v[100:101]
	v_pk_fma_f32 v[122:123], v[170:171], v[84:85], v[122:123]
	v_pk_mul_f32 v[178:179], v[172:173], v[104:105]
	v_pk_fma_f32 v[180:181], v[170:171], v[94:95], v[180:181]
	v_pk_mul_f32 v[182:183], v[172:173], v[110:111]
	v_pk_mul_f32 v[184:185], v[172:173], v[112:113]
	v_pk_mul_f32 v[172:173], v[172:173], v[114:115]
	v_pk_add_f32 v[122:123], v[122:123], v[122:123] op_sel:[0,1] op_sel_hi:[1,0]
	v_pk_fma_f32 v[174:175], v[170:171], v[86:87], v[174:175]
	v_pk_fma_f32 v[176:177], v[170:171], v[88:89], v[176:177]
	v_pk_fma_f32 v[178:179], v[170:171], v[90:91], v[178:179]
	v_pk_add_f32 v[180:181], v[180:181], v[180:181] op_sel:[0,1] op_sel_hi:[1,0]
	v_pk_fma_f32 v[182:183], v[170:171], v[98:99], v[182:183]
	v_pk_fma_f32 v[184:185], v[170:171], v[102:103], v[184:185]
	v_pk_fma_f32 v[170:171], v[170:171], v[106:107], v[172:173]
	v_cndmask_b32_e32 v123, v180, v122, vcc
	v_pk_add_f32 v[170:171], v[170:171], v[170:171] op_sel:[0,1] op_sel_hi:[1,0]
	v_pk_add_f32 v[174:175], v[174:175], v[174:175] op_sel:[0,1] op_sel_hi:[1,0]
	v_mov_b32_e32 v171, v123
	v_pk_add_f32 v[182:183], v[182:183], v[182:183] op_sel:[0,1] op_sel_hi:[1,0]
	s_nop 0
	v_permlane32_swap_b32_e32 v123, v171
	v_cndmask_b32_e32 v122, v122, v180, vcc
	v_cndmask_b32_e32 v123, v171, v123, vcc
	v_add_f32_e32 v122, v122, v123
	v_cndmask_b32_e32 v123, v182, v174, vcc
	v_mov_b32_e32 v172, v123
	v_pk_add_f32 v[176:177], v[176:177], v[176:177] op_sel:[0,1] op_sel_hi:[1,0]
	s_nop 0
	v_permlane32_swap_b32_e32 v123, v172
	v_pk_add_f32 v[184:185], v[184:185], v[184:185] op_sel:[0,1] op_sel_hi:[1,0]
	v_cndmask_b32_e32 v171, v174, v182, vcc
	v_cndmask_b32_e32 v123, v172, v123, vcc
	v_add_f32_e32 v123, v171, v123
	v_cndmask_b32_e32 v171, v184, v176, vcc
	v_mov_b32_e32 v173, v171
	v_pk_add_f32 v[178:179], v[178:179], v[178:179] op_sel:[0,1] op_sel_hi:[1,0]
	s_nop 0
	v_permlane32_swap_b32_e32 v171, v173
	v_cndmask_b32_e32 v172, v176, v184, vcc
	v_cndmask_b32_e32 v171, v173, v171, vcc
	v_add_f32_e32 v171, v172, v171
	v_cndmask_b32_e32 v172, v170, v178, vcc
	v_mov_b32_e32 v173, v172
	v_cndmask_b32_e32 v170, v178, v170, vcc
	s_nop 0
	v_permlane32_swap_b32_e32 v172, v173
	v_cndmask_b32_e32 v172, v173, v172, vcc
	v_add_f32_e32 v170, v170, v172
	v_cndmask_b32_e64 v172, v122, v171, s[2:3]
	v_cndmask_b32_e64 v122, v171, v122, s[2:3]
	v_mov_b32_e32 v171, v172
	v_pk_mul_f32 v[174:175], v[168:169], v[100:101]
	s_nop 0
	v_permlane16_swap_b32_e32 v172, v171
	v_cndmask_b32_e64 v171, v172, v171, s[2:3]
	v_add_f32_e32 v122, v122, v171
	v_cndmask_b32_e64 v171, v123, v170, s[2:3]
	v_cndmask_b32_e64 v123, v170, v123, s[2:3]
	v_mov_b32_e32 v170, v171
	v_pk_mul_f32 v[172:173], v[168:169], v[96:97]
	s_nop 0
	v_permlane16_swap_b32_e32 v171, v170
	v_cndmask_b32_e64 v170, v171, v170, s[2:3]
	v_add_f32_e32 v123, v123, v170
	v_cndmask_b32_e64 v170, v122, v123, s[4:5]
	v_cndmask_b32_e64 v122, v123, v122, s[4:5]
	v_pk_mul_f32 v[176:177], v[168:169], v[104:105]
	v_pk_mul_f32 v[178:179], v[168:169], v[108:109]
	v_add_f32_dpp v122, v170, v122 row_ror:8 row_mask:0xf bank_mask:0xf bound_ctrl:1
	v_pk_mul_f32 v[170:171], v[168:169], v[92:93]
	v_pk_mul_f32 v[180:181], v[168:169], v[110:111]
	v_pk_mul_f32 v[182:183], v[168:169], v[112:113]
	v_pk_mul_f32 v[168:169], v[168:169], v[114:115]
	v_pk_fma_f32 v[170:171], v[166:167], v[84:85], v[170:171]
	v_pk_fma_f32 v[172:173], v[166:167], v[86:87], v[172:173]
	v_pk_fma_f32 v[174:175], v[166:167], v[88:89], v[174:175]
	v_pk_fma_f32 v[176:177], v[166:167], v[90:91], v[176:177]
	v_pk_fma_f32 v[178:179], v[166:167], v[94:95], v[178:179]
	v_pk_fma_f32 v[180:181], v[166:167], v[98:99], v[180:181]
	v_pk_fma_f32 v[182:183], v[166:167], v[102:103], v[182:183]
	v_pk_fma_f32 v[166:167], v[166:167], v[106:107], v[168:169]
	v_pk_add_f32 v[170:171], v[170:171], v[170:171] op_sel:[0,1] op_sel_hi:[1,0]
	v_pk_add_f32 v[178:179], v[178:179], v[178:179] op_sel:[0,1] op_sel_hi:[1,0]
	v_pk_add_f32 v[166:167], v[166:167], v[166:167] op_sel:[0,1] op_sel_hi:[1,0]
	v_pk_add_f32 v[172:173], v[172:173], v[172:173] op_sel:[0,1] op_sel_hi:[1,0]
	v_cndmask_b32_e32 v167, v178, v170, vcc
	v_mov_b32_e32 v169, v167
	v_pk_add_f32 v[180:181], v[180:181], v[180:181] op_sel:[0,1] op_sel_hi:[1,0]
	s_nop 0
	v_permlane32_swap_b32_e32 v167, v169
	v_cndmask_b32_e32 v168, v170, v178, vcc
	v_cndmask_b32_e32 v167, v169, v167, vcc
	v_add_f32_e32 v167, v168, v167
	v_cndmask_b32_e32 v168, v180, v172, vcc
	v_mov_b32_e32 v170, v168
	v_pk_add_f32 v[174:175], v[174:175], v[174:175] op_sel:[0,1] op_sel_hi:[1,0]
	s_nop 0
	v_permlane32_swap_b32_e32 v168, v170
	v_pk_add_f32 v[182:183], v[182:183], v[182:183] op_sel:[0,1] op_sel_hi:[1,0]
	v_cndmask_b32_e32 v169, v172, v180, vcc
	v_cndmask_b32_e32 v168, v170, v168, vcc
	v_add_f32_e32 v168, v169, v168
	v_cndmask_b32_e32 v169, v182, v174, vcc
	v_mov_b32_e32 v171, v169
	v_pk_add_f32 v[176:177], v[176:177], v[176:177] op_sel:[0,1] op_sel_hi:[1,0]
	s_nop 0
	v_permlane32_swap_b32_e32 v169, v171
	v_cndmask_b32_e32 v170, v174, v182, vcc
	v_cndmask_b32_e32 v169, v171, v169, vcc
	v_add_f32_e32 v169, v170, v169
	v_cndmask_b32_e32 v170, v166, v176, vcc
	v_mov_b32_e32 v171, v170
	v_cndmask_b32_e32 v166, v176, v166, vcc
	s_nop 0
	v_permlane32_swap_b32_e32 v170, v171
	v_cndmask_b32_e32 v170, v171, v170, vcc
	v_add_f32_e32 v166, v166, v170
	v_cndmask_b32_e64 v170, v167, v169, s[2:3]
	v_cndmask_b32_e64 v167, v169, v167, s[2:3]
	v_mov_b32_e32 v169, v170
	s_waitcnt vmcnt(7)
	v_pk_mul_f32 v[174:175], v[82:83], v[100:101]
	v_permlane16_swap_b32_e32 v170, v169
	v_cndmask_b32_e64 v169, v170, v169, s[2:3]
	v_add_f32_e32 v167, v167, v169
	v_cndmask_b32_e64 v169, v168, v166, s[2:3]
	v_cndmask_b32_e64 v166, v166, v168, s[2:3]
	v_mov_b32_e32 v168, v169
	v_pk_mul_f32 v[176:177], v[82:83], v[104:105]
	s_nop 0
	v_permlane16_swap_b32_e32 v169, v168
	v_cndmask_b32_e64 v168, v169, v168, s[2:3]
	v_add_f32_e32 v166, v166, v168
	v_cndmask_b32_e64 v168, v167, v166, s[4:5]
	v_cndmask_b32_e64 v166, v166, v167, s[4:5]
	v_pk_mul_f32 v[178:179], v[82:83], v[108:109]
	v_pk_mul_f32 v[180:181], v[82:83], v[110:111]
	v_add_f32_dpp v166, v168, v166 row_ror:8 row_mask:0xf bank_mask:0xf bound_ctrl:1
	v_pk_mul_f32 v[168:169], v[82:83], v[96:97]
	v_pk_mul_f32 v[182:183], v[82:83], v[112:113]
	v_add_f32_dpp v166, v166, v166 quad_perm:[1,0,3,2] row_mask:0xf bank_mask:0xf bound_ctrl:1
	v_pk_fma_f32 v[168:169], v[80:81], v[86:87], v[168:169]
	v_pk_fma_f32 v[174:175], v[80:81], v[88:89], v[174:175]
	v_add_f32_dpp v171, v166, v166 quad_perm:[2,3,0,1] row_mask:0xf bank_mask:0xf bound_ctrl:1
	v_pk_mul_f32 v[166:167], v[82:83], v[92:93]
	v_pk_mul_f32 v[82:83], v[82:83], v[114:115]
	v_pk_fma_f32 v[166:167], v[80:81], v[84:85], v[166:167]
	v_pk_fma_f32 v[176:177], v[80:81], v[90:91], v[176:177]
	v_pk_fma_f32 v[178:179], v[80:81], v[94:95], v[178:179]
	v_pk_fma_f32 v[180:181], v[80:81], v[98:99], v[180:181]
	v_pk_fma_f32 v[182:183], v[80:81], v[102:103], v[182:183]
	v_pk_fma_f32 v[80:81], v[80:81], v[106:107], v[82:83]
	v_pk_add_f32 v[166:167], v[166:167], v[166:167] op_sel:[0,1] op_sel_hi:[1,0]
	v_pk_add_f32 v[178:179], v[178:179], v[178:179] op_sel:[0,1] op_sel_hi:[1,0]
	v_pk_add_f32 v[80:81], v[80:81], v[80:81] op_sel:[0,1] op_sel_hi:[1,0]
	v_pk_add_f32 v[168:169], v[168:169], v[168:169] op_sel:[0,1] op_sel_hi:[1,0]
	v_cndmask_b32_e32 v81, v178, v166, vcc
	v_mov_b32_e32 v83, v81
	v_pk_add_f32 v[180:181], v[180:181], v[180:181] op_sel:[0,1] op_sel_hi:[1,0]
	s_nop 0
	v_permlane32_swap_b32_e32 v81, v83
	v_cndmask_b32_e32 v82, v166, v178, vcc
	v_cndmask_b32_e32 v81, v83, v81, vcc
	v_add_f32_e32 v81, v82, v81
	v_cndmask_b32_e32 v82, v180, v168, vcc
	v_mov_b32_e32 v166, v82
	v_pk_add_f32 v[174:175], v[174:175], v[174:175] op_sel:[0,1] op_sel_hi:[1,0]
	s_nop 0
	v_permlane32_swap_b32_e32 v82, v166
	v_pk_add_f32 v[182:183], v[182:183], v[182:183] op_sel:[0,1] op_sel_hi:[1,0]
	v_cndmask_b32_e32 v83, v168, v180, vcc
	v_cndmask_b32_e32 v82, v166, v82, vcc
	v_add_f32_e32 v82, v83, v82
	v_cndmask_b32_e32 v83, v182, v174, vcc
	v_mov_b32_e32 v167, v83
	v_pk_add_f32 v[176:177], v[176:177], v[176:177] op_sel:[0,1] op_sel_hi:[1,0]
	s_nop 0
	v_permlane32_swap_b32_e32 v83, v167
	v_cndmask_b32_e32 v166, v174, v182, vcc
	v_cndmask_b32_e32 v83, v167, v83, vcc
	v_add_f32_e32 v83, v166, v83
	v_cndmask_b32_e32 v166, v80, v176, vcc
	v_mov_b32_e32 v167, v166
	v_cndmask_b32_e32 v80, v176, v80, vcc
	s_nop 0
	v_permlane32_swap_b32_e32 v166, v167
	v_cndmask_b32_e32 v166, v167, v166, vcc
	v_add_f32_e32 v80, v80, v166
	v_cndmask_b32_e64 v166, v81, v83, s[2:3]
	v_cndmask_b32_e64 v81, v83, v81, s[2:3]
	v_mov_b32_e32 v83, v166
	v_pk_mul_f32 v[168:169], v[78:79], v[104:105]
	s_nop 0
	v_permlane16_swap_b32_e32 v166, v83
	v_cndmask_b32_e64 v83, v166, v83, s[2:3]
	v_add_f32_e32 v81, v81, v83
	v_cndmask_b32_e64 v83, v82, v80, s[2:3]
	v_cndmask_b32_e64 v80, v80, v82, s[2:3]
	v_mov_b32_e32 v82, v83
	v_pk_mul_f32 v[166:167], v[78:79], v[100:101]
	s_nop 0
	v_permlane16_swap_b32_e32 v83, v82
	v_cndmask_b32_e64 v82, v83, v82, s[2:3]
	v_add_f32_e32 v80, v80, v82
	v_cndmask_b32_e64 v82, v81, v80, s[4:5]
	v_cndmask_b32_e64 v80, v80, v81, s[4:5]
	v_pk_mul_f32 v[174:175], v[78:79], v[108:109]
	v_pk_mul_f32 v[176:177], v[78:79], v[110:111]
	v_add_f32_dpp v80, v82, v80 row_ror:8 row_mask:0xf bank_mask:0xf bound_ctrl:1
	v_pk_mul_f32 v[82:83], v[78:79], v[96:97]
	v_pk_mul_f32 v[178:179], v[78:79], v[112:113]
	v_add_f32_dpp v80, v80, v80 quad_perm:[1,0,3,2] row_mask:0xf bank_mask:0xf bound_ctrl:1
	v_pk_fma_f32 v[82:83], v[76:77], v[86:87], v[82:83]
	v_pk_fma_f32 v[166:167], v[76:77], v[88:89], v[166:167]
	v_add_f32_dpp v170, v80, v80 quad_perm:[2,3,0,1] row_mask:0xf bank_mask:0xf bound_ctrl:1
	v_pk_mul_f32 v[80:81], v[78:79], v[92:93]
	v_pk_mul_f32 v[78:79], v[78:79], v[114:115]
	v_pk_fma_f32 v[80:81], v[76:77], v[84:85], v[80:81]
	v_pk_fma_f32 v[168:169], v[76:77], v[90:91], v[168:169]
	v_pk_fma_f32 v[174:175], v[76:77], v[94:95], v[174:175]
	v_pk_fma_f32 v[176:177], v[76:77], v[98:99], v[176:177]
	v_pk_fma_f32 v[178:179], v[76:77], v[102:103], v[178:179]
	v_pk_fma_f32 v[76:77], v[76:77], v[106:107], v[78:79]
	v_pk_add_f32 v[80:81], v[80:81], v[80:81] op_sel:[0,1] op_sel_hi:[1,0]
	v_pk_add_f32 v[174:175], v[174:175], v[174:175] op_sel:[0,1] op_sel_hi:[1,0]
	v_pk_add_f32 v[76:77], v[76:77], v[76:77] op_sel:[0,1] op_sel_hi:[1,0]
	v_pk_add_f32 v[82:83], v[82:83], v[82:83] op_sel:[0,1] op_sel_hi:[1,0]
	v_cndmask_b32_e32 v77, v174, v80, vcc
	v_mov_b32_e32 v79, v77
	v_pk_add_f32 v[176:177], v[176:177], v[176:177] op_sel:[0,1] op_sel_hi:[1,0]
	s_nop 0
	v_permlane32_swap_b32_e32 v77, v79
	v_cndmask_b32_e32 v78, v80, v174, vcc
	v_cndmask_b32_e32 v77, v79, v77, vcc
	v_add_f32_e32 v77, v78, v77
	v_cndmask_b32_e32 v78, v176, v82, vcc
	v_mov_b32_e32 v80, v78
	v_pk_add_f32 v[166:167], v[166:167], v[166:167] op_sel:[0,1] op_sel_hi:[1,0]
	s_nop 0
	v_permlane32_swap_b32_e32 v78, v80
	v_pk_add_f32 v[178:179], v[178:179], v[178:179] op_sel:[0,1] op_sel_hi:[1,0]
	v_cndmask_b32_e32 v79, v82, v176, vcc
	v_cndmask_b32_e32 v78, v80, v78, vcc
	v_add_f32_e32 v78, v79, v78
	v_cndmask_b32_e32 v79, v178, v166, vcc
	v_mov_b32_e32 v81, v79
	v_pk_add_f32 v[168:169], v[168:169], v[168:169] op_sel:[0,1] op_sel_hi:[1,0]
	s_nop 0
	v_permlane32_swap_b32_e32 v79, v81
	v_cndmask_b32_e32 v80, v166, v178, vcc
	v_cndmask_b32_e32 v79, v81, v79, vcc
	v_add_f32_e32 v79, v80, v79
	v_cndmask_b32_e32 v80, v76, v168, vcc
	v_mov_b32_e32 v81, v80
	v_cndmask_b32_e32 v76, v168, v76, vcc
	s_nop 0
	v_permlane32_swap_b32_e32 v80, v81
	v_cndmask_b32_e32 v80, v81, v80, vcc
	v_add_f32_e32 v76, v76, v80
	v_cndmask_b32_e64 v80, v77, v79, s[2:3]
	v_cndmask_b32_e64 v77, v79, v77, s[2:3]
	v_mov_b32_e32 v79, v80
	v_pk_mul_f32 v[82:83], v[74:75], v[104:105]
	s_nop 0
	v_permlane16_swap_b32_e32 v80, v79
	v_cndmask_b32_e64 v79, v80, v79, s[2:3]
	v_add_f32_e32 v77, v77, v79
	v_cndmask_b32_e64 v79, v78, v76, s[2:3]
	v_cndmask_b32_e64 v76, v76, v78, s[2:3]
	v_mov_b32_e32 v78, v79
	v_pk_mul_f32 v[80:81], v[74:75], v[100:101]
	s_nop 0
	v_permlane16_swap_b32_e32 v79, v78
	v_cndmask_b32_e64 v78, v79, v78, s[2:3]
	v_add_f32_e32 v76, v76, v78
	v_cndmask_b32_e64 v78, v77, v76, s[4:5]
	v_cndmask_b32_e64 v76, v76, v77, s[4:5]
	v_pk_mul_f32 v[166:167], v[74:75], v[108:109]
	v_pk_mul_f32 v[168:169], v[74:75], v[110:111]
	v_add_f32_dpp v76, v78, v76 row_ror:8 row_mask:0xf bank_mask:0xf bound_ctrl:1
	v_pk_mul_f32 v[78:79], v[74:75], v[96:97]
	v_pk_mul_f32 v[174:175], v[74:75], v[112:113]
	v_add_f32_dpp v76, v76, v76 quad_perm:[1,0,3,2] row_mask:0xf bank_mask:0xf bound_ctrl:1
	v_pk_fma_f32 v[78:79], v[72:73], v[86:87], v[78:79]
	v_pk_fma_f32 v[80:81], v[72:73], v[88:89], v[80:81]
	v_add_f32_dpp v177, v76, v76 quad_perm:[2,3,0,1] row_mask:0xf bank_mask:0xf bound_ctrl:1
	v_pk_mul_f32 v[76:77], v[74:75], v[92:93]
	v_pk_mul_f32 v[74:75], v[74:75], v[114:115]
	v_pk_fma_f32 v[76:77], v[72:73], v[84:85], v[76:77]
	v_pk_fma_f32 v[82:83], v[72:73], v[90:91], v[82:83]
	v_pk_fma_f32 v[166:167], v[72:73], v[94:95], v[166:167]
	v_pk_fma_f32 v[168:169], v[72:73], v[98:99], v[168:169]
	v_pk_fma_f32 v[174:175], v[72:73], v[102:103], v[174:175]
	v_pk_fma_f32 v[72:73], v[72:73], v[106:107], v[74:75]
	v_pk_add_f32 v[76:77], v[76:77], v[76:77] op_sel:[0,1] op_sel_hi:[1,0]
	v_pk_add_f32 v[166:167], v[166:167], v[166:167] op_sel:[0,1] op_sel_hi:[1,0]
	v_pk_add_f32 v[72:73], v[72:73], v[72:73] op_sel:[0,1] op_sel_hi:[1,0]
	v_pk_add_f32 v[78:79], v[78:79], v[78:79] op_sel:[0,1] op_sel_hi:[1,0]
	v_cndmask_b32_e32 v73, v166, v76, vcc
	v_mov_b32_e32 v75, v73
	v_pk_add_f32 v[168:169], v[168:169], v[168:169] op_sel:[0,1] op_sel_hi:[1,0]
	s_nop 0
	v_permlane32_swap_b32_e32 v73, v75
	v_cndmask_b32_e32 v74, v76, v166, vcc
	v_cndmask_b32_e32 v73, v75, v73, vcc
	v_add_f32_e32 v73, v74, v73
	v_cndmask_b32_e32 v74, v168, v78, vcc
	v_mov_b32_e32 v76, v74
	v_pk_add_f32 v[80:81], v[80:81], v[80:81] op_sel:[0,1] op_sel_hi:[1,0]
	s_nop 0
	v_permlane32_swap_b32_e32 v74, v76
	v_pk_add_f32 v[174:175], v[174:175], v[174:175] op_sel:[0,1] op_sel_hi:[1,0]
	v_cndmask_b32_e32 v75, v78, v168, vcc
	v_cndmask_b32_e32 v74, v76, v74, vcc
	v_add_f32_e32 v74, v75, v74
	v_cndmask_b32_e32 v75, v174, v80, vcc
	v_mov_b32_e32 v77, v75
	v_pk_add_f32 v[82:83], v[82:83], v[82:83] op_sel:[0,1] op_sel_hi:[1,0]
	s_nop 0
	v_permlane32_swap_b32_e32 v75, v77
	v_cndmask_b32_e32 v76, v80, v174, vcc
	v_cndmask_b32_e32 v75, v77, v75, vcc
	v_add_f32_e32 v75, v76, v75
	v_cndmask_b32_e32 v76, v72, v82, vcc
	v_mov_b32_e32 v77, v76
	v_cndmask_b32_e32 v72, v82, v72, vcc
	s_nop 0
	v_permlane32_swap_b32_e32 v76, v77
	v_cndmask_b32_e32 v76, v77, v76, vcc
	v_add_f32_e32 v72, v72, v76
	v_cndmask_b32_e64 v76, v73, v75, s[2:3]
	v_cndmask_b32_e64 v73, v75, v73, s[2:3]
	v_mov_b32_e32 v75, v76
	v_pk_mul_f32 v[78:79], v[70:71], v[104:105]
	s_nop 0
	v_permlane16_swap_b32_e32 v76, v75
	v_cndmask_b32_e64 v75, v76, v75, s[2:3]
	v_add_f32_e32 v73, v73, v75
	v_cndmask_b32_e64 v75, v74, v72, s[2:3]
	v_cndmask_b32_e64 v72, v72, v74, s[2:3]
	v_mov_b32_e32 v74, v75
	v_pk_mul_f32 v[76:77], v[70:71], v[100:101]
	s_nop 0
	v_permlane16_swap_b32_e32 v75, v74
	v_cndmask_b32_e64 v74, v75, v74, s[2:3]
	v_add_f32_e32 v72, v72, v74
	v_cndmask_b32_e64 v74, v73, v72, s[4:5]
	v_cndmask_b32_e64 v72, v72, v73, s[4:5]
	v_pk_mul_f32 v[80:81], v[70:71], v[108:109]
	v_pk_mul_f32 v[82:83], v[70:71], v[110:111]
	v_add_f32_dpp v72, v74, v72 row_ror:8 row_mask:0xf bank_mask:0xf bound_ctrl:1
	v_pk_mul_f32 v[74:75], v[70:71], v[96:97]
	v_pk_mul_f32 v[166:167], v[70:71], v[112:113]
	v_add_f32_dpp v72, v72, v72 quad_perm:[1,0,3,2] row_mask:0xf bank_mask:0xf bound_ctrl:1
	v_pk_fma_f32 v[74:75], v[68:69], v[86:87], v[74:75]
	v_pk_fma_f32 v[76:77], v[68:69], v[88:89], v[76:77]
	v_add_f32_dpp v168, v72, v72 quad_perm:[2,3,0,1] row_mask:0xf bank_mask:0xf bound_ctrl:1
	v_pk_mul_f32 v[72:73], v[70:71], v[92:93]
	v_pk_mul_f32 v[70:71], v[70:71], v[114:115]
	v_pk_fma_f32 v[72:73], v[68:69], v[84:85], v[72:73]
	v_pk_fma_f32 v[78:79], v[68:69], v[90:91], v[78:79]
	v_pk_fma_f32 v[80:81], v[68:69], v[94:95], v[80:81]
	v_pk_fma_f32 v[82:83], v[68:69], v[98:99], v[82:83]
	v_pk_fma_f32 v[166:167], v[68:69], v[102:103], v[166:167]
	v_pk_fma_f32 v[68:69], v[68:69], v[106:107], v[70:71]
	v_pk_add_f32 v[72:73], v[72:73], v[72:73] op_sel:[0,1] op_sel_hi:[1,0]
	v_pk_add_f32 v[80:81], v[80:81], v[80:81] op_sel:[0,1] op_sel_hi:[1,0]
	v_pk_add_f32 v[68:69], v[68:69], v[68:69] op_sel:[0,1] op_sel_hi:[1,0]
	v_pk_add_f32 v[74:75], v[74:75], v[74:75] op_sel:[0,1] op_sel_hi:[1,0]
	v_cndmask_b32_e32 v69, v80, v72, vcc
	v_mov_b32_e32 v71, v69
	v_pk_add_f32 v[82:83], v[82:83], v[82:83] op_sel:[0,1] op_sel_hi:[1,0]
	s_nop 0
	v_permlane32_swap_b32_e32 v69, v71
	v_cndmask_b32_e32 v70, v72, v80, vcc
	v_cndmask_b32_e32 v69, v71, v69, vcc
	v_add_f32_e32 v83, v70, v69
	v_cndmask_b32_e32 v69, v82, v74, vcc
	v_mov_b32_e32 v71, v69
	v_pk_add_f32 v[76:77], v[76:77], v[76:77] op_sel:[0,1] op_sel_hi:[1,0]
	s_nop 0
	v_permlane32_swap_b32_e32 v69, v71
	v_pk_add_f32 v[166:167], v[166:167], v[166:167] op_sel:[0,1] op_sel_hi:[1,0]
	v_cndmask_b32_e32 v70, v74, v82, vcc
	v_cndmask_b32_e32 v69, v71, v69, vcc
	v_add_f32_e32 v82, v70, v69
	v_cndmask_b32_e32 v69, v166, v76, vcc
	v_mov_b32_e32 v71, v69
	v_pk_add_f32 v[78:79], v[78:79], v[78:79] op_sel:[0,1] op_sel_hi:[1,0]
	s_nop 0
	v_permlane32_swap_b32_e32 v69, v71
	v_cndmask_b32_e32 v70, v76, v166, vcc
	v_cndmask_b32_e32 v69, v71, v69, vcc
	v_add_f32_e32 v166, v70, v69
	v_cndmask_b32_e32 v69, v68, v78, vcc
	v_mov_b32_e32 v70, v69
	v_cndmask_b32_e32 v68, v78, v68, vcc
	s_nop 0
	v_permlane32_swap_b32_e32 v69, v70
	v_cndmask_b32_e32 v69, v70, v69, vcc
	v_add_f32_e32 v167, v68, v69
	v_pk_mul_f32 v[68:69], v[66:67], v[92:93]
	v_pk_mul_f32 v[70:71], v[66:67], v[96:97]
	v_pk_mul_f32 v[72:73], v[66:67], v[100:101]
	v_pk_mul_f32 v[74:75], v[66:67], v[104:105]
	v_pk_mul_f32 v[76:77], v[66:67], v[108:109]
	v_pk_mul_f32 v[78:79], v[66:67], v[110:111]
	v_pk_mul_f32 v[80:81], v[66:67], v[112:113]
	v_pk_mul_f32 v[66:67], v[66:67], v[114:115]
	v_pk_fma_f32 v[68:69], v[64:65], v[84:85], v[68:69]
	v_pk_fma_f32 v[70:71], v[64:65], v[86:87], v[70:71]
	v_pk_fma_f32 v[72:73], v[64:65], v[88:89], v[72:73]
	v_pk_fma_f32 v[74:75], v[64:65], v[90:91], v[74:75]
	v_pk_fma_f32 v[76:77], v[64:65], v[94:95], v[76:77]
	v_pk_fma_f32 v[78:79], v[64:65], v[98:99], v[78:79]
	v_pk_fma_f32 v[80:81], v[64:65], v[102:103], v[80:81]
	v_pk_fma_f32 v[64:65], v[64:65], v[106:107], v[66:67]
	v_pk_add_f32 v[68:69], v[68:69], v[68:69] op_sel:[0,1] op_sel_hi:[1,0]
	v_pk_add_f32 v[76:77], v[76:77], v[76:77] op_sel:[0,1] op_sel_hi:[1,0]
	v_pk_add_f32 v[64:65], v[64:65], v[64:65] op_sel:[0,1] op_sel_hi:[1,0]
	v_cndmask_b32_e64 v169, v83, v166, s[2:3]
	v_cndmask_b32_e64 v175, v82, v167, s[2:3]
	v_cndmask_b32_e32 v65, v76, v68, vcc
	v_mov_b32_e32 v174, v169
	v_mov_b32_e32 v176, v175
	v_mov_b32_e32 v67, v65
	v_pk_add_f32 v[70:71], v[70:71], v[70:71] op_sel:[0,1] op_sel_hi:[1,0]
	s_nop 0
	v_permlane32_swap_b32_e32 v65, v67
	v_pk_add_f32 v[78:79], v[78:79], v[78:79] op_sel:[0,1] op_sel_hi:[1,0]
	v_cndmask_b32_e32 v66, v68, v76, vcc
	v_cndmask_b32_e32 v65, v67, v65, vcc
	v_add_f32_e32 v66, v66, v65
	v_cndmask_b32_e32 v65, v78, v70, vcc
	v_mov_b32_e32 v68, v65
	v_pk_add_f32 v[72:73], v[72:73], v[72:73] op_sel:[0,1] op_sel_hi:[1,0]
	s_nop 0
	v_permlane32_swap_b32_e32 v65, v68
	v_pk_add_f32 v[80:81], v[80:81], v[80:81] op_sel:[0,1] op_sel_hi:[1,0]
	v_cndmask_b32_e32 v67, v70, v78, vcc
	v_cndmask_b32_e32 v65, v68, v65, vcc
	v_add_f32_e32 v67, v67, v65
	v_cndmask_b32_e32 v65, v80, v72, vcc
	v_mov_b32_e32 v69, v65
	v_pk_add_f32 v[74:75], v[74:75], v[74:75] op_sel:[0,1] op_sel_hi:[1,0]
	s_nop 0
	v_permlane32_swap_b32_e32 v65, v69
	v_cndmask_b32_e32 v68, v72, v80, vcc
	v_cndmask_b32_e32 v65, v69, v65, vcc
	v_add_f32_e32 v68, v68, v65
	v_cndmask_b32_e32 v65, v64, v74, vcc
	v_mov_b32_e32 v69, v65
	v_cndmask_b32_e32 v64, v74, v64, vcc
	s_nop 0
	v_permlane32_swap_b32_e32 v65, v69
	v_cndmask_b32_e32 v65, v69, v65, vcc
	v_add_f32_e32 v69, v64, v65
	v_cndmask_b32_e64 v70, v66, v68, s[2:3]
	v_cndmask_b32_e64 v72, v67, v69, s[2:3]
	v_add_co_u32_e64 v64, s[6:7], s0, v116
	v_mov_b32_e32 v71, v70
	v_mov_b32_e32 v73, v72
	v_addc_co_u32_e64 v65, s[6:7], 0, v117, s[6:7]
	s_waitcnt vmcnt(0)
	v_mov_b32_e32 v184, v222
	v_mov_b32_e32 v185, v223
	v_mov_b32_e32 v186, v224
	v_mov_b32_e32 v187, v225
	v_mov_b32_e32 v188, v226
	v_mov_b32_e32 v189, v227
	v_mov_b32_e32 v190, v228
	v_mov_b32_e32 v191, v229
	v_permlane16_swap_b32_e32 v169, v174
	v_cndmask_b32_e64 v64, v166, v83, s[2:3]
	v_cndmask_b32_e64 v65, v169, v174, s[2:3]
	v_permlane16_swap_b32_e32 v175, v176
	v_add_f32_e32 v64, v64, v65
	v_cndmask_b32_e64 v65, v167, v82, s[2:3]
	v_cndmask_b32_e64 v74, v175, v176, s[2:3]
	v_add_f32_e32 v65, v65, v74
	v_cndmask_b32_e64 v74, v64, v65, s[4:5]
	v_cndmask_b32_e64 v64, v65, v64, s[4:5]
	v_permlane16_swap_b32_e32 v70, v71
	s_nop 0
	v_add_f32_dpp v64, v74, v64 row_ror:8 row_mask:0xf bank_mask:0xf bound_ctrl:1
	v_cndmask_b32_e64 v65, v70, v71, s[2:3]
	v_permlane16_swap_b32_e32 v72, v73
	v_add_f32_dpp v64, v64, v64 quad_perm:[1,0,3,2] row_mask:0xf bank_mask:0xf bound_ctrl:1
	s_mov_b32 s0, 0x1d000
	v_add_f32_dpp v120, v120, v120 quad_perm:[1,0,3,2] row_mask:0xf bank_mask:0xf bound_ctrl:1
	v_add_f32_dpp v167, v64, v64 quad_perm:[2,3,0,1] row_mask:0xf bank_mask:0xf bound_ctrl:1
	v_cndmask_b32_e64 v64, v68, v66, s[2:3]
	v_add_f32_e32 v64, v64, v65
	v_cndmask_b32_e64 v65, v69, v67, s[2:3]
	v_cndmask_b32_e64 v66, v72, v73, s[2:3]
	v_add_f32_e32 v65, v65, v66
	v_cndmask_b32_e64 v66, v64, v65, s[4:5]
	v_cndmask_b32_e64 v64, v65, v64, s[4:5]
	v_add_f32_dpp v120, v120, v120 quad_perm:[2,3,0,1] row_mask:0xf bank_mask:0xf bound_ctrl:1
	v_add_f32_dpp v122, v122, v122 quad_perm:[1,0,3,2] row_mask:0xf bank_mask:0xf bound_ctrl:1
	v_add_f32_dpp v64, v66, v64 row_ror:8 row_mask:0xf bank_mask:0xf bound_ctrl:1
	v_mov_b32_dpp v121, v120 row_half_mirror row_mask:0xf bank_mask:0xf bound_ctrl:1
	v_add_f32_dpp v122, v122, v122 quad_perm:[2,3,0,1] row_mask:0xf bank_mask:0xf bound_ctrl:1
	v_add_f32_dpp v64, v64, v64 quad_perm:[1,0,3,2] row_mask:0xf bank_mask:0xf bound_ctrl:1
	v_mov_b32_dpp v173, v170 row_half_mirror row_mask:0xf bank_mask:0xf bound_ctrl:1
	v_mov_b32_dpp v123, v122 row_half_mirror row_mask:0xf bank_mask:0xf bound_ctrl:1
	v_add_f32_dpp v166, v64, v64 quad_perm:[2,3,0,1] row_mask:0xf bank_mask:0xf bound_ctrl:1
	v_add_co_u32_e64 v64, s[6:7], s48, v116
	v_mov_b32_dpp v172, v171 row_half_mirror row_mask:0xf bank_mask:0xf bound_ctrl:1
	s_nop 0
	v_addc_co_u32_e64 v65, s[6:7], 0, v117, s[6:7]
	v_add_co_u32_e64 v68, s[6:7], s49, v116
	v_add_f32_e32 v170, v170, v173
	s_nop 0
	v_addc_co_u32_e64 v69, s[6:7], 0, v117, s[6:7]
	v_add_co_u32_e64 v72, s[6:7], s0, v116
	s_mov_b32 s0, 0x1b000
	s_nop 0
	v_addc_co_u32_e64 v73, s[6:7], 0, v117, s[6:7]
	v_add_co_u32_e64 v76, s[6:7], s42, v116
	v_mov_b32_e32 v64, v230
	v_mov_b32_e32 v65, v231
	v_mov_b32_e32 v66, v232
	v_mov_b32_e32 v67, v233
	s_nop 0
	v_mov_b32_e32 v68, v234
	v_mov_b32_e32 v69, v235
	v_mov_b32_e32 v70, v236
	v_mov_b32_e32 v71, v237
	v_addc_co_u32_e64 v77, s[6:7], 0, v117, s[6:7]
	v_add_co_u32_e64 v80, s[6:7], s0, v116
	v_mov_b32_e32 v72, v238
	v_mov_b32_e32 v73, v239
	v_mov_b32_e32 v74, v240
	v_mov_b32_e32 v75, v241
	s_nop 0
	v_mov_b32_e32 v76, v242
	v_mov_b32_e32 v77, v243
	v_mov_b32_e32 v78, v244
	v_mov_b32_e32 v79, v245
	v_addc_co_u32_e64 v81, s[6:7], 0, v117, s[6:7]
	v_add_co_u32_e64 v116, s[6:7], s50, v116
	v_add_f32_e32 v173, v120, v121
	s_nop 0
	v_addc_co_u32_e64 v117, s[6:7], 0, v117, s[6:7]
	v_mov_b32_e32 v80, v250
	v_mov_b32_e32 v81, v251
	v_mov_b32_e32 v82, v252
	v_mov_b32_e32 v83, v253
	s_nop 0
	global_load_dwordx4 v[116:119], v[116:117], off nt
	v_add_f32_e32 v171, v171, v172
	v_add_f32_e32 v172, v122, v123
	v_max3_f32 v134, v134, v147, v148
	v_mul_f32_e32 v154, 0x3d800000, v153
	v_mul_f32_e32 v156, 0x3d800000, v155
	v_max3_f32 v134, v134, v150, v152
	v_mul_f32_e32 v159, 0x3d800000, v158
	v_mul_f32_e32 v163, 0x3d800000, v160
	v_max3_f32 v134, v134, v154, v156
	v_mul_f32_e32 v164, 0x3d800000, v161
	v_pk_mul_f32 v[120:121], v[190:191], v[92:93]
	v_pk_mul_f32 v[216:217], v[190:191], v[108:109]
	v_pk_fma_f32 v[120:121], v[188:189], v[84:85], v[120:121]
	v_pk_mul_f32 v[122:123], v[190:191], v[96:97]
	v_pk_fma_f32 v[216:217], v[188:189], v[94:95], v[216:217]
	v_pk_add_f32 v[120:121], v[120:121], v[120:121] op_sel:[0,1] op_sel_hi:[1,0]
	v_pk_fma_f32 v[122:123], v[188:189], v[86:87], v[122:123]
	v_pk_add_f32 v[216:217], v[216:217], v[216:217] op_sel:[0,1] op_sel_hi:[1,0]
	v_pk_add_f32 v[122:123], v[122:123], v[122:123] op_sel:[0,1] op_sel_hi:[1,0]
	v_cndmask_b32_e32 v121, v216, v120, vcc
	v_mov_b32_e32 v123, v121
	v_pk_mul_f32 v[218:219], v[190:191], v[110:111]
	v_cndmask_b32_e32 v120, v120, v216, vcc
	v_pk_fma_f32 v[218:219], v[188:189], v[98:99], v[218:219]
	v_permlane32_swap_b32_e32 v121, v123
	v_pk_add_f32 v[218:219], v[218:219], v[218:219] op_sel:[0,1] op_sel_hi:[1,0]
	v_cndmask_b32_e32 v121, v123, v121, vcc
	v_add_f32_e32 v120, v121, v120
	v_cndmask_b32_e32 v121, v218, v122, vcc
	v_mov_b32_e32 v123, v121
	v_pk_mul_f32 v[182:183], v[190:191], v[100:101]
	v_pk_mul_f32 v[220:221], v[190:191], v[112:113]
	v_pk_fma_f32 v[182:183], v[188:189], v[88:89], v[182:183]
	v_pk_fma_f32 v[220:221], v[188:189], v[102:103], v[220:221]
	v_permlane32_swap_b32_e32 v121, v123
	v_pk_add_f32 v[182:183], v[182:183], v[182:183] op_sel:[0,1] op_sel_hi:[1,0]
	v_pk_add_f32 v[220:221], v[220:221], v[220:221] op_sel:[0,1] op_sel_hi:[1,0]
	v_cndmask_b32_e32 v122, v122, v218, vcc
	v_cndmask_b32_e32 v121, v123, v121, vcc
	v_add_f32_e32 v121, v121, v122
	v_cndmask_b32_e32 v122, v220, v182, vcc
	v_cndmask_b32_e32 v123, v182, v220, vcc
	v_mov_b32_e32 v182, v122
	v_pk_mul_f32 v[192:193], v[190:191], v[104:105]
	v_pk_mul_f32 v[190:191], v[190:191], v[114:115]
	v_pk_fma_f32 v[192:193], v[188:189], v[90:91], v[192:193]
	v_pk_fma_f32 v[188:189], v[188:189], v[106:107], v[190:191]
	v_permlane32_swap_b32_e32 v122, v182
	v_pk_add_f32 v[192:193], v[192:193], v[192:193] op_sel:[0,1] op_sel_hi:[1,0]
	v_pk_add_f32 v[188:189], v[188:189], v[188:189] op_sel:[0,1] op_sel_hi:[1,0]
	v_cndmask_b32_e32 v122, v182, v122, vcc
	v_add_f32_e32 v122, v123, v122
	v_cndmask_b32_e32 v123, v188, v192, vcc
	v_mov_b32_e32 v183, v123
	v_cndmask_b32_e32 v182, v192, v188, vcc
	s_nop 0
	v_permlane32_swap_b32_e32 v123, v183
	v_cndmask_b32_e32 v123, v183, v123, vcc
	v_add_f32_e32 v123, v182, v123
	v_cndmask_b32_e64 v182, v120, v122, s[2:3]
	v_cndmask_b32_e64 v120, v122, v120, s[2:3]
	v_mov_b32_e32 v122, v182
	v_pk_mul_f32 v[192:193], v[186:187], v[108:109]
	s_nop 0
	v_permlane16_swap_b32_e32 v182, v122
	v_cndmask_b32_e64 v122, v182, v122, s[2:3]
	v_add_f32_e32 v120, v120, v122
	v_cndmask_b32_e64 v122, v121, v123, s[2:3]
	v_cndmask_b32_e64 v121, v123, v121, s[2:3]
	v_mov_b32_e32 v123, v122
	v_pk_fma_f32 v[192:193], v[184:185], v[94:95], v[192:193]
	s_nop 0
	v_permlane16_swap_b32_e32 v122, v123
	v_cndmask_b32_e64 v122, v122, v123, s[2:3]
	v_add_f32_e32 v121, v121, v122
	v_cndmask_b32_e64 v122, v120, v121, s[4:5]
	v_cndmask_b32_e64 v120, v121, v120, s[4:5]
	v_pk_add_f32 v[192:193], v[192:193], v[192:193] op_sel:[0,1] op_sel_hi:[1,0]
	v_pk_mul_f32 v[216:217], v[186:187], v[110:111]
	v_add_f32_dpp v120, v122, v120 row_ror:8 row_mask:0xf bank_mask:0xf bound_ctrl:1
	v_pk_mul_f32 v[122:123], v[186:187], v[96:97]
	v_pk_fma_f32 v[216:217], v[184:185], v[98:99], v[216:217]
	v_add_f32_dpp v120, v120, v120 quad_perm:[1,0,3,2] row_mask:0xf bank_mask:0xf bound_ctrl:1
	v_pk_fma_f32 v[122:123], v[184:185], v[86:87], v[122:123]
	v_pk_add_f32 v[216:217], v[216:217], v[216:217] op_sel:[0,1] op_sel_hi:[1,0]
	v_add_f32_dpp v120, v120, v120 quad_perm:[2,3,0,1] row_mask:0xf bank_mask:0xf bound_ctrl:1
	v_pk_add_f32 v[122:123], v[122:123], v[122:123] op_sel:[0,1] op_sel_hi:[1,0]
	v_pk_mul_f32 v[188:189], v[186:187], v[100:101]
	v_add_f32_dpp v182, v120, v120 row_half_mirror row_mask:0xf bank_mask:0xf bound_ctrl:1
	v_pk_mul_f32 v[120:121], v[186:187], v[92:93]
	v_pk_mul_f32 v[218:219], v[186:187], v[112:113]
	v_pk_fma_f32 v[120:121], v[184:185], v[84:85], v[120:121]
	v_pk_fma_f32 v[188:189], v[184:185], v[88:89], v[188:189]
	v_pk_add_f32 v[120:121], v[120:121], v[120:121] op_sel:[0,1] op_sel_hi:[1,0]
	v_pk_mul_f32 v[190:191], v[186:187], v[104:105]
	v_cndmask_b32_e32 v121, v192, v120, vcc
	v_mov_b32_e32 v123, v121
	v_cndmask_b32_e32 v120, v120, v192, vcc
	s_nop 0
	v_permlane32_swap_b32_e32 v121, v123
	v_cndmask_b32_e32 v121, v123, v121, vcc
	v_add_f32_e32 v120, v120, v121
	v_cndmask_b32_e32 v121, v216, v122, vcc
	v_mov_b32_e32 v123, v121
	v_pk_fma_f32 v[218:219], v[184:185], v[102:103], v[218:219]
	v_pk_mul_f32 v[186:187], v[186:187], v[114:115]
	v_permlane32_swap_b32_e32 v121, v123
	v_pk_add_f32 v[188:189], v[188:189], v[188:189] op_sel:[0,1] op_sel_hi:[1,0]
	v_pk_fma_f32 v[190:191], v[184:185], v[90:91], v[190:191]
	v_pk_add_f32 v[218:219], v[218:219], v[218:219] op_sel:[0,1] op_sel_hi:[1,0]
	v_pk_fma_f32 v[184:185], v[184:185], v[106:107], v[186:187]
	v_cndmask_b32_e32 v122, v122, v216, vcc
	v_cndmask_b32_e32 v121, v123, v121, vcc
	v_pk_add_f32 v[184:185], v[184:185], v[184:185] op_sel:[0,1] op_sel_hi:[1,0]
	v_add_f32_e32 v121, v122, v121
	v_cndmask_b32_e32 v122, v218, v188, vcc
	v_mov_b32_e32 v185, v122
	v_pk_add_f32 v[190:191], v[190:191], v[190:191] op_sel:[0,1] op_sel_hi:[1,0]
	s_nop 0
	v_permlane32_swap_b32_e32 v122, v185
	v_cndmask_b32_e32 v123, v188, v218, vcc
	v_cndmask_b32_e32 v122, v185, v122, vcc
	v_add_f32_e32 v122, v123, v122
	v_cndmask_b32_e32 v123, v184, v190, vcc
	v_mov_b32_e32 v185, v123
	v_cndmask_b32_e32 v184, v190, v184, vcc
	s_nop 0
	v_permlane32_swap_b32_e32 v123, v185
	v_cndmask_b32_e32 v123, v185, v123, vcc
	v_add_f32_e32 v123, v184, v123
	v_cndmask_b32_e64 v184, v120, v122, s[2:3]
	v_cndmask_b32_e64 v120, v122, v120, s[2:3]
	v_mov_b32_e32 v122, v184
	s_waitcnt vmcnt(0)
	v_pk_mul_f32 v[186:187], v[118:119], v[100:101]
	v_permlane16_swap_b32_e32 v184, v122
	v_cndmask_b32_e64 v122, v184, v122, s[2:3]
	v_add_f32_e32 v120, v120, v122
	v_cndmask_b32_e64 v122, v121, v123, s[2:3]
	v_cndmask_b32_e64 v121, v123, v121, s[2:3]
	v_mov_b32_e32 v123, v122
	v_pk_mul_f32 v[188:189], v[118:119], v[104:105]
	s_nop 0
	v_permlane16_swap_b32_e32 v122, v123
	v_cndmask_b32_e64 v122, v122, v123, s[2:3]
	v_add_f32_e32 v121, v121, v122
	v_cndmask_b32_e64 v122, v120, v121, s[4:5]
	v_cndmask_b32_e64 v120, v121, v120, s[4:5]
	v_pk_mul_f32 v[190:191], v[118:119], v[108:109]
	v_pk_mul_f32 v[192:193], v[118:119], v[110:111]
	v_add_f32_dpp v120, v122, v120 row_ror:8 row_mask:0xf bank_mask:0xf bound_ctrl:1
	v_pk_mul_f32 v[122:123], v[118:119], v[96:97]
	v_pk_mul_f32 v[216:217], v[118:119], v[112:113]
	v_add_f32_dpp v120, v120, v120 quad_perm:[1,0,3,2] row_mask:0xf bank_mask:0xf bound_ctrl:1
	v_pk_fma_f32 v[122:123], v[116:117], v[86:87], v[122:123]
	v_pk_fma_f32 v[186:187], v[116:117], v[88:89], v[186:187]
	v_add_f32_dpp v120, v120, v120 quad_perm:[2,3,0,1] row_mask:0xf bank_mask:0xf bound_ctrl:1
	v_pk_fma_f32 v[188:189], v[116:117], v[90:91], v[188:189]
	v_pk_fma_f32 v[190:191], v[116:117], v[94:95], v[190:191]
	v_add_f32_dpp v184, v120, v120 row_half_mirror row_mask:0xf bank_mask:0xf bound_ctrl:1
	v_pk_mul_f32 v[120:121], v[118:119], v[92:93]
	v_pk_mul_f32 v[118:119], v[118:119], v[114:115]
	v_pk_fma_f32 v[120:121], v[116:117], v[84:85], v[120:121]
	v_pk_fma_f32 v[192:193], v[116:117], v[98:99], v[192:193]
	v_pk_fma_f32 v[216:217], v[116:117], v[102:103], v[216:217]
	v_pk_fma_f32 v[116:117], v[116:117], v[106:107], v[118:119]
	v_pk_add_f32 v[120:121], v[120:121], v[120:121] op_sel:[0,1] op_sel_hi:[1,0]
	v_pk_add_f32 v[190:191], v[190:191], v[190:191] op_sel:[0,1] op_sel_hi:[1,0]
	v_pk_add_f32 v[116:117], v[116:117], v[116:117] op_sel:[0,1] op_sel_hi:[1,0]
	v_pk_add_f32 v[122:123], v[122:123], v[122:123] op_sel:[0,1] op_sel_hi:[1,0]
	v_cndmask_b32_e32 v117, v190, v120, vcc
	v_mov_b32_e32 v119, v117
	v_pk_add_f32 v[192:193], v[192:193], v[192:193] op_sel:[0,1] op_sel_hi:[1,0]
	s_nop 0
	v_permlane32_swap_b32_e32 v117, v119
	v_cndmask_b32_e32 v118, v120, v190, vcc
	v_cndmask_b32_e32 v117, v119, v117, vcc
	v_add_f32_e32 v117, v118, v117
	v_cndmask_b32_e32 v118, v192, v122, vcc
	v_mov_b32_e32 v120, v118
	v_pk_add_f32 v[186:187], v[186:187], v[186:187] op_sel:[0,1] op_sel_hi:[1,0]
	s_nop 0
	v_permlane32_swap_b32_e32 v118, v120
	v_pk_add_f32 v[216:217], v[216:217], v[216:217] op_sel:[0,1] op_sel_hi:[1,0]
	v_cndmask_b32_e32 v119, v122, v192, vcc
	v_cndmask_b32_e32 v118, v120, v118, vcc
	v_add_f32_e32 v118, v119, v118
	v_cndmask_b32_e32 v119, v216, v186, vcc
	v_mov_b32_e32 v121, v119
	v_pk_add_f32 v[188:189], v[188:189], v[188:189] op_sel:[0,1] op_sel_hi:[1,0]
	s_nop 0
	v_permlane32_swap_b32_e32 v119, v121
	v_cndmask_b32_e32 v120, v186, v216, vcc
	v_cndmask_b32_e32 v119, v121, v119, vcc
	v_add_f32_e32 v119, v120, v119
	v_cndmask_b32_e32 v120, v116, v188, vcc
	v_mov_b32_e32 v121, v120
	v_cndmask_b32_e32 v116, v188, v116, vcc
	s_nop 0
	v_permlane32_swap_b32_e32 v120, v121
	v_cndmask_b32_e32 v120, v121, v120, vcc
	v_add_f32_e32 v116, v116, v120
	v_cndmask_b32_e64 v120, v117, v119, s[2:3]
	v_cndmask_b32_e64 v117, v119, v117, s[2:3]
	v_mov_b32_e32 v119, v120
	v_pk_mul_f32 v[122:123], v[82:83], v[104:105]
	s_nop 0
	v_permlane16_swap_b32_e32 v120, v119
	v_cndmask_b32_e64 v119, v120, v119, s[2:3]
	v_add_f32_e32 v117, v117, v119
	v_cndmask_b32_e64 v119, v118, v116, s[2:3]
	v_cndmask_b32_e64 v116, v116, v118, s[2:3]
	v_mov_b32_e32 v118, v119
	v_pk_mul_f32 v[120:121], v[82:83], v[100:101]
	s_nop 0
	v_permlane16_swap_b32_e32 v119, v118
	v_cndmask_b32_e64 v118, v119, v118, s[2:3]
	v_add_f32_e32 v116, v116, v118
	v_cndmask_b32_e64 v118, v117, v116, s[4:5]
	v_cndmask_b32_e64 v116, v116, v117, s[4:5]
	v_pk_mul_f32 v[188:189], v[82:83], v[108:109]
	v_pk_mul_f32 v[190:191], v[82:83], v[110:111]
	v_add_f32_dpp v116, v118, v116 row_ror:8 row_mask:0xf bank_mask:0xf bound_ctrl:1
	v_pk_mul_f32 v[118:119], v[82:83], v[96:97]
	v_pk_mul_f32 v[192:193], v[82:83], v[112:113]
	v_add_f32_dpp v116, v116, v116 quad_perm:[1,0,3,2] row_mask:0xf bank_mask:0xf bound_ctrl:1
	v_pk_fma_f32 v[118:119], v[80:81], v[86:87], v[118:119]
	v_pk_fma_f32 v[120:121], v[80:81], v[88:89], v[120:121]
	v_add_f32_dpp v116, v116, v116 quad_perm:[2,3,0,1] row_mask:0xf bank_mask:0xf bound_ctrl:1
	v_pk_fma_f32 v[122:123], v[80:81], v[90:91], v[122:123]
	v_pk_fma_f32 v[188:189], v[80:81], v[94:95], v[188:189]
	v_add_f32_dpp v186, v116, v116 row_half_mirror row_mask:0xf bank_mask:0xf bound_ctrl:1
	v_pk_mul_f32 v[116:117], v[82:83], v[92:93]
	v_pk_mul_f32 v[82:83], v[82:83], v[114:115]
	v_pk_fma_f32 v[116:117], v[80:81], v[84:85], v[116:117]
	v_pk_fma_f32 v[190:191], v[80:81], v[98:99], v[190:191]
	v_pk_fma_f32 v[192:193], v[80:81], v[102:103], v[192:193]
	v_pk_fma_f32 v[80:81], v[80:81], v[106:107], v[82:83]
	v_pk_add_f32 v[116:117], v[116:117], v[116:117] op_sel:[0,1] op_sel_hi:[1,0]
	v_pk_add_f32 v[188:189], v[188:189], v[188:189] op_sel:[0,1] op_sel_hi:[1,0]
	v_pk_add_f32 v[80:81], v[80:81], v[80:81] op_sel:[0,1] op_sel_hi:[1,0]
	v_pk_add_f32 v[118:119], v[118:119], v[118:119] op_sel:[0,1] op_sel_hi:[1,0]
	v_cndmask_b32_e32 v81, v188, v116, vcc
	v_mov_b32_e32 v83, v81
	v_pk_add_f32 v[190:191], v[190:191], v[190:191] op_sel:[0,1] op_sel_hi:[1,0]
	s_nop 0
	v_permlane32_swap_b32_e32 v81, v83
	v_cndmask_b32_e32 v82, v116, v188, vcc
	v_cndmask_b32_e32 v81, v83, v81, vcc
	v_add_f32_e32 v81, v82, v81
	v_cndmask_b32_e32 v82, v190, v118, vcc
	v_mov_b32_e32 v116, v82
	v_pk_add_f32 v[120:121], v[120:121], v[120:121] op_sel:[0,1] op_sel_hi:[1,0]
	s_nop 0
	v_permlane32_swap_b32_e32 v82, v116
	v_pk_add_f32 v[192:193], v[192:193], v[192:193] op_sel:[0,1] op_sel_hi:[1,0]
	v_cndmask_b32_e32 v83, v118, v190, vcc
	v_cndmask_b32_e32 v82, v116, v82, vcc
	v_add_f32_e32 v82, v83, v82
	v_cndmask_b32_e32 v83, v192, v120, vcc
	v_mov_b32_e32 v117, v83
	v_pk_add_f32 v[122:123], v[122:123], v[122:123] op_sel:[0,1] op_sel_hi:[1,0]
	s_nop 0
	v_permlane32_swap_b32_e32 v83, v117
	v_cndmask_b32_e32 v116, v120, v192, vcc
	v_cndmask_b32_e32 v83, v117, v83, vcc
	v_add_f32_e32 v83, v116, v83
	v_cndmask_b32_e32 v116, v80, v122, vcc
	v_mov_b32_e32 v117, v116
	v_cndmask_b32_e32 v80, v122, v80, vcc
	s_nop 0
	v_permlane32_swap_b32_e32 v116, v117
	v_cndmask_b32_e32 v116, v117, v116, vcc
	v_add_f32_e32 v80, v80, v116
	v_cndmask_b32_e64 v116, v81, v83, s[2:3]
	v_cndmask_b32_e64 v81, v83, v81, s[2:3]
	v_mov_b32_e32 v83, v116
	v_pk_mul_f32 v[118:119], v[78:79], v[104:105]
	s_nop 0
	v_permlane16_swap_b32_e32 v116, v83
	v_cndmask_b32_e64 v83, v116, v83, s[2:3]
	v_add_f32_e32 v81, v81, v83
	v_cndmask_b32_e64 v83, v82, v80, s[2:3]
	v_cndmask_b32_e64 v80, v80, v82, s[2:3]
	v_mov_b32_e32 v82, v83
	v_pk_mul_f32 v[116:117], v[78:79], v[100:101]
	s_nop 0
	v_permlane16_swap_b32_e32 v83, v82
	v_cndmask_b32_e64 v82, v83, v82, s[2:3]
	v_add_f32_e32 v80, v80, v82
	v_cndmask_b32_e64 v82, v81, v80, s[4:5]
	v_cndmask_b32_e64 v80, v80, v81, s[4:5]
	v_pk_mul_f32 v[120:121], v[78:79], v[108:109]
	v_pk_mul_f32 v[122:123], v[78:79], v[110:111]
	v_add_f32_dpp v80, v82, v80 row_ror:8 row_mask:0xf bank_mask:0xf bound_ctrl:1
	v_pk_mul_f32 v[82:83], v[78:79], v[96:97]
	v_pk_mul_f32 v[188:189], v[78:79], v[112:113]
	v_add_f32_dpp v80, v80, v80 quad_perm:[1,0,3,2] row_mask:0xf bank_mask:0xf bound_ctrl:1
	v_pk_fma_f32 v[82:83], v[76:77], v[86:87], v[82:83]
	v_pk_fma_f32 v[116:117], v[76:77], v[88:89], v[116:117]
	v_add_f32_dpp v80, v80, v80 quad_perm:[2,3,0,1] row_mask:0xf bank_mask:0xf bound_ctrl:1
	v_pk_fma_f32 v[118:119], v[76:77], v[90:91], v[118:119]
	v_pk_fma_f32 v[120:121], v[76:77], v[94:95], v[120:121]
	v_add_f32_dpp v190, v80, v80 row_half_mirror row_mask:0xf bank_mask:0xf bound_ctrl:1
	v_pk_mul_f32 v[80:81], v[78:79], v[92:93]
	v_pk_mul_f32 v[78:79], v[78:79], v[114:115]
	v_pk_fma_f32 v[80:81], v[76:77], v[84:85], v[80:81]
	v_pk_fma_f32 v[122:123], v[76:77], v[98:99], v[122:123]
	v_pk_fma_f32 v[188:189], v[76:77], v[102:103], v[188:189]
	v_pk_fma_f32 v[76:77], v[76:77], v[106:107], v[78:79]
	v_pk_add_f32 v[80:81], v[80:81], v[80:81] op_sel:[0,1] op_sel_hi:[1,0]
	v_pk_add_f32 v[120:121], v[120:121], v[120:121] op_sel:[0,1] op_sel_hi:[1,0]
	v_pk_add_f32 v[76:77], v[76:77], v[76:77] op_sel:[0,1] op_sel_hi:[1,0]
	v_pk_add_f32 v[82:83], v[82:83], v[82:83] op_sel:[0,1] op_sel_hi:[1,0]
	v_cndmask_b32_e32 v77, v120, v80, vcc
	v_mov_b32_e32 v79, v77
	v_pk_add_f32 v[122:123], v[122:123], v[122:123] op_sel:[0,1] op_sel_hi:[1,0]
	s_nop 0
	v_permlane32_swap_b32_e32 v77, v79
	v_cndmask_b32_e32 v78, v80, v120, vcc
	v_cndmask_b32_e32 v77, v79, v77, vcc
	v_add_f32_e32 v77, v78, v77
	v_cndmask_b32_e32 v78, v122, v82, vcc
	v_mov_b32_e32 v80, v78
	v_pk_add_f32 v[116:117], v[116:117], v[116:117] op_sel:[0,1] op_sel_hi:[1,0]
	s_nop 0
	v_permlane32_swap_b32_e32 v78, v80
	v_pk_add_f32 v[188:189], v[188:189], v[188:189] op_sel:[0,1] op_sel_hi:[1,0]
	v_cndmask_b32_e32 v79, v82, v122, vcc
	v_cndmask_b32_e32 v78, v80, v78, vcc
	v_add_f32_e32 v78, v79, v78
	v_cndmask_b32_e32 v79, v188, v116, vcc
	v_mov_b32_e32 v81, v79
	v_pk_add_f32 v[118:119], v[118:119], v[118:119] op_sel:[0,1] op_sel_hi:[1,0]
	s_nop 0
	v_permlane32_swap_b32_e32 v79, v81
	v_cndmask_b32_e32 v80, v116, v188, vcc
	v_cndmask_b32_e32 v79, v81, v79, vcc
	v_add_f32_e32 v79, v80, v79
	v_cndmask_b32_e32 v80, v76, v118, vcc
	v_mov_b32_e32 v81, v80
	v_cndmask_b32_e32 v76, v118, v76, vcc
	s_nop 0
	v_permlane32_swap_b32_e32 v80, v81
	v_cndmask_b32_e32 v80, v81, v80, vcc
	v_add_f32_e32 v76, v76, v80
	v_cndmask_b32_e64 v80, v77, v79, s[2:3]
	v_cndmask_b32_e64 v77, v79, v77, s[2:3]
	v_mov_b32_e32 v79, v80
	v_pk_mul_f32 v[82:83], v[74:75], v[104:105]
	s_nop 0
	v_permlane16_swap_b32_e32 v80, v79
	v_cndmask_b32_e64 v79, v80, v79, s[2:3]
	v_add_f32_e32 v77, v77, v79
	v_cndmask_b32_e64 v79, v78, v76, s[2:3]
	v_cndmask_b32_e64 v76, v76, v78, s[2:3]
	v_mov_b32_e32 v78, v79
	v_pk_mul_f32 v[80:81], v[74:75], v[100:101]
	s_nop 0
	v_permlane16_swap_b32_e32 v79, v78
	v_cndmask_b32_e64 v78, v79, v78, s[2:3]
	v_add_f32_e32 v76, v76, v78
	v_cndmask_b32_e64 v78, v77, v76, s[4:5]
	v_cndmask_b32_e64 v76, v76, v77, s[4:5]
	v_pk_mul_f32 v[116:117], v[74:75], v[108:109]
	v_pk_mul_f32 v[118:119], v[74:75], v[110:111]
	v_add_f32_dpp v76, v78, v76 row_ror:8 row_mask:0xf bank_mask:0xf bound_ctrl:1
	v_pk_mul_f32 v[78:79], v[74:75], v[96:97]
	v_pk_mul_f32 v[120:121], v[74:75], v[112:113]
	v_add_f32_dpp v76, v76, v76 quad_perm:[1,0,3,2] row_mask:0xf bank_mask:0xf bound_ctrl:1
	v_pk_fma_f32 v[78:79], v[72:73], v[86:87], v[78:79]
	v_pk_fma_f32 v[80:81], v[72:73], v[88:89], v[80:81]
	v_add_f32_dpp v76, v76, v76 quad_perm:[2,3,0,1] row_mask:0xf bank_mask:0xf bound_ctrl:1
	v_pk_fma_f32 v[82:83], v[72:73], v[90:91], v[82:83]
	v_pk_fma_f32 v[116:117], v[72:73], v[94:95], v[116:117]
	v_add_f32_dpp v188, v76, v76 row_half_mirror row_mask:0xf bank_mask:0xf bound_ctrl:1
	v_pk_mul_f32 v[76:77], v[74:75], v[92:93]
	v_pk_mul_f32 v[74:75], v[74:75], v[114:115]
	v_pk_fma_f32 v[76:77], v[72:73], v[84:85], v[76:77]
	v_pk_fma_f32 v[118:119], v[72:73], v[98:99], v[118:119]
	v_pk_fma_f32 v[120:121], v[72:73], v[102:103], v[120:121]
	v_pk_fma_f32 v[72:73], v[72:73], v[106:107], v[74:75]
	v_pk_add_f32 v[76:77], v[76:77], v[76:77] op_sel:[0,1] op_sel_hi:[1,0]
	v_pk_add_f32 v[116:117], v[116:117], v[116:117] op_sel:[0,1] op_sel_hi:[1,0]
	v_pk_add_f32 v[72:73], v[72:73], v[72:73] op_sel:[0,1] op_sel_hi:[1,0]
	v_pk_add_f32 v[78:79], v[78:79], v[78:79] op_sel:[0,1] op_sel_hi:[1,0]
	v_cndmask_b32_e32 v73, v116, v76, vcc
	v_mov_b32_e32 v75, v73
	v_pk_add_f32 v[118:119], v[118:119], v[118:119] op_sel:[0,1] op_sel_hi:[1,0]
	s_nop 0
	v_permlane32_swap_b32_e32 v73, v75
	v_cndmask_b32_e32 v74, v76, v116, vcc
	v_cndmask_b32_e32 v73, v75, v73, vcc
	v_add_f32_e32 v73, v74, v73
	v_cndmask_b32_e32 v74, v118, v78, vcc
	v_mov_b32_e32 v76, v74
	v_pk_add_f32 v[80:81], v[80:81], v[80:81] op_sel:[0,1] op_sel_hi:[1,0]
	s_nop 0
	v_permlane32_swap_b32_e32 v74, v76
	v_pk_add_f32 v[120:121], v[120:121], v[120:121] op_sel:[0,1] op_sel_hi:[1,0]
	v_cndmask_b32_e32 v75, v78, v118, vcc
	v_cndmask_b32_e32 v74, v76, v74, vcc
	v_add_f32_e32 v74, v75, v74
	v_cndmask_b32_e32 v75, v120, v80, vcc
	v_mov_b32_e32 v77, v75
	v_pk_add_f32 v[82:83], v[82:83], v[82:83] op_sel:[0,1] op_sel_hi:[1,0]
	s_nop 0
	v_permlane32_swap_b32_e32 v75, v77
	v_cndmask_b32_e32 v76, v80, v120, vcc
	v_cndmask_b32_e32 v75, v77, v75, vcc
	v_add_f32_e32 v75, v76, v75
	v_cndmask_b32_e32 v76, v72, v82, vcc
	v_mov_b32_e32 v77, v76
	v_cndmask_b32_e32 v72, v82, v72, vcc
	s_nop 0
	v_permlane32_swap_b32_e32 v76, v77
	v_cndmask_b32_e32 v76, v77, v76, vcc
	v_add_f32_e32 v72, v72, v76
	v_cndmask_b32_e64 v76, v73, v75, s[2:3]
	v_cndmask_b32_e64 v73, v75, v73, s[2:3]
	v_mov_b32_e32 v75, v76
	v_pk_mul_f32 v[78:79], v[70:71], v[104:105]
	s_nop 0
	v_permlane16_swap_b32_e32 v76, v75
	v_cndmask_b32_e64 v75, v76, v75, s[2:3]
	v_add_f32_e32 v73, v73, v75
	v_cndmask_b32_e64 v75, v74, v72, s[2:3]
	v_cndmask_b32_e64 v72, v72, v74, s[2:3]
	v_mov_b32_e32 v74, v75
	v_pk_mul_f32 v[76:77], v[70:71], v[100:101]
	s_nop 0
	v_permlane16_swap_b32_e32 v75, v74
	v_cndmask_b32_e64 v74, v75, v74, s[2:3]
	v_add_f32_e32 v72, v72, v74
	v_cndmask_b32_e64 v74, v73, v72, s[4:5]
	v_cndmask_b32_e64 v72, v72, v73, s[4:5]
	v_pk_mul_f32 v[80:81], v[70:71], v[108:109]
	v_pk_mul_f32 v[82:83], v[70:71], v[110:111]
	v_add_f32_dpp v72, v74, v72 row_ror:8 row_mask:0xf bank_mask:0xf bound_ctrl:1
	v_pk_mul_f32 v[74:75], v[70:71], v[96:97]
	v_pk_mul_f32 v[116:117], v[70:71], v[112:113]
	v_add_f32_dpp v72, v72, v72 quad_perm:[1,0,3,2] row_mask:0xf bank_mask:0xf bound_ctrl:1
	v_pk_fma_f32 v[74:75], v[68:69], v[86:87], v[74:75]
	v_pk_fma_f32 v[76:77], v[68:69], v[88:89], v[76:77]
	v_add_f32_dpp v72, v72, v72 quad_perm:[2,3,0,1] row_mask:0xf bank_mask:0xf bound_ctrl:1
	v_pk_fma_f32 v[78:79], v[68:69], v[90:91], v[78:79]
	v_pk_fma_f32 v[80:81], v[68:69], v[94:95], v[80:81]
	v_add_f32_dpp v192, v72, v72 row_half_mirror row_mask:0xf bank_mask:0xf bound_ctrl:1
	v_pk_mul_f32 v[72:73], v[70:71], v[92:93]
	v_pk_mul_f32 v[70:71], v[70:71], v[114:115]
	v_pk_fma_f32 v[72:73], v[68:69], v[84:85], v[72:73]
	v_pk_fma_f32 v[82:83], v[68:69], v[98:99], v[82:83]
	v_pk_fma_f32 v[116:117], v[68:69], v[102:103], v[116:117]
	v_pk_fma_f32 v[68:69], v[68:69], v[106:107], v[70:71]
	v_pk_add_f32 v[72:73], v[72:73], v[72:73] op_sel:[0,1] op_sel_hi:[1,0]
	v_pk_add_f32 v[80:81], v[80:81], v[80:81] op_sel:[0,1] op_sel_hi:[1,0]
	v_pk_add_f32 v[68:69], v[68:69], v[68:69] op_sel:[0,1] op_sel_hi:[1,0]
	v_pk_add_f32 v[74:75], v[74:75], v[74:75] op_sel:[0,1] op_sel_hi:[1,0]
	v_cndmask_b32_e32 v69, v80, v72, vcc
	v_mov_b32_e32 v71, v69
	v_pk_add_f32 v[82:83], v[82:83], v[82:83] op_sel:[0,1] op_sel_hi:[1,0]
	s_nop 0
	v_permlane32_swap_b32_e32 v69, v71
	v_cndmask_b32_e32 v70, v72, v80, vcc
	v_cndmask_b32_e32 v69, v71, v69, vcc
	v_add_f32_e32 v69, v70, v69
	v_cndmask_b32_e32 v70, v82, v74, vcc
	v_mov_b32_e32 v72, v70
	v_pk_add_f32 v[76:77], v[76:77], v[76:77] op_sel:[0,1] op_sel_hi:[1,0]
	s_nop 0
	v_permlane32_swap_b32_e32 v70, v72
	v_pk_add_f32 v[116:117], v[116:117], v[116:117] op_sel:[0,1] op_sel_hi:[1,0]
	v_cndmask_b32_e32 v71, v74, v82, vcc
	v_cndmask_b32_e32 v70, v72, v70, vcc
	v_add_f32_e32 v70, v71, v70
	v_cndmask_b32_e32 v71, v116, v76, vcc
	v_mov_b32_e32 v73, v71
	v_pk_add_f32 v[78:79], v[78:79], v[78:79] op_sel:[0,1] op_sel_hi:[1,0]
	s_nop 0
	v_permlane32_swap_b32_e32 v71, v73
	v_cndmask_b32_e32 v72, v76, v116, vcc
	v_cndmask_b32_e32 v71, v73, v71, vcc
	v_add_f32_e32 v71, v72, v71
	v_cndmask_b32_e32 v72, v68, v78, vcc
	v_mov_b32_e32 v73, v72
	v_cndmask_b32_e32 v68, v78, v68, vcc
	s_nop 0
	v_permlane32_swap_b32_e32 v72, v73
	v_cndmask_b32_e32 v72, v73, v72, vcc
	v_add_f32_e32 v68, v68, v72
	v_cndmask_b32_e64 v72, v69, v71, s[2:3]
	v_cndmask_b32_e64 v69, v71, v69, s[2:3]
	v_mov_b32_e32 v71, v72
	v_pk_mul_f32 v[74:75], v[66:67], v[104:105]
	s_nop 0
	v_permlane16_swap_b32_e32 v72, v71
	v_cndmask_b32_e64 v71, v72, v71, s[2:3]
	v_add_f32_e32 v69, v69, v71
	v_cndmask_b32_e64 v71, v70, v68, s[2:3]
	v_cndmask_b32_e64 v68, v68, v70, s[2:3]
	v_mov_b32_e32 v70, v71
	v_pk_mul_f32 v[72:73], v[66:67], v[100:101]
	s_nop 0
	v_permlane16_swap_b32_e32 v71, v70
	v_cndmask_b32_e64 v70, v71, v70, s[2:3]
	v_add_f32_e32 v68, v68, v70
	v_cndmask_b32_e64 v70, v69, v68, s[4:5]
	v_cndmask_b32_e64 v68, v68, v69, s[4:5]
	v_pk_mul_f32 v[76:77], v[66:67], v[108:109]
	v_pk_mul_f32 v[78:79], v[66:67], v[110:111]
	v_add_f32_dpp v68, v70, v68 row_ror:8 row_mask:0xf bank_mask:0xf bound_ctrl:1
	v_pk_mul_f32 v[70:71], v[66:67], v[96:97]
	v_pk_mul_f32 v[80:81], v[66:67], v[112:113]
	v_add_f32_dpp v68, v68, v68 quad_perm:[1,0,3,2] row_mask:0xf bank_mask:0xf bound_ctrl:1
	v_pk_fma_f32 v[70:71], v[64:65], v[86:87], v[70:71]
	v_pk_fma_f32 v[72:73], v[64:65], v[88:89], v[72:73]
	v_add_f32_dpp v68, v68, v68 quad_perm:[2,3,0,1] row_mask:0xf bank_mask:0xf bound_ctrl:1
	v_pk_fma_f32 v[74:75], v[64:65], v[90:91], v[74:75]
	v_pk_fma_f32 v[76:77], v[64:65], v[94:95], v[76:77]
	v_add_f32_dpp v215, v68, v68 row_half_mirror row_mask:0xf bank_mask:0xf bound_ctrl:1
	v_pk_mul_f32 v[68:69], v[66:67], v[92:93]
	v_pk_mul_f32 v[66:67], v[66:67], v[114:115]
	v_pk_fma_f32 v[68:69], v[64:65], v[84:85], v[68:69]
	v_pk_fma_f32 v[78:79], v[64:65], v[98:99], v[78:79]
	v_pk_fma_f32 v[80:81], v[64:65], v[102:103], v[80:81]
	v_pk_fma_f32 v[64:65], v[64:65], v[106:107], v[66:67]
	v_pk_add_f32 v[68:69], v[68:69], v[68:69] op_sel:[0,1] op_sel_hi:[1,0]
	v_pk_add_f32 v[76:77], v[76:77], v[76:77] op_sel:[0,1] op_sel_hi:[1,0]
	v_pk_add_f32 v[64:65], v[64:65], v[64:65] op_sel:[0,1] op_sel_hi:[1,0]
	v_pk_add_f32 v[70:71], v[70:71], v[70:71] op_sel:[0,1] op_sel_hi:[1,0]
	v_cndmask_b32_e32 v65, v76, v68, vcc
	v_mov_b32_e32 v67, v65
	v_pk_add_f32 v[78:79], v[78:79], v[78:79] op_sel:[0,1] op_sel_hi:[1,0]
	s_nop 0
	v_permlane32_swap_b32_e32 v65, v67
	v_cndmask_b32_e32 v66, v68, v76, vcc
	v_cndmask_b32_e32 v65, v67, v65, vcc
	v_add_f32_e32 v65, v66, v65
	v_cndmask_b32_e32 v66, v78, v70, vcc
	v_mov_b32_e32 v68, v66
	v_pk_add_f32 v[72:73], v[72:73], v[72:73] op_sel:[0,1] op_sel_hi:[1,0]
	s_nop 0
	v_permlane32_swap_b32_e32 v66, v68
	v_pk_add_f32 v[80:81], v[80:81], v[80:81] op_sel:[0,1] op_sel_hi:[1,0]
	v_cndmask_b32_e32 v67, v70, v78, vcc
	v_cndmask_b32_e32 v66, v68, v66, vcc
	v_add_f32_e32 v66, v67, v66
	v_cndmask_b32_e32 v67, v80, v72, vcc
	v_mov_b32_e32 v69, v67
	v_pk_add_f32 v[74:75], v[74:75], v[74:75] op_sel:[0,1] op_sel_hi:[1,0]
	s_nop 0
	v_permlane32_swap_b32_e32 v67, v69
	v_cndmask_b32_e32 v68, v72, v80, vcc
	v_cndmask_b32_e32 v67, v69, v67, vcc
	v_add_f32_e32 v67, v68, v67
	v_cndmask_b32_e32 v68, v64, v74, vcc
	v_mov_b32_e32 v69, v68
	v_cndmask_b32_e32 v64, v74, v64, vcc
	s_nop 0
	v_permlane32_swap_b32_e32 v68, v69
	v_cndmask_b32_e32 v68, v69, v68, vcc
	v_add_f32_e32 v64, v64, v68
	v_cndmask_b32_e64 v68, v65, v67, s[2:3]
	v_cndmask_b32_e64 v65, v67, v65, s[2:3]
	v_mov_b32_e32 v67, v68
	v_mul_f32_e32 v165, 0x3d800000, v162
	s_nop 0
	v_permlane16_swap_b32_e32 v68, v67
	v_cndmask_b32_e64 v67, v68, v67, s[2:3]
	v_add_f32_e32 v65, v65, v67
	v_cndmask_b32_e64 v67, v66, v64, s[2:3]
	v_cndmask_b32_e64 v64, v64, v66, s[2:3]
	v_mov_b32_e32 v66, v67
	v_max3_f32 v134, v134, v159, v163
	s_nop 0
	v_permlane16_swap_b32_e32 v67, v66
	v_mov_b32_dpp v178, v177 row_half_mirror row_mask:0xf bank_mask:0xf bound_ctrl:1
	v_mov_b32_dpp v179, v168 row_half_mirror row_mask:0xf bank_mask:0xf bound_ctrl:1
	v_mov_b32_dpp v169, v167 row_half_mirror row_mask:0xf bank_mask:0xf bound_ctrl:1
	v_mul_f32_e32 v180, 0x3d800000, v172
	v_mul_f32_e32 v181, 0x3d800000, v173
	v_cndmask_b32_e64 v66, v67, v66, s[2:3]
	v_max3_f32 v134, v134, v164, v165
	v_mov_b32_dpp v174, v166 row_half_mirror row_mask:0xf bank_mask:0xf bound_ctrl:1
	v_add_f32_e32 v167, v167, v169
	v_add_f32_e32 v168, v168, v179
	v_add_f32_e32 v169, v177, v178
	v_mul_f32_e32 v178, 0x3d800000, v170
	v_mul_f32_e32 v179, 0x3d800000, v171
	v_add_f32_e32 v64, v64, v66
	v_max3_f32 v134, v134, v181, v180
	v_add_f32_e32 v166, v166, v174
	v_mul_f32_e32 v176, 0x3d800000, v168
	v_mul_f32_e32 v177, 0x3d800000, v169
	v_cndmask_b32_e64 v66, v65, v64, s[4:5]
	v_cndmask_b32_e64 v64, v64, v65, s[4:5]
	v_max3_f32 v134, v134, v179, v178
	v_mul_f32_e32 v174, 0x3d800000, v166
	v_mul_f32_e32 v175, 0x3d800000, v167
	v_add_f32_dpp v64, v66, v64 row_ror:8 row_mask:0xf bank_mask:0xf bound_ctrl:1
	v_max3_f32 v134, v134, v177, v176
	v_mul_f32_e32 v183, 0x3d800000, v182
	v_mul_f32_e32 v185, 0x3d800000, v184
	v_add_f32_dpp v64, v64, v64 quad_perm:[1,0,3,2] row_mask:0xf bank_mask:0xf bound_ctrl:1
	v_max3_f32 v134, v134, v175, v174
	v_mul_f32_e32 v187, 0x3d800000, v186
	v_mul_f32_e32 v191, 0x3d800000, v190
	v_add_f32_dpp v64, v64, v64 quad_perm:[2,3,0,1] row_mask:0xf bank_mask:0xf bound_ctrl:1
	v_max3_f32 v134, v134, v183, v185
	v_mul_f32_e32 v189, 0x3d800000, v188
	v_mul_f32_e32 v193, 0x3d800000, v192
	v_add_f32_dpp v217, v64, v64 row_half_mirror row_mask:0xf bank_mask:0xf bound_ctrl:1
	v_max3_f32 v134, v134, v187, v191
	v_mul_f32_e32 v216, 0x3d800000, v215
	v_mul_f32_e32 v218, 0x3d800000, v217
	v_max3_f32 v134, v134, v189, v193
	v_max3_f32 v134, v134, v216, v218
	v_fma_f32 v133, v133, s28, -v134
	v_mul_f32_e32 v133, 0x3fb8aa3b, v133
	v_exp_f32_e32 v133, v133
	v_fma_f32 v140, v145, s28, -v134
	v_fma_f32 v144, v153, s28, -v134
	v_fma_f32 v145, v155, s28, -v134
	v_readlane_b32 s0, v133, 0
	v_fma_f32 v152, v171, s28, -v134
	v_fma_f32 v153, v170, s28, -v134
	v_fma_f32 v154, v169, s28, -v134
	v_fma_f32 v155, v168, s28, -v134
	v_pk_fma_f32 v[168:169], v[28:29], s[0:1], 0 op_sel_hi:[1,0,0]
	v_pk_fma_f32 v[170:171], v[30:31], s[0:1], 0 op_sel_hi:[1,0,0]
	v_readlane_b32 s0, v133, 8
	v_fma_f32 v135, v135, s28, -v134
	v_fma_f32 v136, v137, s28, -v134
	v_fma_f32 v137, v139, s28, -v134
	v_fma_f32 v139, v143, s28, -v134
	v_fma_f32 v143, v151, s28, -v134
	v_fma_f32 v150, v173, s28, -v134
	v_fma_f32 v151, v172, s28, -v134
	v_pk_fma_f32 v[172:173], v[28:29], s[0:1], 0 op_sel_hi:[1,0,0]
	v_pk_fma_f32 v[174:175], v[30:31], s[0:1], 0 op_sel_hi:[1,0,0]
	v_readlane_b32 s0, v133, 16
	v_mul_f32_e32 v135, 0x3fb8aa3b, v135
	v_exp_f32_e32 v135, v135
	v_pk_fma_f32 v[176:177], v[28:29], s[0:1], 0 op_sel_hi:[1,0,0]
	v_pk_fma_f32 v[178:179], v[30:31], s[0:1], 0 op_sel_hi:[1,0,0]
	v_readlane_b32 s0, v133, 24
	v_fma_f32 v159, v182, s28, -v134
	v_fma_f32 v147, v160, s28, -v134
	v_pk_fma_f32 v[180:181], v[28:29], s[0:1], 0 op_sel_hi:[1,0,0]
	v_pk_fma_f32 v[182:183], v[30:31], s[0:1], 0 op_sel_hi:[1,0,0]
	v_readlane_b32 s0, v133, 32
	v_fma_f32 v148, v161, s28, -v134
	v_fma_f32 v160, v184, s28, -v134
	v_fma_f32 v161, v186, s28, -v134
	v_pk_fma_f32 v[184:185], v[28:29], s[0:1], 0 op_sel_hi:[1,0,0]
	v_pk_fma_f32 v[186:187], v[30:31], s[0:1], 0 op_sel_hi:[1,0,0]
	v_readlane_b32 s0, v133, 40
	v_fma_f32 v142, v149, s28, -v134
	v_fma_f32 v149, v162, s28, -v134
	v_fma_f32 v162, v190, s28, -v134
	v_fma_f32 v163, v188, s28, -v134
	v_pk_fma_f32 v[188:189], v[28:29], s[0:1], 0 op_sel_hi:[1,0,0]
	v_pk_fma_f32 v[190:191], v[30:31], s[0:1], 0 op_sel_hi:[1,0,0]
	v_readlane_b32 s0, v133, 48
	v_fma_f32 v138, v141, s28, -v134
	v_fma_f32 v141, v146, s28, -v134
	v_fma_f32 v146, v158, s28, -v134
	v_fma_f32 v158, v166, s28, -v134
	v_fma_f32 v164, v192, s28, -v134
	v_fma_f32 v166, v217, s28, -v134
	v_pk_fma_f32 v[192:193], v[28:29], s[0:1], 0 op_sel_hi:[1,0,0]
	v_pk_fma_f32 v[216:217], v[30:31], s[0:1], 0 op_sel_hi:[1,0,0]
	v_readlane_b32 s0, v133, 56
	v_mul_f32_e32 v136, 0x3fb8aa3b, v136
	v_exp_f32_e32 v136, v136
	v_pk_fma_f32 v[28:29], v[28:29], s[0:1], 0 op_sel_hi:[1,0,0]
	v_pk_fma_f32 v[30:31], v[30:31], s[0:1], 0 op_sel_hi:[1,0,0]
	v_readlane_b32 s0, v135, 0
	v_mul_f32_e32 v137, 0x3fb8aa3b, v137
	v_exp_f32_e32 v137, v137
	v_pk_fma_f32 v[170:171], v[26:27], s[0:1], v[170:171] op_sel_hi:[1,0,1]
	v_pk_fma_f32 v[168:169], v[24:25], s[0:1], v[168:169] op_sel_hi:[1,0,1]
	v_readlane_b32 s0, v135, 8
	v_mul_f32_e32 v138, 0x3fb8aa3b, v138
	v_exp_f32_e32 v138, v138
	v_pk_fma_f32 v[174:175], v[26:27], s[0:1], v[174:175] op_sel_hi:[1,0,1]
	v_pk_fma_f32 v[172:173], v[24:25], s[0:1], v[172:173] op_sel_hi:[1,0,1]
	v_readlane_b32 s0, v135, 16
	v_add_co_u32_e32 v64, vcc, s47, v124
	s_nop 0
	v_pk_fma_f32 v[178:179], v[26:27], s[0:1], v[178:179] op_sel_hi:[1,0,1]
	v_pk_fma_f32 v[176:177], v[24:25], s[0:1], v[176:177] op_sel_hi:[1,0,1]
	v_readlane_b32 s0, v135, 24
	v_addc_co_u32_e32 v65, vcc, 0, v125, vcc
	s_nop 0
	v_pk_fma_f32 v[182:183], v[26:27], s[0:1], v[182:183] op_sel_hi:[1,0,1]
	v_pk_fma_f32 v[180:181], v[24:25], s[0:1], v[180:181] op_sel_hi:[1,0,1]
	v_readlane_b32 s0, v135, 32
	v_mul_f32_e32 v139, 0x3fb8aa3b, v139
	global_load_dwordx4 v[120:123], v[64:65], off offset:-4096 nt
	global_load_dwordx4 v[116:119], v[64:65], off nt
	v_pk_fma_f32 v[186:187], v[26:27], s[0:1], v[186:187] op_sel_hi:[1,0,1]
	v_pk_fma_f32 v[184:185], v[24:25], s[0:1], v[184:185] op_sel_hi:[1,0,1]
	v_readlane_b32 s0, v135, 40
	v_add_co_u32_e32 v64, vcc, s40, v124
	s_nop 0
	v_pk_fma_f32 v[190:191], v[26:27], s[0:1], v[190:191] op_sel_hi:[1,0,1]
	v_pk_fma_f32 v[188:189], v[24:25], s[0:1], v[188:189] op_sel_hi:[1,0,1]
	v_readlane_b32 s0, v135, 48
	v_exp_f32_e32 v139, v139
	v_addc_co_u32_e32 v65, vcc, 0, v125, vcc
	v_pk_fma_f32 v[216:217], v[26:27], s[0:1], v[216:217] op_sel_hi:[1,0,1]
	v_pk_fma_f32 v[192:193], v[24:25], s[0:1], v[192:193] op_sel_hi:[1,0,1]
	v_readlane_b32 s0, v135, 56
	global_load_dwordx4 v[112:115], v[64:65], off offset:-4096 nt
	global_load_dwordx4 v[108:111], v[64:65], off nt
	v_pk_fma_f32 v[26:27], v[26:27], s[0:1], v[30:31] op_sel_hi:[1,0,1]
	v_pk_fma_f32 v[24:25], v[24:25], s[0:1], v[28:29] op_sel_hi:[1,0,1]
	v_readlane_b32 s0, v136, 0
	v_add_co_u32_e32 v64, vcc, s46, v124
	s_nop 0
	v_pk_fma_f32 v[28:29], v[20:21], s[0:1], v[168:169] op_sel_hi:[1,0,1]
	v_pk_fma_f32 v[30:31], v[22:23], s[0:1], v[170:171] op_sel_hi:[1,0,1]
	v_readlane_b32 s0, v136, 8
	v_addc_co_u32_e32 v65, vcc, 0, v125, vcc
	s_nop 0
	v_pk_fma_f32 v[168:169], v[20:21], s[0:1], v[172:173] op_sel_hi:[1,0,1]
	v_pk_fma_f32 v[170:171], v[22:23], s[0:1], v[174:175] op_sel_hi:[1,0,1]
	v_readlane_b32 s0, v136, 16
	global_load_dwordx4 v[104:107], v[64:65], off offset:-4096 nt
	global_load_dwordx4 v[100:103], v[64:65], off nt
	v_pk_fma_f32 v[172:173], v[20:21], s[0:1], v[176:177] op_sel_hi:[1,0,1]
	v_pk_fma_f32 v[174:175], v[22:23], s[0:1], v[178:179] op_sel_hi:[1,0,1]
	v_readlane_b32 s0, v136, 24
	v_add_co_u32_e32 v64, vcc, s41, v124
	s_nop 0
	v_pk_fma_f32 v[176:177], v[20:21], s[0:1], v[180:181] op_sel_hi:[1,0,1]
	v_pk_fma_f32 v[178:179], v[22:23], s[0:1], v[182:183] op_sel_hi:[1,0,1]
	v_readlane_b32 s0, v136, 32
	v_addc_co_u32_e32 v65, vcc, 0, v125, vcc
	s_nop 0
	v_pk_fma_f32 v[180:181], v[20:21], s[0:1], v[184:185] op_sel_hi:[1,0,1]
	v_pk_fma_f32 v[182:183], v[22:23], s[0:1], v[186:187] op_sel_hi:[1,0,1]
	v_readlane_b32 s0, v136, 40
	global_load_dwordx4 v[96:99], v[64:65], off offset:-4096 nt
	global_load_dwordx4 v[92:95], v[64:65], off nt
	v_pk_fma_f32 v[184:185], v[20:21], s[0:1], v[188:189] op_sel_hi:[1,0,1]
	v_pk_fma_f32 v[186:187], v[22:23], s[0:1], v[190:191] op_sel_hi:[1,0,1]
	v_readlane_b32 s0, v136, 48
	v_add_co_u32_e32 v64, vcc, s50, v124
	s_nop 0
	v_pk_fma_f32 v[188:189], v[20:21], s[0:1], v[192:193] op_sel_hi:[1,0,1]
	v_pk_fma_f32 v[190:191], v[22:23], s[0:1], v[216:217] op_sel_hi:[1,0,1]
	v_readlane_b32 s0, v136, 56
	v_addc_co_u32_e32 v65, vcc, 0, v125, vcc
	s_nop 0
	v_pk_fma_f32 v[20:21], v[20:21], s[0:1], v[24:25] op_sel_hi:[1,0,1]
	v_pk_fma_f32 v[22:23], v[22:23], s[0:1], v[26:27] op_sel_hi:[1,0,1]
	v_readlane_b32 s0, v137, 0
	v_mul_f32_e32 v140, 0x3fb8aa3b, v140
	global_load_dwordx4 v[88:91], v[64:65], off offset:-4096 nt
	global_load_dwordx4 v[84:87], v[64:65], off nt
	v_pk_fma_f32 v[24:25], v[18:19], s[0:1], v[30:31] op_sel_hi:[1,0,1]
	v_pk_fma_f32 v[26:27], v[16:17], s[0:1], v[28:29] op_sel_hi:[1,0,1]
	v_readlane_b32 s0, v137, 8
	v_add_co_u32_e32 v64, vcc, s42, v124
	s_nop 0
	v_pk_fma_f32 v[28:29], v[18:19], s[0:1], v[170:171] op_sel_hi:[1,0,1]
	v_pk_fma_f32 v[30:31], v[16:17], s[0:1], v[168:169] op_sel_hi:[1,0,1]
	v_readlane_b32 s0, v137, 16
	v_exp_f32_e32 v140, v140
	v_addc_co_u32_e32 v65, vcc, 0, v125, vcc
	v_pk_fma_f32 v[168:169], v[18:19], s[0:1], v[174:175] op_sel_hi:[1,0,1]
	v_pk_fma_f32 v[170:171], v[16:17], s[0:1], v[172:173] op_sel_hi:[1,0,1]
	v_readlane_b32 s0, v137, 24
	global_load_dwordx4 v[80:83], v[64:65], off offset:-4096 nt
	global_load_dwordx4 v[76:79], v[64:65], off nt
	v_pk_fma_f32 v[172:173], v[18:19], s[0:1], v[178:179] op_sel_hi:[1,0,1]
	v_pk_fma_f32 v[174:175], v[16:17], s[0:1], v[176:177] op_sel_hi:[1,0,1]
	v_readlane_b32 s0, v137, 32
	v_add_co_u32_e32 v64, vcc, s49, v124
	s_nop 0
	v_pk_fma_f32 v[176:177], v[18:19], s[0:1], v[182:183] op_sel_hi:[1,0,1]
	v_pk_fma_f32 v[178:179], v[16:17], s[0:1], v[180:181] op_sel_hi:[1,0,1]
	v_readlane_b32 s0, v137, 40
	v_addc_co_u32_e32 v65, vcc, 0, v125, vcc
	s_nop 0
	v_pk_fma_f32 v[180:181], v[18:19], s[0:1], v[186:187] op_sel_hi:[1,0,1]
	v_pk_fma_f32 v[182:183], v[16:17], s[0:1], v[184:185] op_sel_hi:[1,0,1]
	v_readlane_b32 s0, v137, 48
	global_load_dwordx4 v[72:75], v[64:65], off offset:-4096 nt
	global_load_dwordx4 v[68:71], v[64:65], off nt
	v_pk_fma_f32 v[184:185], v[18:19], s[0:1], v[190:191] op_sel_hi:[1,0,1]
	v_pk_fma_f32 v[186:187], v[16:17], s[0:1], v[188:189] op_sel_hi:[1,0,1]
	v_readlane_b32 s0, v137, 56
	v_add_co_u32_e32 v64, vcc, s48, v124
	s_nop 0
	v_pk_fma_f32 v[18:19], v[18:19], s[0:1], v[22:23] op_sel_hi:[1,0,1]
	v_pk_fma_f32 v[16:17], v[16:17], s[0:1], v[20:21] op_sel_hi:[1,0,1]
	v_readlane_b32 s0, v138, 0
	v_addc_co_u32_e32 v65, vcc, 0, v125, vcc
	s_nop 0
	v_pk_fma_f32 v[20:21], v[12:13], s[0:1], v[26:27] op_sel_hi:[1,0,1]
	v_pk_fma_f32 v[22:23], v[14:15], s[0:1], v[24:25] op_sel_hi:[1,0,1]
	v_readlane_b32 s0, v138, 8
	global_load_dwordx4 v[124:127], v[126:127], off nt
	s_nop 0
	global_load_dwordx4 v[64:67], v[64:65], off nt
	v_pk_fma_f32 v[24:25], v[12:13], s[0:1], v[30:31] op_sel_hi:[1,0,1]
	v_pk_fma_f32 v[26:27], v[14:15], s[0:1], v[28:29] op_sel_hi:[1,0,1]
	v_readlane_b32 s0, v138, 16
	v_mul_f32_e32 v141, 0x3fb8aa3b, v141
	v_exp_f32_e32 v141, v141
	v_pk_fma_f32 v[28:29], v[12:13], s[0:1], v[170:171] op_sel_hi:[1,0,1]
	v_pk_fma_f32 v[30:31], v[14:15], s[0:1], v[168:169] op_sel_hi:[1,0,1]
	v_readlane_b32 s0, v138, 24
	v_mul_f32_e32 v142, 0x3fb8aa3b, v142
	v_exp_f32_e32 v142, v142
	v_pk_fma_f32 v[168:169], v[12:13], s[0:1], v[174:175] op_sel_hi:[1,0,1]
	v_pk_fma_f32 v[170:171], v[14:15], s[0:1], v[172:173] op_sel_hi:[1,0,1]
	v_readlane_b32 s0, v138, 32
	v_mul_f32_e32 v143, 0x3fb8aa3b, v143
	v_exp_f32_e32 v143, v143
	v_pk_fma_f32 v[172:173], v[12:13], s[0:1], v[178:179] op_sel_hi:[1,0,1]
	v_pk_fma_f32 v[174:175], v[14:15], s[0:1], v[176:177] op_sel_hi:[1,0,1]
	v_readlane_b32 s0, v138, 40
	v_mul_f32_e32 v144, 0x3fb8aa3b, v144
	v_exp_f32_e32 v144, v144
	v_pk_fma_f32 v[176:177], v[12:13], s[0:1], v[182:183] op_sel_hi:[1,0,1]
	v_pk_fma_f32 v[178:179], v[14:15], s[0:1], v[180:181] op_sel_hi:[1,0,1]
	v_readlane_b32 s0, v138, 48
	v_mul_f32_e32 v145, 0x3fb8aa3b, v145
	v_exp_f32_e32 v145, v145
	v_pk_fma_f32 v[180:181], v[12:13], s[0:1], v[186:187] op_sel_hi:[1,0,1]
	v_pk_fma_f32 v[182:183], v[14:15], s[0:1], v[184:185] op_sel_hi:[1,0,1]
	v_readlane_b32 s0, v138, 56
	v_mul_f32_e32 v146, 0x3fb8aa3b, v146
	v_exp_f32_e32 v146, v146
	v_pk_fma_f32 v[12:13], v[12:13], s[0:1], v[16:17] op_sel_hi:[1,0,1]
	v_pk_fma_f32 v[14:15], v[14:15], s[0:1], v[18:19] op_sel_hi:[1,0,1]
	v_readlane_b32 s0, v139, 0
	v_mul_f32_e32 v147, 0x3fb8aa3b, v147
	v_exp_f32_e32 v147, v147
	v_pk_fma_f32 v[16:17], v[10:11], s[0:1], v[22:23] op_sel_hi:[1,0,1]
	v_pk_fma_f32 v[18:19], v[8:9], s[0:1], v[20:21] op_sel_hi:[1,0,1]
	v_readlane_b32 s0, v139, 8
	v_mul_f32_e32 v148, 0x3fb8aa3b, v148
	v_exp_f32_e32 v148, v148
	v_pk_fma_f32 v[20:21], v[10:11], s[0:1], v[26:27] op_sel_hi:[1,0,1]
	v_pk_fma_f32 v[22:23], v[8:9], s[0:1], v[24:25] op_sel_hi:[1,0,1]
	v_readlane_b32 s0, v139, 16
	v_mul_f32_e32 v149, 0x3fb8aa3b, v149
	v_exp_f32_e32 v149, v149
	v_pk_fma_f32 v[24:25], v[10:11], s[0:1], v[30:31] op_sel_hi:[1,0,1]
	v_pk_fma_f32 v[26:27], v[8:9], s[0:1], v[28:29] op_sel_hi:[1,0,1]
	v_readlane_b32 s0, v139, 24
	v_mul_f32_e32 v150, 0x3fb8aa3b, v150
	v_exp_f32_e32 v150, v150
	v_pk_fma_f32 v[28:29], v[10:11], s[0:1], v[170:171] op_sel_hi:[1,0,1]
	v_pk_fma_f32 v[30:31], v[8:9], s[0:1], v[168:169] op_sel_hi:[1,0,1]
	v_readlane_b32 s0, v139, 32
	v_mul_f32_e32 v151, 0x3fb8aa3b, v151
	v_exp_f32_e32 v151, v151
	v_pk_fma_f32 v[168:169], v[10:11], s[0:1], v[174:175] op_sel_hi:[1,0,1]
	v_pk_fma_f32 v[170:171], v[8:9], s[0:1], v[172:173] op_sel_hi:[1,0,1]
	v_readlane_b32 s0, v139, 40
	v_mul_f32_e32 v152, 0x3fb8aa3b, v152
	v_exp_f32_e32 v152, v152
	v_pk_fma_f32 v[172:173], v[10:11], s[0:1], v[178:179] op_sel_hi:[1,0,1]
	v_pk_fma_f32 v[174:175], v[8:9], s[0:1], v[176:177] op_sel_hi:[1,0,1]
	v_readlane_b32 s0, v139, 48
	v_mul_f32_e32 v153, 0x3fb8aa3b, v153
	v_exp_f32_e32 v153, v153
	v_pk_fma_f32 v[176:177], v[10:11], s[0:1], v[182:183] op_sel_hi:[1,0,1]
	v_pk_fma_f32 v[178:179], v[8:9], s[0:1], v[180:181] op_sel_hi:[1,0,1]
	v_readlane_b32 s0, v139, 56
	v_mul_f32_e32 v154, 0x3fb8aa3b, v154
	v_exp_f32_e32 v154, v154
	v_pk_fma_f32 v[10:11], v[10:11], s[0:1], v[14:15] op_sel_hi:[1,0,1]
	v_pk_fma_f32 v[8:9], v[8:9], s[0:1], v[12:13] op_sel_hi:[1,0,1]
	v_readlane_b32 s0, v140, 0
	v_mul_f32_e32 v155, 0x3fb8aa3b, v155
	v_exp_f32_e32 v155, v155
	v_pk_fma_f32 v[12:13], v[4:5], s[0:1], v[18:19] op_sel_hi:[1,0,1]
	v_pk_fma_f32 v[14:15], v[6:7], s[0:1], v[16:17] op_sel_hi:[1,0,1]
	v_readlane_b32 s0, v140, 8
	v_fma_f32 v156, v167, s28, -v134
	v_mul_f32_e32 v156, 0x3fb8aa3b, v156
	v_pk_fma_f32 v[16:17], v[4:5], s[0:1], v[22:23] op_sel_hi:[1,0,1]
	v_pk_fma_f32 v[18:19], v[6:7], s[0:1], v[20:21] op_sel_hi:[1,0,1]
	v_readlane_b32 s0, v140, 16
	v_exp_f32_e32 v156, v156
	v_mul_f32_e32 v158, 0x3fb8aa3b, v158
	v_pk_fma_f32 v[20:21], v[4:5], s[0:1], v[26:27] op_sel_hi:[1,0,1]
	v_pk_fma_f32 v[22:23], v[6:7], s[0:1], v[24:25] op_sel_hi:[1,0,1]
	v_readlane_b32 s0, v140, 24
	v_exp_f32_e32 v158, v158
	v_mul_f32_e32 v159, 0x3fb8aa3b, v159
	v_pk_fma_f32 v[24:25], v[4:5], s[0:1], v[30:31] op_sel_hi:[1,0,1]
	v_pk_fma_f32 v[26:27], v[6:7], s[0:1], v[28:29] op_sel_hi:[1,0,1]
	v_readlane_b32 s0, v140, 32
	v_exp_f32_e32 v159, v159
	v_mul_f32_e32 v160, 0x3fb8aa3b, v160
	v_pk_fma_f32 v[28:29], v[4:5], s[0:1], v[170:171] op_sel_hi:[1,0,1]
	v_pk_fma_f32 v[30:31], v[6:7], s[0:1], v[168:169] op_sel_hi:[1,0,1]
	v_readlane_b32 s0, v140, 40
	v_exp_f32_e32 v160, v160
	v_mul_f32_e32 v161, 0x3fb8aa3b, v161
	v_pk_fma_f32 v[168:169], v[4:5], s[0:1], v[174:175] op_sel_hi:[1,0,1]
	v_pk_fma_f32 v[170:171], v[6:7], s[0:1], v[172:173] op_sel_hi:[1,0,1]
	v_readlane_b32 s0, v140, 48
	v_exp_f32_e32 v161, v161
	v_mul_f32_e32 v162, 0x3fb8aa3b, v162
	v_pk_fma_f32 v[172:173], v[4:5], s[0:1], v[178:179] op_sel_hi:[1,0,1]
	v_pk_fma_f32 v[174:175], v[6:7], s[0:1], v[176:177] op_sel_hi:[1,0,1]
	v_readlane_b32 s0, v140, 56
	v_exp_f32_e32 v162, v162
	v_mul_f32_e32 v163, 0x3fb8aa3b, v163
	v_pk_fma_f32 v[4:5], v[4:5], s[0:1], v[8:9] op_sel_hi:[1,0,1]
	v_pk_fma_f32 v[6:7], v[6:7], s[0:1], v[10:11] op_sel_hi:[1,0,1]
	v_readlane_b32 s0, v141, 0
	v_exp_f32_e32 v163, v163
	v_mul_f32_e32 v164, 0x3fb8aa3b, v164
	v_pk_fma_f32 v[8:9], v[2:3], s[0:1], v[14:15] op_sel_hi:[1,0,1]
	v_pk_fma_f32 v[10:11], v[0:1], s[0:1], v[12:13] op_sel_hi:[1,0,1]
	v_readlane_b32 s0, v141, 8
	v_exp_f32_e32 v164, v164
	v_fma_f32 v165, v215, s28, -v134
	v_pk_fma_f32 v[12:13], v[2:3], s[0:1], v[18:19] op_sel_hi:[1,0,1]
	v_pk_fma_f32 v[14:15], v[0:1], s[0:1], v[16:17] op_sel_hi:[1,0,1]
	v_readlane_b32 s0, v141, 16
	v_mul_f32_e32 v165, 0x3fb8aa3b, v165
	v_exp_f32_e32 v165, v165
	v_pk_fma_f32 v[16:17], v[2:3], s[0:1], v[22:23] op_sel_hi:[1,0,1]
	v_pk_fma_f32 v[18:19], v[0:1], s[0:1], v[20:21] op_sel_hi:[1,0,1]
	v_readlane_b32 s0, v141, 24
	v_mul_f32_e32 v166, 0x3fb8aa3b, v166
	v_exp_f32_e32 v166, v166
	v_pk_fma_f32 v[20:21], v[2:3], s[0:1], v[26:27] op_sel_hi:[1,0,1]
	v_pk_fma_f32 v[22:23], v[0:1], s[0:1], v[24:25] op_sel_hi:[1,0,1]
	v_readlane_b32 s0, v141, 32
	s_nop 1
	v_pk_fma_f32 v[24:25], v[2:3], s[0:1], v[30:31] op_sel_hi:[1,0,1]
	v_pk_fma_f32 v[26:27], v[0:1], s[0:1], v[28:29] op_sel_hi:[1,0,1]
	v_readlane_b32 s0, v141, 40
	s_nop 1
	v_pk_fma_f32 v[28:29], v[2:3], s[0:1], v[170:171] op_sel_hi:[1,0,1]
	v_pk_fma_f32 v[30:31], v[0:1], s[0:1], v[168:169] op_sel_hi:[1,0,1]
	v_readlane_b32 s0, v141, 48
	s_nop 1
	v_pk_fma_f32 v[168:169], v[2:3], s[0:1], v[174:175] op_sel_hi:[1,0,1]
	v_pk_fma_f32 v[170:171], v[0:1], s[0:1], v[172:173] op_sel_hi:[1,0,1]
	v_readlane_b32 s0, v141, 56
	s_nop 1
	v_pk_fma_f32 v[2:3], v[2:3], s[0:1], v[6:7] op_sel_hi:[1,0,1]
	v_pk_fma_f32 v[0:1], v[0:1], s[0:1], v[4:5] op_sel_hi:[1,0,1]
	v_readlane_b32 s0, v142, 0
	s_nop 1
	v_pk_fma_f32 v[4:5], v[60:61], s[0:1], v[10:11] op_sel_hi:[1,0,1]
	v_pk_fma_f32 v[6:7], v[62:63], s[0:1], v[8:9] op_sel_hi:[1,0,1]
	v_readlane_b32 s0, v142, 8
	s_nop 1
	v_pk_fma_f32 v[8:9], v[60:61], s[0:1], v[14:15] op_sel_hi:[1,0,1]
	v_pk_fma_f32 v[10:11], v[62:63], s[0:1], v[12:13] op_sel_hi:[1,0,1]
	v_readlane_b32 s0, v142, 16
	s_nop 1
	v_pk_fma_f32 v[12:13], v[60:61], s[0:1], v[18:19] op_sel_hi:[1,0,1]
	v_pk_fma_f32 v[14:15], v[62:63], s[0:1], v[16:17] op_sel_hi:[1,0,1]
	v_readlane_b32 s0, v142, 24
	s_nop 1
	v_pk_fma_f32 v[16:17], v[60:61], s[0:1], v[22:23] op_sel_hi:[1,0,1]
	v_pk_fma_f32 v[18:19], v[62:63], s[0:1], v[20:21] op_sel_hi:[1,0,1]
	v_readlane_b32 s0, v142, 32
	s_nop 1
	v_pk_fma_f32 v[20:21], v[60:61], s[0:1], v[26:27] op_sel_hi:[1,0,1]
	v_pk_fma_f32 v[22:23], v[62:63], s[0:1], v[24:25] op_sel_hi:[1,0,1]
	v_readlane_b32 s0, v142, 40
	s_nop 1
	v_pk_fma_f32 v[24:25], v[60:61], s[0:1], v[30:31] op_sel_hi:[1,0,1]
	v_pk_fma_f32 v[26:27], v[62:63], s[0:1], v[28:29] op_sel_hi:[1,0,1]
	v_readlane_b32 s0, v142, 48
	s_nop 1
	v_pk_fma_f32 v[28:29], v[60:61], s[0:1], v[170:171] op_sel_hi:[1,0,1]
	v_pk_fma_f32 v[30:31], v[62:63], s[0:1], v[168:169] op_sel_hi:[1,0,1]
	v_readlane_b32 s0, v142, 56
	s_nop 1
	v_pk_fma_f32 v[0:1], v[60:61], s[0:1], v[0:1] op_sel_hi:[1,0,1]
	v_pk_fma_f32 v[2:3], v[62:63], s[0:1], v[2:3] op_sel_hi:[1,0,1]
	v_readlane_b32 s0, v143, 0
	s_nop 1
	v_pk_fma_f32 v[6:7], v[58:59], s[0:1], v[6:7] op_sel_hi:[1,0,1]
	v_pk_fma_f32 v[4:5], v[56:57], s[0:1], v[4:5] op_sel_hi:[1,0,1]
	v_readlane_b32 s0, v143, 8
	s_nop 1
	v_pk_fma_f32 v[10:11], v[58:59], s[0:1], v[10:11] op_sel_hi:[1,0,1]
	v_pk_fma_f32 v[8:9], v[56:57], s[0:1], v[8:9] op_sel_hi:[1,0,1]
	v_readlane_b32 s0, v143, 16
	s_nop 1
	v_pk_fma_f32 v[14:15], v[58:59], s[0:1], v[14:15] op_sel_hi:[1,0,1]
	v_pk_fma_f32 v[12:13], v[56:57], s[0:1], v[12:13] op_sel_hi:[1,0,1]
	v_readlane_b32 s0, v143, 24
	s_nop 1
	v_pk_fma_f32 v[18:19], v[58:59], s[0:1], v[18:19] op_sel_hi:[1,0,1]
	v_pk_fma_f32 v[16:17], v[56:57], s[0:1], v[16:17] op_sel_hi:[1,0,1]
	v_readlane_b32 s0, v143, 32
	s_nop 1
	v_pk_fma_f32 v[22:23], v[58:59], s[0:1], v[22:23] op_sel_hi:[1,0,1]
	v_pk_fma_f32 v[20:21], v[56:57], s[0:1], v[20:21] op_sel_hi:[1,0,1]
	v_readlane_b32 s0, v143, 40
	s_nop 1
	v_pk_fma_f32 v[26:27], v[58:59], s[0:1], v[26:27] op_sel_hi:[1,0,1]
	v_pk_fma_f32 v[24:25], v[56:57], s[0:1], v[24:25] op_sel_hi:[1,0,1]
	v_readlane_b32 s0, v143, 48
	s_nop 1
	v_pk_fma_f32 v[30:31], v[58:59], s[0:1], v[30:31] op_sel_hi:[1,0,1]
	v_pk_fma_f32 v[28:29], v[56:57], s[0:1], v[28:29] op_sel_hi:[1,0,1]
	v_readlane_b32 s0, v143, 56
	s_nop 1
	v_pk_fma_f32 v[2:3], v[58:59], s[0:1], v[2:3] op_sel_hi:[1,0,1]
	v_pk_fma_f32 v[0:1], v[56:57], s[0:1], v[0:1] op_sel_hi:[1,0,1]
	v_readlane_b32 s0, v144, 0
	s_nop 1
	v_pk_fma_f32 v[4:5], v[52:53], s[0:1], v[4:5] op_sel_hi:[1,0,1]
	v_pk_fma_f32 v[6:7], v[54:55], s[0:1], v[6:7] op_sel_hi:[1,0,1]
	v_readlane_b32 s0, v144, 8
	s_nop 1
	v_pk_fma_f32 v[8:9], v[52:53], s[0:1], v[8:9] op_sel_hi:[1,0,1]
	v_pk_fma_f32 v[10:11], v[54:55], s[0:1], v[10:11] op_sel_hi:[1,0,1]
	v_readlane_b32 s0, v144, 16
	s_nop 1
	v_pk_fma_f32 v[12:13], v[52:53], s[0:1], v[12:13] op_sel_hi:[1,0,1]
	v_pk_fma_f32 v[14:15], v[54:55], s[0:1], v[14:15] op_sel_hi:[1,0,1]
	v_readlane_b32 s0, v144, 24
	s_nop 1
	v_pk_fma_f32 v[16:17], v[52:53], s[0:1], v[16:17] op_sel_hi:[1,0,1]
	v_pk_fma_f32 v[18:19], v[54:55], s[0:1], v[18:19] op_sel_hi:[1,0,1]
	v_readlane_b32 s0, v144, 32
	s_nop 1
	v_pk_fma_f32 v[20:21], v[52:53], s[0:1], v[20:21] op_sel_hi:[1,0,1]
	v_pk_fma_f32 v[22:23], v[54:55], s[0:1], v[22:23] op_sel_hi:[1,0,1]
	v_readlane_b32 s0, v144, 40
	s_nop 1
	v_pk_fma_f32 v[24:25], v[52:53], s[0:1], v[24:25] op_sel_hi:[1,0,1]
	v_pk_fma_f32 v[26:27], v[54:55], s[0:1], v[26:27] op_sel_hi:[1,0,1]
	v_readlane_b32 s0, v144, 48
	s_nop 1
	v_pk_fma_f32 v[28:29], v[52:53], s[0:1], v[28:29] op_sel_hi:[1,0,1]
	v_pk_fma_f32 v[30:31], v[54:55], s[0:1], v[30:31] op_sel_hi:[1,0,1]
	v_readlane_b32 s0, v144, 56
	s_nop 1
	v_pk_fma_f32 v[0:1], v[52:53], s[0:1], v[0:1] op_sel_hi:[1,0,1]
	v_pk_fma_f32 v[2:3], v[54:55], s[0:1], v[2:3] op_sel_hi:[1,0,1]
	v_readlane_b32 s0, v145, 0
	s_nop 1
	v_pk_fma_f32 v[6:7], v[50:51], s[0:1], v[6:7] op_sel_hi:[1,0,1]
	v_pk_fma_f32 v[4:5], v[48:49], s[0:1], v[4:5] op_sel_hi:[1,0,1]
	v_readlane_b32 s0, v145, 8
	s_nop 1
	v_pk_fma_f32 v[10:11], v[50:51], s[0:1], v[10:11] op_sel_hi:[1,0,1]
	v_pk_fma_f32 v[8:9], v[48:49], s[0:1], v[8:9] op_sel_hi:[1,0,1]
	v_readlane_b32 s0, v145, 16
	s_nop 1
	v_pk_fma_f32 v[14:15], v[50:51], s[0:1], v[14:15] op_sel_hi:[1,0,1]
	v_pk_fma_f32 v[12:13], v[48:49], s[0:1], v[12:13] op_sel_hi:[1,0,1]
	v_readlane_b32 s0, v145, 24
	s_nop 1
	v_pk_fma_f32 v[18:19], v[50:51], s[0:1], v[18:19] op_sel_hi:[1,0,1]
	v_pk_fma_f32 v[16:17], v[48:49], s[0:1], v[16:17] op_sel_hi:[1,0,1]
	v_readlane_b32 s0, v145, 32
	s_nop 1
	v_pk_fma_f32 v[22:23], v[50:51], s[0:1], v[22:23] op_sel_hi:[1,0,1]
	v_pk_fma_f32 v[20:21], v[48:49], s[0:1], v[20:21] op_sel_hi:[1,0,1]
	v_readlane_b32 s0, v145, 40
	s_nop 1
	v_pk_fma_f32 v[26:27], v[50:51], s[0:1], v[26:27] op_sel_hi:[1,0,1]
	v_pk_fma_f32 v[24:25], v[48:49], s[0:1], v[24:25] op_sel_hi:[1,0,1]
	v_readlane_b32 s0, v145, 48
	s_nop 1
	v_pk_fma_f32 v[30:31], v[50:51], s[0:1], v[30:31] op_sel_hi:[1,0,1]
	v_pk_fma_f32 v[28:29], v[48:49], s[0:1], v[28:29] op_sel_hi:[1,0,1]
	v_readlane_b32 s0, v145, 56
	s_nop 1
	v_pk_fma_f32 v[2:3], v[50:51], s[0:1], v[2:3] op_sel_hi:[1,0,1]
	v_pk_fma_f32 v[0:1], v[48:49], s[0:1], v[0:1] op_sel_hi:[1,0,1]
	v_readlane_b32 s0, v146, 0
	s_nop 1
	v_pk_fma_f32 v[4:5], v[44:45], s[0:1], v[4:5] op_sel_hi:[1,0,1]
	v_pk_fma_f32 v[6:7], v[46:47], s[0:1], v[6:7] op_sel_hi:[1,0,1]
	v_readlane_b32 s0, v146, 8
	s_nop 1
	v_pk_fma_f32 v[8:9], v[44:45], s[0:1], v[8:9] op_sel_hi:[1,0,1]
	v_pk_fma_f32 v[10:11], v[46:47], s[0:1], v[10:11] op_sel_hi:[1,0,1]
	v_readlane_b32 s0, v146, 16
	s_nop 1
	v_pk_fma_f32 v[12:13], v[44:45], s[0:1], v[12:13] op_sel_hi:[1,0,1]
	v_pk_fma_f32 v[14:15], v[46:47], s[0:1], v[14:15] op_sel_hi:[1,0,1]
	v_readlane_b32 s0, v146, 24
	s_nop 1
	v_pk_fma_f32 v[16:17], v[44:45], s[0:1], v[16:17] op_sel_hi:[1,0,1]
	v_pk_fma_f32 v[18:19], v[46:47], s[0:1], v[18:19] op_sel_hi:[1,0,1]
	v_readlane_b32 s0, v146, 32
	s_nop 1
	v_pk_fma_f32 v[20:21], v[44:45], s[0:1], v[20:21] op_sel_hi:[1,0,1]
	v_pk_fma_f32 v[22:23], v[46:47], s[0:1], v[22:23] op_sel_hi:[1,0,1]
	v_readlane_b32 s0, v146, 40
	s_nop 1
	v_pk_fma_f32 v[24:25], v[44:45], s[0:1], v[24:25] op_sel_hi:[1,0,1]
	v_pk_fma_f32 v[26:27], v[46:47], s[0:1], v[26:27] op_sel_hi:[1,0,1]
	v_readlane_b32 s0, v146, 48
	s_nop 1
	v_pk_fma_f32 v[28:29], v[44:45], s[0:1], v[28:29] op_sel_hi:[1,0,1]
	v_pk_fma_f32 v[30:31], v[46:47], s[0:1], v[30:31] op_sel_hi:[1,0,1]
	v_readlane_b32 s0, v146, 56
	s_nop 1
	v_pk_fma_f32 v[0:1], v[44:45], s[0:1], v[0:1] op_sel_hi:[1,0,1]
	v_pk_fma_f32 v[2:3], v[46:47], s[0:1], v[2:3] op_sel_hi:[1,0,1]
	v_readlane_b32 s0, v147, 0
	s_nop 1
	v_pk_fma_f32 v[6:7], v[42:43], s[0:1], v[6:7] op_sel_hi:[1,0,1]
	v_pk_fma_f32 v[4:5], v[40:41], s[0:1], v[4:5] op_sel_hi:[1,0,1]
	v_readlane_b32 s0, v147, 8
	s_nop 1
	v_pk_fma_f32 v[10:11], v[42:43], s[0:1], v[10:11] op_sel_hi:[1,0,1]
	v_pk_fma_f32 v[8:9], v[40:41], s[0:1], v[8:9] op_sel_hi:[1,0,1]
	v_readlane_b32 s0, v147, 16
	s_nop 1
	v_pk_fma_f32 v[14:15], v[42:43], s[0:1], v[14:15] op_sel_hi:[1,0,1]
	v_pk_fma_f32 v[12:13], v[40:41], s[0:1], v[12:13] op_sel_hi:[1,0,1]
	v_readlane_b32 s0, v147, 24
	s_nop 1
	v_pk_fma_f32 v[18:19], v[42:43], s[0:1], v[18:19] op_sel_hi:[1,0,1]
	v_pk_fma_f32 v[16:17], v[40:41], s[0:1], v[16:17] op_sel_hi:[1,0,1]
	v_readlane_b32 s0, v147, 32
	s_nop 1
	v_pk_fma_f32 v[22:23], v[42:43], s[0:1], v[22:23] op_sel_hi:[1,0,1]
	v_pk_fma_f32 v[20:21], v[40:41], s[0:1], v[20:21] op_sel_hi:[1,0,1]
	v_readlane_b32 s0, v147, 40
	s_nop 1
	v_pk_fma_f32 v[26:27], v[42:43], s[0:1], v[26:27] op_sel_hi:[1,0,1]
	v_pk_fma_f32 v[24:25], v[40:41], s[0:1], v[24:25] op_sel_hi:[1,0,1]
	v_readlane_b32 s0, v147, 48
	s_nop 1
	v_pk_fma_f32 v[30:31], v[42:43], s[0:1], v[30:31] op_sel_hi:[1,0,1]
	v_pk_fma_f32 v[28:29], v[40:41], s[0:1], v[28:29] op_sel_hi:[1,0,1]
	v_readlane_b32 s0, v147, 56
	s_nop 1
	v_pk_fma_f32 v[2:3], v[42:43], s[0:1], v[2:3] op_sel_hi:[1,0,1]
	v_pk_fma_f32 v[0:1], v[40:41], s[0:1], v[0:1] op_sel_hi:[1,0,1]
	v_readlane_b32 s0, v148, 0
	s_nop 1
	v_pk_fma_f32 v[4:5], v[36:37], s[0:1], v[4:5] op_sel_hi:[1,0,1]
	v_pk_fma_f32 v[6:7], v[38:39], s[0:1], v[6:7] op_sel_hi:[1,0,1]
	v_readlane_b32 s0, v148, 8
	s_nop 1
	v_pk_fma_f32 v[8:9], v[36:37], s[0:1], v[8:9] op_sel_hi:[1,0,1]
	v_pk_fma_f32 v[10:11], v[38:39], s[0:1], v[10:11] op_sel_hi:[1,0,1]
	v_readlane_b32 s0, v148, 16
	s_nop 1
	v_pk_fma_f32 v[12:13], v[36:37], s[0:1], v[12:13] op_sel_hi:[1,0,1]
	v_pk_fma_f32 v[14:15], v[38:39], s[0:1], v[14:15] op_sel_hi:[1,0,1]
	v_readlane_b32 s0, v148, 24
	s_nop 1
	v_pk_fma_f32 v[16:17], v[36:37], s[0:1], v[16:17] op_sel_hi:[1,0,1]
	v_pk_fma_f32 v[18:19], v[38:39], s[0:1], v[18:19] op_sel_hi:[1,0,1]
	v_readlane_b32 s0, v148, 32
	s_nop 1
	v_pk_fma_f32 v[20:21], v[36:37], s[0:1], v[20:21] op_sel_hi:[1,0,1]
	v_pk_fma_f32 v[22:23], v[38:39], s[0:1], v[22:23] op_sel_hi:[1,0,1]
	v_readlane_b32 s0, v148, 40
	s_nop 1
	v_pk_fma_f32 v[24:25], v[36:37], s[0:1], v[24:25] op_sel_hi:[1,0,1]
	v_pk_fma_f32 v[26:27], v[38:39], s[0:1], v[26:27] op_sel_hi:[1,0,1]
	v_readlane_b32 s0, v148, 48
	s_nop 1
	v_pk_fma_f32 v[28:29], v[36:37], s[0:1], v[28:29] op_sel_hi:[1,0,1]
	v_pk_fma_f32 v[30:31], v[38:39], s[0:1], v[30:31] op_sel_hi:[1,0,1]
	v_readlane_b32 s0, v148, 56
	s_nop 1
	v_pk_fma_f32 v[0:1], v[36:37], s[0:1], v[0:1] op_sel_hi:[1,0,1]
	v_pk_fma_f32 v[2:3], v[38:39], s[0:1], v[2:3] op_sel_hi:[1,0,1]
	v_readlane_b32 s0, v149, 0
	s_nop 1
	v_pk_fma_f32 v[6:7], v[34:35], s[0:1], v[6:7] op_sel_hi:[1,0,1]
	v_pk_fma_f32 v[4:5], v[32:33], s[0:1], v[4:5] op_sel_hi:[1,0,1]
	v_readlane_b32 s0, v149, 8
	s_nop 1
	v_pk_fma_f32 v[10:11], v[34:35], s[0:1], v[10:11] op_sel_hi:[1,0,1]
	v_pk_fma_f32 v[8:9], v[32:33], s[0:1], v[8:9] op_sel_hi:[1,0,1]
	v_readlane_b32 s0, v149, 16
	s_nop 1
	v_pk_fma_f32 v[14:15], v[34:35], s[0:1], v[14:15] op_sel_hi:[1,0,1]
	v_pk_fma_f32 v[12:13], v[32:33], s[0:1], v[12:13] op_sel_hi:[1,0,1]
	v_readlane_b32 s0, v149, 24
	s_nop 1
	v_pk_fma_f32 v[18:19], v[34:35], s[0:1], v[18:19] op_sel_hi:[1,0,1]
	v_pk_fma_f32 v[16:17], v[32:33], s[0:1], v[16:17] op_sel_hi:[1,0,1]
	v_readlane_b32 s0, v149, 32
	s_nop 1
	v_pk_fma_f32 v[22:23], v[34:35], s[0:1], v[22:23] op_sel_hi:[1,0,1]
	v_pk_fma_f32 v[20:21], v[32:33], s[0:1], v[20:21] op_sel_hi:[1,0,1]
	v_readlane_b32 s0, v149, 40
	s_nop 1
	v_pk_fma_f32 v[26:27], v[34:35], s[0:1], v[26:27] op_sel_hi:[1,0,1]
	v_pk_fma_f32 v[24:25], v[32:33], s[0:1], v[24:25] op_sel_hi:[1,0,1]
	v_readlane_b32 s0, v149, 48
	s_nop 1
	v_pk_fma_f32 v[30:31], v[34:35], s[0:1], v[30:31] op_sel_hi:[1,0,1]
	v_pk_fma_f32 v[28:29], v[32:33], s[0:1], v[28:29] op_sel_hi:[1,0,1]
	v_readlane_b32 s0, v149, 56
	s_nop 1
	v_pk_fma_f32 v[2:3], v[34:35], s[0:1], v[2:3] op_sel_hi:[1,0,1]
	v_pk_fma_f32 v[0:1], v[32:33], s[0:1], v[0:1] op_sel_hi:[1,0,1]
	v_readlane_b32 s0, v150, 0
	s_waitcnt vmcnt(1)
	s_nop 0
	v_pk_fma_f32 v[4:5], v[124:125], s[0:1], v[4:5] op_sel_hi:[1,0,1]
	v_pk_fma_f32 v[6:7], v[126:127], s[0:1], v[6:7] op_sel_hi:[1,0,1]
	v_readlane_b32 s0, v150, 8
	s_nop 1
	v_pk_fma_f32 v[8:9], v[124:125], s[0:1], v[8:9] op_sel_hi:[1,0,1]
	v_pk_fma_f32 v[10:11], v[126:127], s[0:1], v[10:11] op_sel_hi:[1,0,1]
	v_readlane_b32 s0, v150, 16
	s_nop 1
	v_pk_fma_f32 v[12:13], v[124:125], s[0:1], v[12:13] op_sel_hi:[1,0,1]
	v_pk_fma_f32 v[14:15], v[126:127], s[0:1], v[14:15] op_sel_hi:[1,0,1]
	v_readlane_b32 s0, v150, 24
	s_nop 1
	v_pk_fma_f32 v[16:17], v[124:125], s[0:1], v[16:17] op_sel_hi:[1,0,1]
	v_pk_fma_f32 v[18:19], v[126:127], s[0:1], v[18:19] op_sel_hi:[1,0,1]
	v_readlane_b32 s0, v150, 32
	s_nop 1
	v_pk_fma_f32 v[20:21], v[124:125], s[0:1], v[20:21] op_sel_hi:[1,0,1]
	v_pk_fma_f32 v[22:23], v[126:127], s[0:1], v[22:23] op_sel_hi:[1,0,1]
	v_readlane_b32 s0, v150, 40
	s_nop 1
	v_pk_fma_f32 v[24:25], v[124:125], s[0:1], v[24:25] op_sel_hi:[1,0,1]
	v_pk_fma_f32 v[26:27], v[126:127], s[0:1], v[26:27] op_sel_hi:[1,0,1]
	v_readlane_b32 s0, v150, 48
	s_nop 1
	v_pk_fma_f32 v[28:29], v[124:125], s[0:1], v[28:29] op_sel_hi:[1,0,1]
	v_pk_fma_f32 v[30:31], v[126:127], s[0:1], v[30:31] op_sel_hi:[1,0,1]
	v_readlane_b32 s0, v150, 56
	s_nop 1
	v_pk_fma_f32 v[0:1], v[124:125], s[0:1], v[0:1] op_sel_hi:[1,0,1]
	v_pk_fma_f32 v[2:3], v[126:127], s[0:1], v[2:3] op_sel_hi:[1,0,1]
	v_readlane_b32 s0, v151, 0
	s_nop 1
	v_pk_fma_f32 v[6:7], v[122:123], s[0:1], v[6:7] op_sel_hi:[1,0,1]
	v_pk_fma_f32 v[4:5], v[120:121], s[0:1], v[4:5] op_sel_hi:[1,0,1]
	v_readlane_b32 s0, v151, 8
	s_nop 1
	v_pk_fma_f32 v[10:11], v[122:123], s[0:1], v[10:11] op_sel_hi:[1,0,1]
	v_pk_fma_f32 v[8:9], v[120:121], s[0:1], v[8:9] op_sel_hi:[1,0,1]
	v_readlane_b32 s0, v151, 16
	s_nop 1
	v_pk_fma_f32 v[14:15], v[122:123], s[0:1], v[14:15] op_sel_hi:[1,0,1]
	v_pk_fma_f32 v[12:13], v[120:121], s[0:1], v[12:13] op_sel_hi:[1,0,1]
	v_readlane_b32 s0, v151, 24
	s_nop 1
	v_pk_fma_f32 v[18:19], v[122:123], s[0:1], v[18:19] op_sel_hi:[1,0,1]
	v_pk_fma_f32 v[16:17], v[120:121], s[0:1], v[16:17] op_sel_hi:[1,0,1]
	v_readlane_b32 s0, v151, 32
	s_nop 1
	v_pk_fma_f32 v[22:23], v[122:123], s[0:1], v[22:23] op_sel_hi:[1,0,1]
	v_pk_fma_f32 v[20:21], v[120:121], s[0:1], v[20:21] op_sel_hi:[1,0,1]
	v_readlane_b32 s0, v151, 40
	s_nop 1
	v_pk_fma_f32 v[26:27], v[122:123], s[0:1], v[26:27] op_sel_hi:[1,0,1]
	v_pk_fma_f32 v[24:25], v[120:121], s[0:1], v[24:25] op_sel_hi:[1,0,1]
	v_readlane_b32 s0, v151, 48
	s_nop 1
	v_pk_fma_f32 v[30:31], v[122:123], s[0:1], v[30:31] op_sel_hi:[1,0,1]
	v_pk_fma_f32 v[28:29], v[120:121], s[0:1], v[28:29] op_sel_hi:[1,0,1]
	v_readlane_b32 s0, v151, 56
	s_nop 1
	v_pk_fma_f32 v[2:3], v[122:123], s[0:1], v[2:3] op_sel_hi:[1,0,1]
	v_pk_fma_f32 v[0:1], v[120:121], s[0:1], v[0:1] op_sel_hi:[1,0,1]
	v_readlane_b32 s0, v152, 0
	s_nop 1
	v_pk_fma_f32 v[4:5], v[116:117], s[0:1], v[4:5] op_sel_hi:[1,0,1]
	v_pk_fma_f32 v[6:7], v[118:119], s[0:1], v[6:7] op_sel_hi:[1,0,1]
	v_readlane_b32 s0, v152, 8
	s_nop 1
	v_pk_fma_f32 v[8:9], v[116:117], s[0:1], v[8:9] op_sel_hi:[1,0,1]
	v_pk_fma_f32 v[10:11], v[118:119], s[0:1], v[10:11] op_sel_hi:[1,0,1]
	v_readlane_b32 s0, v152, 16
	s_nop 1
	v_pk_fma_f32 v[12:13], v[116:117], s[0:1], v[12:13] op_sel_hi:[1,0,1]
	v_pk_fma_f32 v[14:15], v[118:119], s[0:1], v[14:15] op_sel_hi:[1,0,1]
	v_readlane_b32 s0, v152, 24
	s_nop 1
	v_pk_fma_f32 v[16:17], v[116:117], s[0:1], v[16:17] op_sel_hi:[1,0,1]
	v_pk_fma_f32 v[18:19], v[118:119], s[0:1], v[18:19] op_sel_hi:[1,0,1]
	v_readlane_b32 s0, v152, 32
	s_nop 1
	v_pk_fma_f32 v[20:21], v[116:117], s[0:1], v[20:21] op_sel_hi:[1,0,1]
	v_pk_fma_f32 v[22:23], v[118:119], s[0:1], v[22:23] op_sel_hi:[1,0,1]
	v_readlane_b32 s0, v152, 40
	s_nop 1
	v_pk_fma_f32 v[24:25], v[116:117], s[0:1], v[24:25] op_sel_hi:[1,0,1]
	v_pk_fma_f32 v[26:27], v[118:119], s[0:1], v[26:27] op_sel_hi:[1,0,1]
	v_readlane_b32 s0, v152, 48
	s_nop 1
	v_pk_fma_f32 v[28:29], v[116:117], s[0:1], v[28:29] op_sel_hi:[1,0,1]
	v_pk_fma_f32 v[30:31], v[118:119], s[0:1], v[30:31] op_sel_hi:[1,0,1]
	v_readlane_b32 s0, v152, 56
	s_nop 1
	v_pk_fma_f32 v[0:1], v[116:117], s[0:1], v[0:1] op_sel_hi:[1,0,1]
	v_pk_fma_f32 v[2:3], v[118:119], s[0:1], v[2:3] op_sel_hi:[1,0,1]
	v_readlane_b32 s0, v153, 0
	s_nop 1
	v_pk_fma_f32 v[6:7], v[114:115], s[0:1], v[6:7] op_sel_hi:[1,0,1]
	v_pk_fma_f32 v[4:5], v[112:113], s[0:1], v[4:5] op_sel_hi:[1,0,1]
	v_readlane_b32 s0, v153, 8
	s_nop 1
	v_pk_fma_f32 v[10:11], v[114:115], s[0:1], v[10:11] op_sel_hi:[1,0,1]
	v_pk_fma_f32 v[8:9], v[112:113], s[0:1], v[8:9] op_sel_hi:[1,0,1]
	v_readlane_b32 s0, v153, 16
	s_nop 1
	v_pk_fma_f32 v[14:15], v[114:115], s[0:1], v[14:15] op_sel_hi:[1,0,1]
	v_pk_fma_f32 v[12:13], v[112:113], s[0:1], v[12:13] op_sel_hi:[1,0,1]
	v_readlane_b32 s0, v153, 24
	s_nop 1
	v_pk_fma_f32 v[18:19], v[114:115], s[0:1], v[18:19] op_sel_hi:[1,0,1]
	v_pk_fma_f32 v[16:17], v[112:113], s[0:1], v[16:17] op_sel_hi:[1,0,1]
	v_readlane_b32 s0, v153, 32
	s_nop 1
	v_pk_fma_f32 v[22:23], v[114:115], s[0:1], v[22:23] op_sel_hi:[1,0,1]
	v_pk_fma_f32 v[20:21], v[112:113], s[0:1], v[20:21] op_sel_hi:[1,0,1]
	v_readlane_b32 s0, v153, 40
	s_nop 1
	v_pk_fma_f32 v[26:27], v[114:115], s[0:1], v[26:27] op_sel_hi:[1,0,1]
	v_pk_fma_f32 v[24:25], v[112:113], s[0:1], v[24:25] op_sel_hi:[1,0,1]
	v_readlane_b32 s0, v153, 48
	s_nop 1
	v_pk_fma_f32 v[30:31], v[114:115], s[0:1], v[30:31] op_sel_hi:[1,0,1]
	v_pk_fma_f32 v[28:29], v[112:113], s[0:1], v[28:29] op_sel_hi:[1,0,1]
	v_readlane_b32 s0, v153, 56
	s_nop 1
	v_pk_fma_f32 v[2:3], v[114:115], s[0:1], v[2:3] op_sel_hi:[1,0,1]
	v_pk_fma_f32 v[0:1], v[112:113], s[0:1], v[0:1] op_sel_hi:[1,0,1]
	v_readlane_b32 s0, v154, 0
	s_nop 1
	v_pk_fma_f32 v[4:5], v[108:109], s[0:1], v[4:5] op_sel_hi:[1,0,1]
	v_pk_fma_f32 v[6:7], v[110:111], s[0:1], v[6:7] op_sel_hi:[1,0,1]
	v_readlane_b32 s0, v154, 8
	s_nop 1
	v_pk_fma_f32 v[8:9], v[108:109], s[0:1], v[8:9] op_sel_hi:[1,0,1]
	v_pk_fma_f32 v[10:11], v[110:111], s[0:1], v[10:11] op_sel_hi:[1,0,1]
	v_readlane_b32 s0, v154, 16
	s_nop 1
	v_pk_fma_f32 v[12:13], v[108:109], s[0:1], v[12:13] op_sel_hi:[1,0,1]
	v_pk_fma_f32 v[14:15], v[110:111], s[0:1], v[14:15] op_sel_hi:[1,0,1]
	v_readlane_b32 s0, v154, 24
	s_nop 1
	v_pk_fma_f32 v[16:17], v[108:109], s[0:1], v[16:17] op_sel_hi:[1,0,1]
	v_pk_fma_f32 v[18:19], v[110:111], s[0:1], v[18:19] op_sel_hi:[1,0,1]
	v_readlane_b32 s0, v154, 32
	s_nop 1
	v_pk_fma_f32 v[20:21], v[108:109], s[0:1], v[20:21] op_sel_hi:[1,0,1]
	v_pk_fma_f32 v[22:23], v[110:111], s[0:1], v[22:23] op_sel_hi:[1,0,1]
	v_readlane_b32 s0, v154, 40
	s_nop 1
	v_pk_fma_f32 v[24:25], v[108:109], s[0:1], v[24:25] op_sel_hi:[1,0,1]
	v_pk_fma_f32 v[26:27], v[110:111], s[0:1], v[26:27] op_sel_hi:[1,0,1]
	v_readlane_b32 s0, v154, 48
	s_nop 1
	v_pk_fma_f32 v[28:29], v[108:109], s[0:1], v[28:29] op_sel_hi:[1,0,1]
	v_pk_fma_f32 v[30:31], v[110:111], s[0:1], v[30:31] op_sel_hi:[1,0,1]
	v_readlane_b32 s0, v154, 56
	s_nop 1
	v_pk_fma_f32 v[0:1], v[108:109], s[0:1], v[0:1] op_sel_hi:[1,0,1]
	v_pk_fma_f32 v[2:3], v[110:111], s[0:1], v[2:3] op_sel_hi:[1,0,1]
	v_readlane_b32 s0, v155, 0
	s_nop 1
	v_pk_fma_f32 v[6:7], v[106:107], s[0:1], v[6:7] op_sel_hi:[1,0,1]
	v_pk_fma_f32 v[4:5], v[104:105], s[0:1], v[4:5] op_sel_hi:[1,0,1]
	v_readlane_b32 s0, v155, 8
	s_nop 1
	v_pk_fma_f32 v[10:11], v[106:107], s[0:1], v[10:11] op_sel_hi:[1,0,1]
	v_pk_fma_f32 v[8:9], v[104:105], s[0:1], v[8:9] op_sel_hi:[1,0,1]
	v_readlane_b32 s0, v155, 16
	s_nop 1
	v_pk_fma_f32 v[14:15], v[106:107], s[0:1], v[14:15] op_sel_hi:[1,0,1]
	v_pk_fma_f32 v[12:13], v[104:105], s[0:1], v[12:13] op_sel_hi:[1,0,1]
	v_readlane_b32 s0, v155, 24
	s_nop 1
	v_pk_fma_f32 v[18:19], v[106:107], s[0:1], v[18:19] op_sel_hi:[1,0,1]
	v_pk_fma_f32 v[16:17], v[104:105], s[0:1], v[16:17] op_sel_hi:[1,0,1]
	v_readlane_b32 s0, v155, 32
	s_nop 1
	v_pk_fma_f32 v[22:23], v[106:107], s[0:1], v[22:23] op_sel_hi:[1,0,1]
	v_pk_fma_f32 v[20:21], v[104:105], s[0:1], v[20:21] op_sel_hi:[1,0,1]
	v_readlane_b32 s0, v155, 40
	s_nop 1
	v_pk_fma_f32 v[26:27], v[106:107], s[0:1], v[26:27] op_sel_hi:[1,0,1]
	v_pk_fma_f32 v[24:25], v[104:105], s[0:1], v[24:25] op_sel_hi:[1,0,1]
	v_readlane_b32 s0, v155, 48
	s_nop 1
	v_pk_fma_f32 v[30:31], v[106:107], s[0:1], v[30:31] op_sel_hi:[1,0,1]
	v_pk_fma_f32 v[28:29], v[104:105], s[0:1], v[28:29] op_sel_hi:[1,0,1]
	v_readlane_b32 s0, v155, 56
	s_nop 1
	v_pk_fma_f32 v[2:3], v[106:107], s[0:1], v[2:3] op_sel_hi:[1,0,1]
	v_pk_fma_f32 v[0:1], v[104:105], s[0:1], v[0:1] op_sel_hi:[1,0,1]
	v_readlane_b32 s0, v156, 0
	s_nop 1
	v_pk_fma_f32 v[4:5], v[100:101], s[0:1], v[4:5] op_sel_hi:[1,0,1]
	v_pk_fma_f32 v[6:7], v[102:103], s[0:1], v[6:7] op_sel_hi:[1,0,1]
	v_readlane_b32 s0, v156, 8
	s_nop 1
	v_pk_fma_f32 v[8:9], v[100:101], s[0:1], v[8:9] op_sel_hi:[1,0,1]
	v_pk_fma_f32 v[10:11], v[102:103], s[0:1], v[10:11] op_sel_hi:[1,0,1]
	v_readlane_b32 s0, v156, 16
	s_nop 1
	v_pk_fma_f32 v[12:13], v[100:101], s[0:1], v[12:13] op_sel_hi:[1,0,1]
	v_pk_fma_f32 v[14:15], v[102:103], s[0:1], v[14:15] op_sel_hi:[1,0,1]
	v_readlane_b32 s0, v156, 24
	s_nop 1
	v_pk_fma_f32 v[16:17], v[100:101], s[0:1], v[16:17] op_sel_hi:[1,0,1]
	v_pk_fma_f32 v[18:19], v[102:103], s[0:1], v[18:19] op_sel_hi:[1,0,1]
	v_readlane_b32 s0, v156, 32
	s_nop 1
	v_pk_fma_f32 v[20:21], v[100:101], s[0:1], v[20:21] op_sel_hi:[1,0,1]
	v_pk_fma_f32 v[22:23], v[102:103], s[0:1], v[22:23] op_sel_hi:[1,0,1]
	v_readlane_b32 s0, v156, 40
	s_nop 1
	v_pk_fma_f32 v[24:25], v[100:101], s[0:1], v[24:25] op_sel_hi:[1,0,1]
	v_pk_fma_f32 v[26:27], v[102:103], s[0:1], v[26:27] op_sel_hi:[1,0,1]
	v_readlane_b32 s0, v156, 48
	s_nop 1
	v_pk_fma_f32 v[28:29], v[100:101], s[0:1], v[28:29] op_sel_hi:[1,0,1]
	v_pk_fma_f32 v[30:31], v[102:103], s[0:1], v[30:31] op_sel_hi:[1,0,1]
	v_readlane_b32 s0, v156, 56
	s_nop 1
	v_pk_fma_f32 v[0:1], v[100:101], s[0:1], v[0:1] op_sel_hi:[1,0,1]
	v_pk_fma_f32 v[2:3], v[102:103], s[0:1], v[2:3] op_sel_hi:[1,0,1]
	v_readlane_b32 s0, v158, 0
	s_nop 1
	v_pk_fma_f32 v[6:7], v[98:99], s[0:1], v[6:7] op_sel_hi:[1,0,1]
	v_pk_fma_f32 v[4:5], v[96:97], s[0:1], v[4:5] op_sel_hi:[1,0,1]
	v_readlane_b32 s0, v158, 8
	s_nop 1
	v_pk_fma_f32 v[10:11], v[98:99], s[0:1], v[10:11] op_sel_hi:[1,0,1]
	v_pk_fma_f32 v[8:9], v[96:97], s[0:1], v[8:9] op_sel_hi:[1,0,1]
	v_readlane_b32 s0, v158, 16
	s_nop 1
	v_pk_fma_f32 v[14:15], v[98:99], s[0:1], v[14:15] op_sel_hi:[1,0,1]
	v_pk_fma_f32 v[12:13], v[96:97], s[0:1], v[12:13] op_sel_hi:[1,0,1]
	v_readlane_b32 s0, v158, 24
	s_nop 1
	v_pk_fma_f32 v[18:19], v[98:99], s[0:1], v[18:19] op_sel_hi:[1,0,1]
	v_pk_fma_f32 v[16:17], v[96:97], s[0:1], v[16:17] op_sel_hi:[1,0,1]
	v_readlane_b32 s0, v158, 32
	s_nop 1
	v_pk_fma_f32 v[22:23], v[98:99], s[0:1], v[22:23] op_sel_hi:[1,0,1]
	v_pk_fma_f32 v[20:21], v[96:97], s[0:1], v[20:21] op_sel_hi:[1,0,1]
	v_readlane_b32 s0, v158, 40
	s_nop 1
	v_pk_fma_f32 v[26:27], v[98:99], s[0:1], v[26:27] op_sel_hi:[1,0,1]
	v_pk_fma_f32 v[24:25], v[96:97], s[0:1], v[24:25] op_sel_hi:[1,0,1]
	v_readlane_b32 s0, v158, 48
	s_nop 1
	v_pk_fma_f32 v[30:31], v[98:99], s[0:1], v[30:31] op_sel_hi:[1,0,1]
	v_pk_fma_f32 v[28:29], v[96:97], s[0:1], v[28:29] op_sel_hi:[1,0,1]
	v_readlane_b32 s0, v158, 56
	s_nop 1
	v_pk_fma_f32 v[2:3], v[98:99], s[0:1], v[2:3] op_sel_hi:[1,0,1]
	v_pk_fma_f32 v[0:1], v[96:97], s[0:1], v[0:1] op_sel_hi:[1,0,1]
	v_readlane_b32 s0, v159, 0
	s_nop 1
	v_pk_fma_f32 v[4:5], v[92:93], s[0:1], v[4:5] op_sel_hi:[1,0,1]
	v_pk_fma_f32 v[6:7], v[94:95], s[0:1], v[6:7] op_sel_hi:[1,0,1]
	v_readlane_b32 s0, v159, 8
	s_nop 1
	v_pk_fma_f32 v[8:9], v[92:93], s[0:1], v[8:9] op_sel_hi:[1,0,1]
	v_pk_fma_f32 v[10:11], v[94:95], s[0:1], v[10:11] op_sel_hi:[1,0,1]
	v_readlane_b32 s0, v159, 16
	s_nop 1
	v_pk_fma_f32 v[12:13], v[92:93], s[0:1], v[12:13] op_sel_hi:[1,0,1]
	v_pk_fma_f32 v[14:15], v[94:95], s[0:1], v[14:15] op_sel_hi:[1,0,1]
	v_readlane_b32 s0, v159, 24
	s_nop 1
	v_pk_fma_f32 v[16:17], v[92:93], s[0:1], v[16:17] op_sel_hi:[1,0,1]
	v_pk_fma_f32 v[18:19], v[94:95], s[0:1], v[18:19] op_sel_hi:[1,0,1]
	v_readlane_b32 s0, v159, 32
	s_nop 1
	v_pk_fma_f32 v[20:21], v[92:93], s[0:1], v[20:21] op_sel_hi:[1,0,1]
	v_pk_fma_f32 v[22:23], v[94:95], s[0:1], v[22:23] op_sel_hi:[1,0,1]
	v_readlane_b32 s0, v159, 40
	s_nop 1
	v_pk_fma_f32 v[24:25], v[92:93], s[0:1], v[24:25] op_sel_hi:[1,0,1]
	v_pk_fma_f32 v[26:27], v[94:95], s[0:1], v[26:27] op_sel_hi:[1,0,1]
	v_readlane_b32 s0, v159, 48
	s_nop 1
	v_pk_fma_f32 v[28:29], v[92:93], s[0:1], v[28:29] op_sel_hi:[1,0,1]
	v_pk_fma_f32 v[30:31], v[94:95], s[0:1], v[30:31] op_sel_hi:[1,0,1]
	v_readlane_b32 s0, v159, 56
	s_nop 1
	v_pk_fma_f32 v[0:1], v[92:93], s[0:1], v[0:1] op_sel_hi:[1,0,1]
	v_pk_fma_f32 v[2:3], v[94:95], s[0:1], v[2:3] op_sel_hi:[1,0,1]
	v_readlane_b32 s0, v160, 0
	s_nop 1
	v_pk_fma_f32 v[6:7], v[90:91], s[0:1], v[6:7] op_sel_hi:[1,0,1]
	v_pk_fma_f32 v[4:5], v[88:89], s[0:1], v[4:5] op_sel_hi:[1,0,1]
	v_readlane_b32 s0, v160, 8
	s_nop 1
	v_pk_fma_f32 v[10:11], v[90:91], s[0:1], v[10:11] op_sel_hi:[1,0,1]
	v_pk_fma_f32 v[8:9], v[88:89], s[0:1], v[8:9] op_sel_hi:[1,0,1]
	v_readlane_b32 s0, v160, 16
	s_nop 1
	v_pk_fma_f32 v[14:15], v[90:91], s[0:1], v[14:15] op_sel_hi:[1,0,1]
	v_pk_fma_f32 v[12:13], v[88:89], s[0:1], v[12:13] op_sel_hi:[1,0,1]
	v_readlane_b32 s0, v160, 24
	s_nop 1
	v_pk_fma_f32 v[18:19], v[90:91], s[0:1], v[18:19] op_sel_hi:[1,0,1]
	v_pk_fma_f32 v[16:17], v[88:89], s[0:1], v[16:17] op_sel_hi:[1,0,1]
	v_readlane_b32 s0, v160, 32
	s_nop 1
	v_pk_fma_f32 v[22:23], v[90:91], s[0:1], v[22:23] op_sel_hi:[1,0,1]
	v_pk_fma_f32 v[20:21], v[88:89], s[0:1], v[20:21] op_sel_hi:[1,0,1]
	v_readlane_b32 s0, v160, 40
	s_nop 1
	v_pk_fma_f32 v[26:27], v[90:91], s[0:1], v[26:27] op_sel_hi:[1,0,1]
	v_pk_fma_f32 v[24:25], v[88:89], s[0:1], v[24:25] op_sel_hi:[1,0,1]
	v_readlane_b32 s0, v160, 48
	s_nop 1
	v_pk_fma_f32 v[30:31], v[90:91], s[0:1], v[30:31] op_sel_hi:[1,0,1]
	v_pk_fma_f32 v[28:29], v[88:89], s[0:1], v[28:29] op_sel_hi:[1,0,1]
	v_readlane_b32 s0, v160, 56
	s_nop 1
	v_pk_fma_f32 v[2:3], v[90:91], s[0:1], v[2:3] op_sel_hi:[1,0,1]
	v_pk_fma_f32 v[0:1], v[88:89], s[0:1], v[0:1] op_sel_hi:[1,0,1]
	v_readlane_b32 s0, v161, 0
	s_nop 1
	v_pk_fma_f32 v[4:5], v[84:85], s[0:1], v[4:5] op_sel_hi:[1,0,1]
	v_pk_fma_f32 v[6:7], v[86:87], s[0:1], v[6:7] op_sel_hi:[1,0,1]
	v_readlane_b32 s0, v161, 8
	s_nop 1
	v_pk_fma_f32 v[8:9], v[84:85], s[0:1], v[8:9] op_sel_hi:[1,0,1]
	v_pk_fma_f32 v[10:11], v[86:87], s[0:1], v[10:11] op_sel_hi:[1,0,1]
	v_readlane_b32 s0, v161, 16
	s_nop 1
	v_pk_fma_f32 v[12:13], v[84:85], s[0:1], v[12:13] op_sel_hi:[1,0,1]
	v_pk_fma_f32 v[14:15], v[86:87], s[0:1], v[14:15] op_sel_hi:[1,0,1]
	v_readlane_b32 s0, v161, 24
	s_nop 1
	v_pk_fma_f32 v[16:17], v[84:85], s[0:1], v[16:17] op_sel_hi:[1,0,1]
	v_pk_fma_f32 v[18:19], v[86:87], s[0:1], v[18:19] op_sel_hi:[1,0,1]
	v_readlane_b32 s0, v161, 32
	s_nop 1
	v_pk_fma_f32 v[20:21], v[84:85], s[0:1], v[20:21] op_sel_hi:[1,0,1]
	v_pk_fma_f32 v[22:23], v[86:87], s[0:1], v[22:23] op_sel_hi:[1,0,1]
	v_readlane_b32 s0, v161, 40
	s_nop 1
	v_pk_fma_f32 v[24:25], v[84:85], s[0:1], v[24:25] op_sel_hi:[1,0,1]
	v_pk_fma_f32 v[26:27], v[86:87], s[0:1], v[26:27] op_sel_hi:[1,0,1]
	v_readlane_b32 s0, v161, 48
	s_nop 1
	v_pk_fma_f32 v[28:29], v[84:85], s[0:1], v[28:29] op_sel_hi:[1,0,1]
	v_pk_fma_f32 v[30:31], v[86:87], s[0:1], v[30:31] op_sel_hi:[1,0,1]
	v_readlane_b32 s0, v161, 56
	s_nop 1
	v_pk_fma_f32 v[0:1], v[84:85], s[0:1], v[0:1] op_sel_hi:[1,0,1]
	v_pk_fma_f32 v[2:3], v[86:87], s[0:1], v[2:3] op_sel_hi:[1,0,1]
	v_readlane_b32 s0, v162, 0
	s_nop 1
	v_pk_fma_f32 v[6:7], v[82:83], s[0:1], v[6:7] op_sel_hi:[1,0,1]
	v_pk_fma_f32 v[4:5], v[80:81], s[0:1], v[4:5] op_sel_hi:[1,0,1]
	v_readlane_b32 s0, v162, 8
	s_nop 1
	v_pk_fma_f32 v[10:11], v[82:83], s[0:1], v[10:11] op_sel_hi:[1,0,1]
	v_pk_fma_f32 v[8:9], v[80:81], s[0:1], v[8:9] op_sel_hi:[1,0,1]
	v_readlane_b32 s0, v162, 16
	s_nop 1
	v_pk_fma_f32 v[14:15], v[82:83], s[0:1], v[14:15] op_sel_hi:[1,0,1]
	v_pk_fma_f32 v[12:13], v[80:81], s[0:1], v[12:13] op_sel_hi:[1,0,1]
	v_readlane_b32 s0, v162, 24
	s_nop 1
	v_pk_fma_f32 v[18:19], v[82:83], s[0:1], v[18:19] op_sel_hi:[1,0,1]
	v_pk_fma_f32 v[16:17], v[80:81], s[0:1], v[16:17] op_sel_hi:[1,0,1]
	v_readlane_b32 s0, v162, 32
	s_nop 1
	v_pk_fma_f32 v[22:23], v[82:83], s[0:1], v[22:23] op_sel_hi:[1,0,1]
	v_pk_fma_f32 v[20:21], v[80:81], s[0:1], v[20:21] op_sel_hi:[1,0,1]
	v_readlane_b32 s0, v162, 40
	s_nop 1
	v_pk_fma_f32 v[26:27], v[82:83], s[0:1], v[26:27] op_sel_hi:[1,0,1]
	v_pk_fma_f32 v[24:25], v[80:81], s[0:1], v[24:25] op_sel_hi:[1,0,1]
	v_readlane_b32 s0, v162, 48
	s_nop 1
	v_pk_fma_f32 v[30:31], v[82:83], s[0:1], v[30:31] op_sel_hi:[1,0,1]
	v_pk_fma_f32 v[28:29], v[80:81], s[0:1], v[28:29] op_sel_hi:[1,0,1]
	v_readlane_b32 s0, v162, 56
	s_nop 1
	v_pk_fma_f32 v[2:3], v[82:83], s[0:1], v[2:3] op_sel_hi:[1,0,1]
	v_pk_fma_f32 v[0:1], v[80:81], s[0:1], v[0:1] op_sel_hi:[1,0,1]
	v_readlane_b32 s0, v163, 0
	s_nop 1
	v_pk_fma_f32 v[4:5], v[76:77], s[0:1], v[4:5] op_sel_hi:[1,0,1]
	v_pk_fma_f32 v[6:7], v[78:79], s[0:1], v[6:7] op_sel_hi:[1,0,1]
	v_readlane_b32 s0, v163, 8
	s_nop 1
	v_pk_fma_f32 v[8:9], v[76:77], s[0:1], v[8:9] op_sel_hi:[1,0,1]
	v_pk_fma_f32 v[10:11], v[78:79], s[0:1], v[10:11] op_sel_hi:[1,0,1]
	v_readlane_b32 s0, v163, 16
	s_nop 1
	v_pk_fma_f32 v[12:13], v[76:77], s[0:1], v[12:13] op_sel_hi:[1,0,1]
	v_pk_fma_f32 v[14:15], v[78:79], s[0:1], v[14:15] op_sel_hi:[1,0,1]
	v_readlane_b32 s0, v163, 24
	s_nop 1
	v_pk_fma_f32 v[16:17], v[76:77], s[0:1], v[16:17] op_sel_hi:[1,0,1]
	v_pk_fma_f32 v[18:19], v[78:79], s[0:1], v[18:19] op_sel_hi:[1,0,1]
	v_readlane_b32 s0, v163, 32
	s_nop 1
	v_pk_fma_f32 v[20:21], v[76:77], s[0:1], v[20:21] op_sel_hi:[1,0,1]
	v_pk_fma_f32 v[22:23], v[78:79], s[0:1], v[22:23] op_sel_hi:[1,0,1]
	v_readlane_b32 s0, v163, 40
	s_nop 1
	v_pk_fma_f32 v[24:25], v[76:77], s[0:1], v[24:25] op_sel_hi:[1,0,1]
	v_pk_fma_f32 v[26:27], v[78:79], s[0:1], v[26:27] op_sel_hi:[1,0,1]
	v_readlane_b32 s0, v163, 48
	s_nop 1
	v_pk_fma_f32 v[28:29], v[76:77], s[0:1], v[28:29] op_sel_hi:[1,0,1]
	v_pk_fma_f32 v[30:31], v[78:79], s[0:1], v[30:31] op_sel_hi:[1,0,1]
	v_readlane_b32 s0, v163, 56
	s_nop 1
	v_pk_fma_f32 v[0:1], v[76:77], s[0:1], v[0:1] op_sel_hi:[1,0,1]
	v_pk_fma_f32 v[2:3], v[78:79], s[0:1], v[2:3] op_sel_hi:[1,0,1]
	v_readlane_b32 s0, v164, 0
	s_nop 1
	v_pk_fma_f32 v[6:7], v[74:75], s[0:1], v[6:7] op_sel_hi:[1,0,1]
	v_pk_fma_f32 v[4:5], v[72:73], s[0:1], v[4:5] op_sel_hi:[1,0,1]
	v_readlane_b32 s0, v164, 8
	s_nop 1
	v_pk_fma_f32 v[10:11], v[74:75], s[0:1], v[10:11] op_sel_hi:[1,0,1]
	v_pk_fma_f32 v[8:9], v[72:73], s[0:1], v[8:9] op_sel_hi:[1,0,1]
	v_readlane_b32 s0, v164, 16
	s_nop 1
	v_pk_fma_f32 v[14:15], v[74:75], s[0:1], v[14:15] op_sel_hi:[1,0,1]
	v_pk_fma_f32 v[12:13], v[72:73], s[0:1], v[12:13] op_sel_hi:[1,0,1]
	v_readlane_b32 s0, v164, 24
	s_nop 1
	v_pk_fma_f32 v[18:19], v[74:75], s[0:1], v[18:19] op_sel_hi:[1,0,1]
	v_pk_fma_f32 v[16:17], v[72:73], s[0:1], v[16:17] op_sel_hi:[1,0,1]
	v_readlane_b32 s0, v164, 32
	s_nop 1
	v_pk_fma_f32 v[22:23], v[74:75], s[0:1], v[22:23] op_sel_hi:[1,0,1]
	v_pk_fma_f32 v[20:21], v[72:73], s[0:1], v[20:21] op_sel_hi:[1,0,1]
	v_readlane_b32 s0, v164, 40
	s_nop 1
	v_pk_fma_f32 v[26:27], v[74:75], s[0:1], v[26:27] op_sel_hi:[1,0,1]
	v_pk_fma_f32 v[24:25], v[72:73], s[0:1], v[24:25] op_sel_hi:[1,0,1]
	v_readlane_b32 s0, v164, 48
	s_nop 1
	v_pk_fma_f32 v[30:31], v[74:75], s[0:1], v[30:31] op_sel_hi:[1,0,1]
	v_pk_fma_f32 v[28:29], v[72:73], s[0:1], v[28:29] op_sel_hi:[1,0,1]
	v_readlane_b32 s0, v164, 56
	s_nop 1
	v_pk_fma_f32 v[2:3], v[74:75], s[0:1], v[2:3] op_sel_hi:[1,0,1]
	v_pk_fma_f32 v[0:1], v[72:73], s[0:1], v[0:1] op_sel_hi:[1,0,1]
	v_readlane_b32 s0, v165, 0
	s_nop 1
	v_pk_fma_f32 v[4:5], v[68:69], s[0:1], v[4:5] op_sel_hi:[1,0,1]
	v_pk_fma_f32 v[6:7], v[70:71], s[0:1], v[6:7] op_sel_hi:[1,0,1]
	v_readlane_b32 s0, v165, 8
	s_nop 1
	v_pk_fma_f32 v[8:9], v[68:69], s[0:1], v[8:9] op_sel_hi:[1,0,1]
	v_pk_fma_f32 v[10:11], v[70:71], s[0:1], v[10:11] op_sel_hi:[1,0,1]
	v_readlane_b32 s0, v165, 16
	s_nop 1
	v_pk_fma_f32 v[12:13], v[68:69], s[0:1], v[12:13] op_sel_hi:[1,0,1]
	v_pk_fma_f32 v[14:15], v[70:71], s[0:1], v[14:15] op_sel_hi:[1,0,1]
	v_readlane_b32 s0, v165, 24
	s_nop 1
	v_pk_fma_f32 v[16:17], v[68:69], s[0:1], v[16:17] op_sel_hi:[1,0,1]
	v_pk_fma_f32 v[18:19], v[70:71], s[0:1], v[18:19] op_sel_hi:[1,0,1]
	v_readlane_b32 s0, v165, 32
	s_nop 1
	v_pk_fma_f32 v[20:21], v[68:69], s[0:1], v[20:21] op_sel_hi:[1,0,1]
	v_pk_fma_f32 v[22:23], v[70:71], s[0:1], v[22:23] op_sel_hi:[1,0,1]
	v_readlane_b32 s0, v165, 40
	s_nop 1
	v_pk_fma_f32 v[24:25], v[68:69], s[0:1], v[24:25] op_sel_hi:[1,0,1]
	v_pk_fma_f32 v[26:27], v[70:71], s[0:1], v[26:27] op_sel_hi:[1,0,1]
	v_readlane_b32 s0, v165, 48
	s_nop 1
	v_pk_fma_f32 v[28:29], v[68:69], s[0:1], v[28:29] op_sel_hi:[1,0,1]
	v_pk_fma_f32 v[30:31], v[70:71], s[0:1], v[30:31] op_sel_hi:[1,0,1]
	v_readlane_b32 s0, v165, 56
	s_nop 1
	v_pk_fma_f32 v[32:33], v[68:69], s[0:1], v[0:1] op_sel_hi:[1,0,1]
	v_pk_fma_f32 v[34:35], v[70:71], s[0:1], v[2:3] op_sel_hi:[1,0,1]
	v_readlane_b32 s0, v166, 0
	s_waitcnt vmcnt(0)
	s_nop 0
	v_pk_fma_f32 v[2:3], v[66:67], s[0:1], v[6:7] op_sel_hi:[1,0,1]
	v_pk_fma_f32 v[0:1], v[64:65], s[0:1], v[4:5] op_sel_hi:[1,0,1]
	v_readlane_b32 s0, v166, 8
	s_nop 1
	v_pk_fma_f32 v[6:7], v[66:67], s[0:1], v[10:11] op_sel_hi:[1,0,1]
	v_pk_fma_f32 v[4:5], v[64:65], s[0:1], v[8:9] op_sel_hi:[1,0,1]
	v_readlane_b32 s0, v166, 16
	s_nop 1
	v_pk_fma_f32 v[10:11], v[66:67], s[0:1], v[14:15] op_sel_hi:[1,0,1]
	v_pk_fma_f32 v[8:9], v[64:65], s[0:1], v[12:13] op_sel_hi:[1,0,1]
	v_readlane_b32 s0, v166, 24
	s_nop 1
	v_pk_fma_f32 v[14:15], v[66:67], s[0:1], v[18:19] op_sel_hi:[1,0,1]
	v_pk_fma_f32 v[12:13], v[64:65], s[0:1], v[16:17] op_sel_hi:[1,0,1]
	v_readlane_b32 s0, v166, 32
	s_nop 1
	v_pk_fma_f32 v[18:19], v[66:67], s[0:1], v[22:23] op_sel_hi:[1,0,1]
	v_pk_fma_f32 v[16:17], v[64:65], s[0:1], v[20:21] op_sel_hi:[1,0,1]
	v_readlane_b32 s0, v166, 40
	s_nop 1
	v_pk_fma_f32 v[22:23], v[66:67], s[0:1], v[26:27] op_sel_hi:[1,0,1]
	v_pk_fma_f32 v[20:21], v[64:65], s[0:1], v[24:25] op_sel_hi:[1,0,1]
	v_readlane_b32 s0, v166, 48
	s_nop 1
	v_pk_fma_f32 v[26:27], v[66:67], s[0:1], v[30:31] op_sel_hi:[1,0,1]
	v_pk_fma_f32 v[24:25], v[64:65], s[0:1], v[28:29] op_sel_hi:[1,0,1]
	v_readlane_b32 s0, v166, 56
	s_nop 1
	v_pk_fma_f32 v[28:29], v[64:65], s[0:1], v[32:33] op_sel_hi:[1,0,1]
	v_lshlrev_b32_e32 v32, 13, v129
	v_lshlrev_b32_e32 v33, 4, v131
	v_add3_u32 v32, 0, v32, v33
	v_pk_fma_f32 v[30:31], v[66:67], s[0:1], v[34:35] op_sel_hi:[1,0,1]
	ds_write_b128 v32, v[0:3]
	ds_write_b128 v32, v[4:7] offset:1024
	ds_write_b128 v32, v[8:11] offset:2048
	ds_write_b128 v32, v[12:15] offset:3072
	ds_write_b128 v32, v[16:19] offset:4096
	ds_write_b128 v32, v[20:23] offset:5120
	ds_write_b128 v32, v[24:27] offset:6144
	ds_write_b128 v32, v[28:31] offset:7168
	v_and_b32_e32 v0, 7, v130
	v_cmp_eq_u32_e32 vcc, 0, v0
	s_and_saveexec_b64 s[2:3], vcc
	s_cbranch_execz .LBB0_500
	v_add_f32_e32 v0, 0, v133
	v_add_f32_e32 v0, v135, v0
	v_add_f32_e32 v0, v136, v0
	v_add_f32_e32 v0, v137, v0
	v_add_f32_e32 v0, v138, v0
	v_add_f32_e32 v0, v139, v0
	v_add_f32_e32 v0, v140, v0
	v_add_f32_e32 v0, v141, v0
	v_add_f32_e32 v0, v142, v0
	v_add_f32_e32 v0, v143, v0
	v_add_f32_e32 v0, v144, v0
	v_add_f32_e32 v0, v145, v0
	v_add_f32_e32 v0, v146, v0
	v_add_f32_e32 v0, v147, v0
	v_add_f32_e32 v0, v148, v0
	v_add_f32_e32 v0, v149, v0
	v_add_f32_e32 v0, v150, v0
	v_add_f32_e32 v0, v151, v0
	v_add_f32_e32 v0, v152, v0
	v_add_f32_e32 v0, v153, v0
	v_add_f32_e32 v0, v154, v0
	v_add_f32_e32 v0, v155, v0
	v_add_f32_e32 v0, v156, v0
	v_add_f32_e32 v0, v158, v0
	v_add_f32_e32 v0, v159, v0
	v_add_f32_e32 v0, v160, v0
	v_add_f32_e32 v0, v161, v0
	v_add_f32_e32 v0, v162, v0
	v_add_f32_e32 v0, v163, v0
	v_add_f32_e32 v0, v164, v0
	v_lshrrev_b32_e32 v2, 1, v130
	v_add_f32_e32 v0, v165, v0
	v_and_b32_e32 v1, 0xffffffc0, v132
	s_add_i32 s0, 0, 0x10000
	v_and_b32_e32 v2, 28, v2
	v_add_f32_e32 v0, v166, v0
	v_add3_u32 v1, s0, v1, v2
	ds_write2_b32 v1, v134, v0 offset1:8
	s_branch .LBB0_500

	.amdhsa_kernel _Z10hybrid_fwd4Args
		.amdhsa_group_segment_fixed_size 0
		.amdhsa_private_segment_fixed_size 0
		.amdhsa_kernarg_size 608
		.amdhsa_user_sgpr_count 2
		.amdhsa_user_sgpr_dispatch_ptr 0
		.amdhsa_user_sgpr_queue_ptr 0
		.amdhsa_user_sgpr_kernarg_segment_ptr 1
		.amdhsa_user_sgpr_dispatch_id 0
		.amdhsa_user_sgpr_kernarg_preload_length 0
		.amdhsa_user_sgpr_kernarg_preload_offset 0
		.amdhsa_user_sgpr_private_segment_size 0
		.amdhsa_uses_dynamic_stack 0
		.amdhsa_enable_private_segment 0
		.amdhsa_system_sgpr_workgroup_id_x 1
		.amdhsa_system_sgpr_workgroup_id_y 0
		.amdhsa_system_sgpr_workgroup_id_z 0
		.amdhsa_system_sgpr_workgroup_info 0
		.amdhsa_system_vgpr_workitem_id 0
		.amdhsa_next_free_vgpr 256
		.amdhsa_next_free_sgpr 102
		.amdhsa_accum_offset 256
		.amdhsa_reserve_vcc 1
		.amdhsa_float_round_mode_32 0
		.amdhsa_float_round_mode_16_64 0
		.amdhsa_float_denorm_mode_32 3
		.amdhsa_float_denorm_mode_16_64 3
		.amdhsa_dx10_clamp 1
		.amdhsa_ieee_mode 1
		.amdhsa_fp16_overflow 0
		.amdhsa_tg_split 0
		.amdhsa_exception_fp_ieee_invalid_op 0
		.amdhsa_exception_fp_denorm_src 0
		.amdhsa_exception_fp_ieee_div_zero 0
		.amdhsa_exception_fp_ieee_overflow 0
		.amdhsa_exception_fp_ieee_underflow 0
		.amdhsa_exception_fp_ieee_inexact 0
		.amdhsa_exception_int_div_zero 0
	.end_amdhsa_kernel

amdhsa.kernels:
  - .agpr_count:     0
    .args:
      - .offset:         0
        .size:           352
        .value_kind:     by_value
      - .offset:         352
        .size:           4
        .value_kind:     hidden_block_count_x
      - .offset:         356
        .size:           4
        .value_kind:     hidden_block_count_y
      - .offset:         360
        .size:           4
        .value_kind:     hidden_block_count_z
      - .offset:         364
        .size:           2
        .value_kind:     hidden_group_size_x
      - .offset:         366
        .size:           2
        .value_kind:     hidden_group_size_y
      - .offset:         368
        .size:           2
        .value_kind:     hidden_group_size_z
      - .offset:         370
        .size:           2
        .value_kind:     hidden_remainder_x
      - .offset:         372
        .size:           2
        .value_kind:     hidden_remainder_y
      - .offset:         374
        .size:           2
        .value_kind:     hidden_remainder_z
      - .offset:         392
        .size:           8
        .value_kind:     hidden_global_offset_x
      - .offset:         400
        .size:           8
        .value_kind:     hidden_global_offset_y
      - .offset:         408
        .size:           8
        .value_kind:     hidden_global_offset_z
      - .offset:         416
        .size:           2
        .value_kind:     hidden_grid_dims
      - .offset:         472
        .size:           4
        .value_kind:     hidden_dynamic_lds_size
    .group_segment_fixed_size: 0
    .kernarg_segment_align: 8
    .kernarg_segment_size: 608
    .language:       OpenCL C
    .language_version:
      - 2
      - 0
    .max_flat_workgroup_size: 512
    .name:           _Z10hybrid_fwd4Args
    .private_segment_fixed_size: 0
    .sgpr_count:     108
    .sgpr_spill_count: 171
    .symbol:         _Z10hybrid_fwd4Args.kd
    .uniform_work_group_size: 1
    .uses_dynamic_stack: false
    .vgpr_count:     256
    .vgpr_spill_count: 0
    .wavefront_size: 64
